# v28 + snake MFMA order (every consecutive MFMA pair shares one source operand)
# speedup vs baseline: 1.0157x; 1.0157x over previous
; #define PG8_STAGE(bufoff, gbase, voff) do { _Pragma("unroll") for (int _i = 0; _i < 2; ++_i) \
;         __builtin_amdgcn_global_load_lds((const unsigned*)((const char*)(gbase) + (voff)[_i]), (PG8_LAS unsigned*)(lds + (bufoff) + ldsw + _i * 8192), 16, 0, 0); } while (0)
; #define PG8_LDA(dst, b, h) do { _Pragma("unroll") for (int m = 0; m < 4; ++m) _Pragma("unroll") for (int k = 0; k < 2; ++k) dst[m][k] = *(const PG8_LAS bf16x8*)(lds + PG8_SA(b, h) + aoff + m * 2048 + k * 1024); } while (0)
; #define PG8_LDB(dst, b, h) do { _Pragma("unroll") for (int n = 0; n < 2; ++n) _Pragma("unroll") for (int k = 0; k < 2; ++k) dst[n][k] = *(const PG8_LAS bf16x8*)(lds + PG8_SB(b, h) + boff + n * 2048 + k * 1024); } while (0)
; #define PG8_WAIT_V(n) asm volatile("s_waitcnt vmcnt(" #n ")" ::: "memory")
; #define PG8_WAIT_L(n) asm volatile("s_waitcnt lgkmcnt(" #n ")" ::: "memory")
; #define PG8_BAR __builtin_amdgcn_s_barrier()
; #define PG8_SCHED __builtin_amdgcn_sched_barrier(0)
; template <class Epi, class Sched, bool ALIGN_EPI = false, bool SP2 = false>
; __device__ __forceinline__ void gemm_phase(PG8_LAS unsigned char* lds, const Gemm g, const Sched& S, const Epi& E) {
;     ...
;         const bool has_next = S.next(ui + 1, nxt);
;         const char* nA = has_next ? (const char*)g.A + (size_t)nxt.pm * tstep : cA; const char* nB = has_next ? (const char*)g.Bt + (size_t)nxt.pn * tstep : cB;
;         for (int t = 0; t < nt; t += 2) {
;             const bool last = (t == nt - 2);
;             const char* a1 = cA + (size_t)(t + 1) * kstep;
;             const char* a2 = last ? nA : cA + (size_t)(t + 2) * kstep; const char* b2 = last ? nB : cB + (size_t)(t + 2) * kstep;
;             const char* a3 = a2 + kstep; const char* b3 = b2 + kstep;
;             if (last && has_next) S.a_ready(nxt);
;             if constexpr (SP2) {
;             PG8_LDB(B0, 0, 0); PG8_LDB(B1, 0, 1); PG8_SCHED; PG8_LDA(At, 0, 0); PG8_STAGE(PG8_SA(1, 1), a1 + hstep, voffA);
;             PG8_WAIT_V(8); PG8_WAIT_L(0); PG8_BAR; PG8_MMA(0, 0, At, B0); PG8_MMA(0, 1, At, B1); PG8_BAR; PG8_SCHED;
;             PG8_LDA(At, 0, 1); PG8_STAGE(PG8_SB(0, 0), b2, voffB); PG8_STAGE(PG8_SB(0, 1), b2 + hstep, voffB); PG8_STAGE(PG8_SA(0, 0), a2, voffA);
;             PG8_WAIT_V(8); PG8_WAIT_L(0); PG8_BAR; PG8_MMA(1, 0, At, B0); PG8_MMA(1, 1, At, B1); PG8_BAR; PG8_SCHED;
.LBB0_224:
	s_ashr_i32 s15, s14, 31
	s_lshl_b64 s[16:17], s[14:15], 19
	s_add_u32 s16, s34, s16
	s_addc_u32 s17, s35, s17
	s_and_b64 s[18:19], s[2:3], exec
	s_cselect_b32 s5, s17, s23
	s_cselect_b32 s15, s16, s22
	s_ashr_i32 s13, s12, 31
	s_lshl_b64 s[18:19], s[12:13], 19
	s_add_u32 s18, s38, s18
	s_addc_u32 s19, s39, s19
	s_and_b64 s[26:27], s[2:3], exec
	s_cselect_b32 s13, s19, s25
	s_cselect_b32 s21, s18, s24
	s_add_u32 s22, s22, 0x40080
	s_addc_u32 s23, s23, 0
	s_add_u32 s49, s24, 0x100
	s_addc_u32 s50, s25, 0
	s_mov_b32 s51, -2
	s_add_u32 s24, s22, 0xfffc0080
	s_addc_u32 s25, s23, -1
	s_add_i32 s52, 0, 0x10000
	s_cmp_eq_u32 s51, 12
	s_cselect_b32 s27, s5, s25
	s_cselect_b32 s26, s15, s24
	v_add_u32_e32 v138, s52, v149
	s_cselect_b32 s25, s13, s50
	s_cselect_b32 s24, s21, s49
	s_add_i32 s55, 0, 0x14000
	ds_read_b128 v[144:147], v138
	ds_read_b128 v[154:157], v138 offset:1024
	ds_read_b128 v[158:161], v138 offset:2048
	ds_read_b128 v[162:165], v138 offset:3072
	v_add_u32_e32 v138, s55, v149
	ds_read_b128 v[166:169], v138
	ds_read_b128 v[170:173], v138 offset:1024
	ds_read_b128 v[174:177], v138 offset:2048
	ds_read_b128 v[178:181], v138 offset:3072
	v_lshl_add_u64 v[138:139], s[22:23], 0, v[136:137]
	s_add_i32 m0, s41, 0xc000
	ds_read_b128 v[182:185], v152
	ds_read_b128 v[186:189], v152 offset:1024
	ds_read_b128 v[190:193], v152 offset:2048
	ds_read_b128 v[194:197], v152 offset:3072
	ds_read_b128 v[198:201], v152 offset:4096
	ds_read_b128 v[202:205], v152 offset:5120
	ds_read_b128 v[224:227], v152 offset:6144
	ds_read_b128 v[228:231], v152 offset:7168
	global_load_lds_dwordx4 v[138:139], off
	v_lshl_add_u64 v[138:139], s[22:23], 0, v[142:143]
	s_add_i32 m0, s41, 0xe000
	s_nop 0
	global_load_lds_dwordx4 v[138:139], off
	s_waitcnt vmcnt(8)
	s_waitcnt lgkmcnt(0)
	s_setprio 1
	s_barrier
	v_mfma_f32_16x16x32_bf16 v[126:129], v[144:147], v[182:185], 0
	v_mfma_f32_16x16x32_bf16 v[122:125], v[158:161], v[182:185], 0
	v_mfma_f32_16x16x32_bf16 v[110:113], v[144:147], v[190:193], 0
	v_mfma_f32_16x16x32_bf16 v[106:109], v[158:161], v[190:193], 0
	v_mfma_f32_16x16x32_bf16 v[94:97], v[144:147], v[198:201], 0
	v_mfma_f32_16x16x32_bf16 v[90:93], v[158:161], v[198:201], 0
	v_mfma_f32_16x16x32_bf16 v[78:81], v[144:147], v[224:227], 0
	v_mfma_f32_16x16x32_bf16 v[74:77], v[158:161], v[224:227], 0
	v_mfma_f32_16x16x32_bf16 v[126:129], v[154:157], v[186:189], v[126:129]
	v_mfma_f32_16x16x32_bf16 v[122:125], v[162:165], v[186:189], v[122:125]
	v_mfma_f32_16x16x32_bf16 v[106:109], v[162:165], v[194:197], v[106:109]
	v_mfma_f32_16x16x32_bf16 v[110:113], v[154:157], v[194:197], v[110:113]
	v_mfma_f32_16x16x32_bf16 v[94:97], v[154:157], v[202:205], v[94:97]
	v_mfma_f32_16x16x32_bf16 v[90:93], v[162:165], v[202:205], v[90:93]
	v_mfma_f32_16x16x32_bf16 v[74:77], v[162:165], v[228:231], v[74:77]
	v_mfma_f32_16x16x32_bf16 v[78:81], v[154:157], v[228:231], v[78:81]
	v_mfma_f32_16x16x32_bf16 v[118:121], v[166:169], v[182:185], 0
	v_mfma_f32_16x16x32_bf16 v[114:117], v[174:177], v[182:185], 0
	v_mfma_f32_16x16x32_bf16 v[102:105], v[166:169], v[190:193], 0
	v_mfma_f32_16x16x32_bf16 v[98:101], v[174:177], v[190:193], 0
	v_mfma_f32_16x16x32_bf16 v[86:89], v[166:169], v[198:201], 0
	v_mfma_f32_16x16x32_bf16 v[82:85], v[174:177], v[198:201], 0
	v_mfma_f32_16x16x32_bf16 v[70:73], v[166:169], v[224:227], 0
	v_mfma_f32_16x16x32_bf16 v[66:69], v[174:177], v[224:227], 0
	v_mfma_f32_16x16x32_bf16 v[118:121], v[170:173], v[186:189], v[118:121]
	v_mfma_f32_16x16x32_bf16 v[114:117], v[178:181], v[186:189], v[114:117]
	v_mfma_f32_16x16x32_bf16 v[98:101], v[178:181], v[194:197], v[98:101]
	v_mfma_f32_16x16x32_bf16 v[102:105], v[170:173], v[194:197], v[102:105]
	v_mfma_f32_16x16x32_bf16 v[86:89], v[170:173], v[202:205], v[86:89]
	v_mfma_f32_16x16x32_bf16 v[82:85], v[178:181], v[202:205], v[82:85]
	v_mfma_f32_16x16x32_bf16 v[66:69], v[178:181], v[228:231], v[66:69]
	v_mfma_f32_16x16x32_bf16 v[70:73], v[170:173], v[228:231], v[70:73]
	s_barrier
	s_setprio 0
	s_add_i32 s52, s52, s31
	v_lshl_add_u64 v[138:139], s[24:25], 0, v[0:1]
	s_mov_b32 m0, s52
	ds_read_b128 v[182:185], v152 offset:16384
	ds_read_b128 v[186:189], v152 offset:17408
	ds_read_b128 v[190:193], v152 offset:18432
	ds_read_b128 v[194:197], v152 offset:19456
	ds_read_b128 v[198:201], v152 offset:20480
	ds_read_b128 v[202:205], v152 offset:21504
	ds_read_b128 v[224:227], v152 offset:22528
	ds_read_b128 v[228:231], v152 offset:23552
	global_load_lds_dwordx4 v[138:139], off
	s_add_i32 m0, s52, 0x2000
	s_add_u32 s52, s24, 0x40000
	v_lshl_add_u64 v[140:141], s[24:25], 0, v[134:135]
	s_addc_u32 s53, s25, 0
	s_add_i32 s55, s55, s31
	global_load_lds_dwordx4 v[140:141], off
	v_lshl_add_u64 v[232:233], s[52:53], 0, v[0:1]
	s_mov_b32 m0, s55
	v_lshl_add_u64 v[234:235], s[26:27], 0, v[132:133]
	global_load_lds_dwordx4 v[232:233], off
	v_lshl_add_u64 v[232:233], s[52:53], 0, v[134:135]
	s_add_i32 m0, s55, 0x2000
	s_nop 0
	global_load_lds_dwordx4 v[232:233], off
	v_lshl_add_u64 v[232:233], s[26:27], 0, v[130:131]
	s_mov_b32 m0, s41
	s_nop 0
	global_load_lds_dwordx4 v[232:233], off
	s_mov_b32 m0, s42
	s_nop 0
	global_load_lds_dwordx4 v[234:235], off
	s_waitcnt vmcnt(8)
	s_waitcnt lgkmcnt(0)
	s_setprio 1
	s_barrier
; #define PG8_STAGE(bufoff, gbase, voff) do { _Pragma("unroll") for (int _i = 0; _i < 2; ++_i) \
;         __builtin_amdgcn_global_load_lds((const unsigned*)((const char*)(gbase) + (voff)[_i]), (PG8_LAS unsigned*)(lds + (bufoff) + ldsw + _i * 8192), 16, 0, 0); } while (0)
; #define PG8_LDA(dst, b, h) do { _Pragma("unroll") for (int m = 0; m < 4; ++m) _Pragma("unroll") for (int k = 0; k < 2; ++k) dst[m][k] = *(const PG8_LAS bf16x8*)(lds + PG8_SA(b, h) + aoff + m * 2048 + k * 1024); } while (0)
; #define PG8_LDB(dst, b, h) do { _Pragma("unroll") for (int n = 0; n < 2; ++n) _Pragma("unroll") for (int k = 0; k < 2; ++k) dst[n][k] = *(const PG8_LAS bf16x8*)(lds + PG8_SB(b, h) + boff + n * 2048 + k * 1024); } while (0)
; #define PG8_MMA(ai, bj, At, Bt) do { __builtin_amdgcn_s_setprio(1); _Pragma("unroll") for (int m = 0; m < 4; ++m) _Pragma("unroll") for (int n = 0; n < 2; ++n) _Pragma("unroll") for (int k = 0; k < 2; ++k) \
;         acc[ai][bj][m][n] = __builtin_amdgcn_mfma_f32_16x16x32_bf16(Bt[n][k], At[m][k], acc[ai][bj][m][n], 0, 0, 0); __builtin_amdgcn_s_setprio(0); } while (0)
; #define PG8_WAIT_V(n) asm volatile("s_waitcnt vmcnt(" #n ")" ::: "memory")
; #define PG8_WAIT_L(n) asm volatile("s_waitcnt lgkmcnt(" #n ")" ::: "memory")
; #define PG8_BAR __builtin_amdgcn_s_barrier()
; #define PG8_SCHED __builtin_amdgcn_sched_barrier(0)
; template <class Epi, class Sched, bool ALIGN_EPI = false, bool SP2 = false>
; __device__ __forceinline__ void gemm_phase(PG8_LAS unsigned char* lds, const Gemm g, const Sched& S, const Epi& E) {
;     ...
;             PG8_WAIT_V(8); PG8_WAIT_L(0); PG8_BAR; PG8_MMA(0, 0, At, B0); PG8_MMA(0, 1, At, B1); PG8_BAR; PG8_SCHED;
;             PG8_LDA(At, 0, 1); PG8_STAGE(PG8_SB(0, 0), b2, voffB); PG8_STAGE(PG8_SB(0, 1), b2 + hstep, voffB); PG8_STAGE(PG8_SA(0, 0), a2, voffA);
;             PG8_WAIT_V(8); PG8_WAIT_L(0); PG8_BAR; PG8_MMA(1, 0, At, B0); PG8_MMA(1, 1, At, B1); PG8_BAR; PG8_SCHED;
;             PG8_LDB(B0, 1, 0); PG8_LDB(B1, 1, 1); PG8_SCHED; PG8_LDA(At, 1, 0); PG8_STAGE(PG8_SA(0, 1), a2 + hstep, voffA);
;             PG8_WAIT_V(8); PG8_WAIT_L(0); PG8_BAR; PG8_MMA(0, 0, At, B0); PG8_MMA(0, 1, At, B1); PG8_BAR; PG8_SCHED;
	v_mfma_f32_16x16x32_bf16 v[62:65], v[144:147], v[182:185], 0
	v_mfma_f32_16x16x32_bf16 v[58:61], v[158:161], v[182:185], 0
	v_mfma_f32_16x16x32_bf16 v[46:49], v[144:147], v[190:193], 0
	v_mfma_f32_16x16x32_bf16 v[42:45], v[158:161], v[190:193], 0
	v_mfma_f32_16x16x32_bf16 v[30:33], v[144:147], v[198:201], 0
	v_mfma_f32_16x16x32_bf16 v[26:29], v[158:161], v[198:201], 0
	v_mfma_f32_16x16x32_bf16 v[14:17], v[144:147], v[224:227], 0
	v_mfma_f32_16x16x32_bf16 v[10:13], v[158:161], v[224:227], 0
	v_mfma_f32_16x16x32_bf16 v[62:65], v[154:157], v[186:189], v[62:65]
	v_mfma_f32_16x16x32_bf16 v[58:61], v[162:165], v[186:189], v[58:61]
	v_mfma_f32_16x16x32_bf16 v[42:45], v[162:165], v[194:197], v[42:45]
	v_mfma_f32_16x16x32_bf16 v[46:49], v[154:157], v[194:197], v[46:49]
	v_mfma_f32_16x16x32_bf16 v[30:33], v[154:157], v[202:205], v[30:33]
	v_mfma_f32_16x16x32_bf16 v[26:29], v[162:165], v[202:205], v[26:29]
	v_mfma_f32_16x16x32_bf16 v[10:13], v[162:165], v[228:231], v[10:13]
	v_mfma_f32_16x16x32_bf16 v[14:17], v[154:157], v[228:231], v[14:17]
	v_mfma_f32_16x16x32_bf16 v[54:57], v[166:169], v[182:185], 0
	v_mfma_f32_16x16x32_bf16 v[50:53], v[174:177], v[182:185], 0
	v_mfma_f32_16x16x32_bf16 v[38:41], v[166:169], v[190:193], 0
	v_mfma_f32_16x16x32_bf16 v[34:37], v[174:177], v[190:193], 0
	v_mfma_f32_16x16x32_bf16 v[22:25], v[166:169], v[198:201], 0
	v_mfma_f32_16x16x32_bf16 v[18:21], v[174:177], v[198:201], 0
	v_mfma_f32_16x16x32_bf16 v[6:9], v[166:169], v[224:227], 0
	v_mfma_f32_16x16x32_bf16 v[2:5], v[174:177], v[224:227], 0
	v_mfma_f32_16x16x32_bf16 v[54:57], v[170:173], v[186:189], v[54:57]
	v_mfma_f32_16x16x32_bf16 v[50:53], v[178:181], v[186:189], v[50:53]
	v_mfma_f32_16x16x32_bf16 v[34:37], v[178:181], v[194:197], v[34:37]
	v_mfma_f32_16x16x32_bf16 v[38:41], v[170:173], v[194:197], v[38:41]
	v_mfma_f32_16x16x32_bf16 v[22:25], v[170:173], v[202:205], v[22:25]
	v_mfma_f32_16x16x32_bf16 v[18:21], v[178:181], v[202:205], v[18:21]
	v_mfma_f32_16x16x32_bf16 v[2:5], v[178:181], v[228:231], v[2:5]
	v_mfma_f32_16x16x32_bf16 v[6:9], v[170:173], v[228:231], v[6:9]
	s_barrier
	s_setprio 0
	s_add_i32 s52, 0, 0x18000
	v_add_u32_e32 v153, s52, v149
	s_add_i32 s53, 0, 0x1c000
	ds_read_b128 v[144:147], v153
	ds_read_b128 v[154:157], v153 offset:1024
	ds_read_b128 v[158:161], v153 offset:2048
	ds_read_b128 v[162:165], v153 offset:3072
	v_add_u32_e32 v153, s53, v149
	ds_read_b128 v[166:169], v153
	ds_read_b128 v[170:173], v153 offset:1024
	ds_read_b128 v[174:177], v153 offset:2048
	ds_read_b128 v[178:181], v153 offset:3072
	s_add_u32 s26, s26, 0x40000
	s_addc_u32 s27, s27, 0
	s_mov_b32 m0, s43
	v_lshl_add_u64 v[236:237], s[26:27], 0, v[130:131]
	ds_read_b128 v[182:185], v152 offset:32768
	ds_read_b128 v[186:189], v152 offset:33792
	ds_read_b128 v[190:193], v152 offset:34816
	ds_read_b128 v[194:197], v152 offset:35840
	ds_read_b128 v[198:201], v152 offset:36864
	ds_read_b128 v[202:205], v152 offset:37888
	ds_read_b128 v[224:227], v152 offset:38912
	ds_read_b128 v[228:231], v152 offset:39936
	global_load_lds_dwordx4 v[236:237], off
	v_lshl_add_u64 v[236:237], s[26:27], 0, v[132:133]
	s_mov_b32 m0, s44
	s_nop 0
	global_load_lds_dwordx4 v[236:237], off
	s_waitcnt vmcnt(8)
	s_waitcnt lgkmcnt(0)
	s_setprio 1
	s_barrier
	v_mfma_f32_16x16x32_bf16 v[126:129], v[144:147], v[182:185], v[126:129]
	v_mfma_f32_16x16x32_bf16 v[122:125], v[158:161], v[182:185], v[122:125]
	v_mfma_f32_16x16x32_bf16 v[106:109], v[158:161], v[190:193], v[106:109]
	v_mfma_f32_16x16x32_bf16 v[110:113], v[144:147], v[190:193], v[110:113]
	v_mfma_f32_16x16x32_bf16 v[94:97], v[144:147], v[198:201], v[94:97]
	v_mfma_f32_16x16x32_bf16 v[90:93], v[158:161], v[198:201], v[90:93]
	v_mfma_f32_16x16x32_bf16 v[74:77], v[158:161], v[224:227], v[74:77]
	v_mfma_f32_16x16x32_bf16 v[78:81], v[144:147], v[224:227], v[78:81]
	v_mfma_f32_16x16x32_bf16 v[126:129], v[154:157], v[186:189], v[126:129]
	v_mfma_f32_16x16x32_bf16 v[122:125], v[162:165], v[186:189], v[122:125]
	v_mfma_f32_16x16x32_bf16 v[106:109], v[162:165], v[194:197], v[106:109]
	v_mfma_f32_16x16x32_bf16 v[110:113], v[154:157], v[194:197], v[110:113]
	v_mfma_f32_16x16x32_bf16 v[94:97], v[154:157], v[202:205], v[94:97]
	v_mfma_f32_16x16x32_bf16 v[90:93], v[162:165], v[202:205], v[90:93]
	v_mfma_f32_16x16x32_bf16 v[74:77], v[162:165], v[228:231], v[74:77]
	v_mfma_f32_16x16x32_bf16 v[78:81], v[154:157], v[228:231], v[78:81]
	v_mfma_f32_16x16x32_bf16 v[118:121], v[166:169], v[182:185], v[118:121]
	v_mfma_f32_16x16x32_bf16 v[114:117], v[174:177], v[182:185], v[114:117]
	v_mfma_f32_16x16x32_bf16 v[98:101], v[174:177], v[190:193], v[98:101]
	v_mfma_f32_16x16x32_bf16 v[102:105], v[166:169], v[190:193], v[102:105]
	v_mfma_f32_16x16x32_bf16 v[86:89], v[166:169], v[198:201], v[86:89]
	v_mfma_f32_16x16x32_bf16 v[82:85], v[174:177], v[198:201], v[82:85]
	v_mfma_f32_16x16x32_bf16 v[66:69], v[174:177], v[224:227], v[66:69]
	v_mfma_f32_16x16x32_bf16 v[70:73], v[166:169], v[224:227], v[70:73]
	v_mfma_f32_16x16x32_bf16 v[118:121], v[170:173], v[186:189], v[118:121]
	v_mfma_f32_16x16x32_bf16 v[114:117], v[178:181], v[186:189], v[114:117]
	v_mfma_f32_16x16x32_bf16 v[98:101], v[178:181], v[194:197], v[98:101]
	v_mfma_f32_16x16x32_bf16 v[102:105], v[170:173], v[194:197], v[102:105]
	v_mfma_f32_16x16x32_bf16 v[86:89], v[170:173], v[202:205], v[86:89]
	v_mfma_f32_16x16x32_bf16 v[82:85], v[178:181], v[202:205], v[82:85]
	v_mfma_f32_16x16x32_bf16 v[66:69], v[178:181], v[228:231], v[66:69]
	v_mfma_f32_16x16x32_bf16 v[70:73], v[170:173], v[228:231], v[70:73]
	s_barrier
; #define PG8_STAGE(bufoff, gbase, voff) do { _Pragma("unroll") for (int _i = 0; _i < 2; ++_i) \
;         __builtin_amdgcn_global_load_lds((const unsigned*)((const char*)(gbase) + (voff)[_i]), (PG8_LAS unsigned*)(lds + (bufoff) + ldsw + _i * 8192), 16, 0, 0); } while (0)
; #define PG8_LDA(dst, b, h) do { _Pragma("unroll") for (int m = 0; m < 4; ++m) _Pragma("unroll") for (int k = 0; k < 2; ++k) dst[m][k] = *(const PG8_LAS bf16x8*)(lds + PG8_SA(b, h) + aoff + m * 2048 + k * 1024); } while (0)
; #define PG8_LDB(dst, b, h) do { _Pragma("unroll") for (int n = 0; n < 2; ++n) _Pragma("unroll") for (int k = 0; k < 2; ++k) dst[n][k] = *(const PG8_LAS bf16x8*)(lds + PG8_SB(b, h) + boff + n * 2048 + k * 1024); } while (0)
; template <class Epi, class Sched, bool ALIGN_EPI = false, bool SP2 = false>
; __device__ __forceinline__ void gemm_phase(PG8_LAS unsigned char* lds, const Gemm g, const Sched& S, const Epi& E) {
;     ...
;         for (int t = 0; t < nt; t += 2) {
;             const bool last = (t == nt - 2);
;             const char* a1 = cA + (size_t)(t + 1) * kstep;
;             const char* a2 = last ? nA : cA + (size_t)(t + 2) * kstep; const char* b2 = last ? nB : cB + (size_t)(t + 2) * kstep;
;             const char* a3 = a2 + kstep; const char* b3 = b2 + kstep;
;             if (last && has_next) S.a_ready(nxt);
;             if constexpr (SP2) {
;             PG8_LDB(B0, 0, 0); PG8_LDB(B1, 0, 1); PG8_SCHED; PG8_LDA(At, 0, 0); PG8_STAGE(PG8_SA(1, 1), a1 + hstep, voffA);
;             PG8_WAIT_V(8); PG8_WAIT_L(0); PG8_BAR; PG8_MMA(0, 0, At, B0); PG8_MMA(0, 1, At, B1); PG8_BAR; PG8_SCHED;
;             PG8_LDA(At, 0, 1); PG8_STAGE(PG8_SB(0, 0), b2, voffB); PG8_STAGE(PG8_SB(0, 1), b2 + hstep, voffB); PG8_STAGE(PG8_SA(0, 0), a2, voffA);
;             PG8_WAIT_V(8); PG8_WAIT_L(0); PG8_BAR; PG8_MMA(1, 0, At, B0); PG8_MMA(1, 1, At, B1); PG8_BAR; PG8_SCHED;
;             PG8_LDB(B0, 1, 0); PG8_LDB(B1, 1, 1); PG8_SCHED; PG8_LDA(At, 1, 0); PG8_STAGE(PG8_SA(0, 1), a2 + hstep, voffA);
;             PG8_WAIT_V(8); PG8_WAIT_L(0); PG8_BAR; PG8_MMA(0, 0, At, B0); PG8_MMA(0, 1, At, B1); PG8_BAR; PG8_SCHED;
;             PG8_LDA(At, 1, 1); PG8_STAGE(PG8_SB(1, 0), b3, voffB); PG8_STAGE(PG8_SB(1, 1), b3 + hstep, voffB); PG8_STAGE(PG8_SA(1, 0), a3, voffA);
;             PG8_WAIT_V(8); PG8_WAIT_L(0); PG8_BAR; PG8_MMA(1, 0, At, B0); PG8_MMA(1, 1, At, B1); PG8_BAR; PG8_SCHED;
	s_setprio 0
	s_add_i32 s26, s52, s31
	v_lshl_add_u64 v[138:139], v[138:139], 0, s[86:87]
	s_mov_b32 m0, s26
	ds_read_b128 v[182:185], v152 offset:49152
	ds_read_b128 v[186:189], v152 offset:50176
	ds_read_b128 v[190:193], v152 offset:51200
	ds_read_b128 v[194:197], v152 offset:52224
	ds_read_b128 v[198:201], v152 offset:53248
	ds_read_b128 v[202:205], v152 offset:54272
	ds_read_b128 v[224:227], v152 offset:55296
	ds_read_b128 v[228:231], v152 offset:56320
	global_load_lds_dwordx4 v[138:139], off
	s_add_i32 m0, s26, 0x2000
	s_add_u32 s24, s24, 0x40080
	v_lshl_add_u64 v[138:139], v[140:141], 0, s[86:87]
	s_addc_u32 s25, s25, 0
	s_add_i32 s26, s53, s31
	global_load_lds_dwordx4 v[138:139], off
	v_lshl_add_u64 v[138:139], s[24:25], 0, v[0:1]
	s_mov_b32 m0, s26
	s_nop 0
	global_load_lds_dwordx4 v[138:139], off
	v_lshl_add_u64 v[138:139], s[24:25], 0, v[134:135]
	s_add_i32 m0, s26, 0x2000
	s_nop 0
	global_load_lds_dwordx4 v[138:139], off
	v_lshl_add_u64 v[138:139], v[232:233], 0, s[86:87]
	s_mov_b32 m0, s45
	s_nop 0
	global_load_lds_dwordx4 v[138:139], off
	v_lshl_add_u64 v[138:139], v[234:235], 0, s[86:87]
	s_mov_b32 m0, s46
	s_nop 0
	global_load_lds_dwordx4 v[138:139], off
	s_waitcnt vmcnt(8)
	s_waitcnt lgkmcnt(0)
	s_setprio 1
	s_barrier
	v_mfma_f32_16x16x32_bf16 v[62:65], v[144:147], v[182:185], v[62:65]
	v_mfma_f32_16x16x32_bf16 v[58:61], v[158:161], v[182:185], v[58:61]
	v_mfma_f32_16x16x32_bf16 v[42:45], v[158:161], v[190:193], v[42:45]
	v_mfma_f32_16x16x32_bf16 v[46:49], v[144:147], v[190:193], v[46:49]
	v_mfma_f32_16x16x32_bf16 v[30:33], v[144:147], v[198:201], v[30:33]
	v_mfma_f32_16x16x32_bf16 v[26:29], v[158:161], v[198:201], v[26:29]
	v_mfma_f32_16x16x32_bf16 v[10:13], v[158:161], v[224:227], v[10:13]
	v_mfma_f32_16x16x32_bf16 v[14:17], v[144:147], v[224:227], v[14:17]
	v_mfma_f32_16x16x32_bf16 v[62:65], v[154:157], v[186:189], v[62:65]
	v_mfma_f32_16x16x32_bf16 v[58:61], v[162:165], v[186:189], v[58:61]
	v_mfma_f32_16x16x32_bf16 v[42:45], v[162:165], v[194:197], v[42:45]
	v_mfma_f32_16x16x32_bf16 v[46:49], v[154:157], v[194:197], v[46:49]
	v_mfma_f32_16x16x32_bf16 v[30:33], v[154:157], v[202:205], v[30:33]
	v_mfma_f32_16x16x32_bf16 v[26:29], v[162:165], v[202:205], v[26:29]
	v_mfma_f32_16x16x32_bf16 v[10:13], v[162:165], v[228:231], v[10:13]
	v_mfma_f32_16x16x32_bf16 v[14:17], v[154:157], v[228:231], v[14:17]
	v_mfma_f32_16x16x32_bf16 v[54:57], v[166:169], v[182:185], v[54:57]
	v_mfma_f32_16x16x32_bf16 v[50:53], v[174:177], v[182:185], v[50:53]
	v_mfma_f32_16x16x32_bf16 v[34:37], v[174:177], v[190:193], v[34:37]
	v_mfma_f32_16x16x32_bf16 v[38:41], v[166:169], v[190:193], v[38:41]
	v_mfma_f32_16x16x32_bf16 v[22:25], v[166:169], v[198:201], v[22:25]
	v_mfma_f32_16x16x32_bf16 v[18:21], v[174:177], v[198:201], v[18:21]
	v_mfma_f32_16x16x32_bf16 v[2:5], v[174:177], v[224:227], v[2:5]
	v_mfma_f32_16x16x32_bf16 v[6:9], v[166:169], v[224:227], v[6:9]
	v_mfma_f32_16x16x32_bf16 v[54:57], v[170:173], v[186:189], v[54:57]
	v_mfma_f32_16x16x32_bf16 v[50:53], v[178:181], v[186:189], v[50:53]
	v_mfma_f32_16x16x32_bf16 v[34:37], v[178:181], v[194:197], v[34:37]
	v_mfma_f32_16x16x32_bf16 v[38:41], v[170:173], v[194:197], v[38:41]
	v_mfma_f32_16x16x32_bf16 v[22:25], v[170:173], v[202:205], v[22:25]
	v_mfma_f32_16x16x32_bf16 v[18:21], v[178:181], v[202:205], v[18:21]
	v_mfma_f32_16x16x32_bf16 v[2:5], v[178:181], v[228:231], v[2:5]
	v_mfma_f32_16x16x32_bf16 v[6:9], v[170:173], v[228:231], v[6:9]
	s_barrier
	s_setprio 0
	s_add_i32 s51, s51, 2
	s_add_u32 s22, s22, 0x100
	s_addc_u32 s23, s23, 0
	s_add_u32 s49, s49, 0x100
	s_addc_u32 s50, s50, 0
	s_cmp_gt_u32 s51, 13
	s_cbranch_scc1 .Lpeel_exit_sw
.LBB0_225:
	s_add_u32 s24, s22, 0xfffc0080
	s_addc_u32 s25, s23, -1
	s_add_i32 s52, 0, 0x10000
	s_cmp_eq_u32 s51, 12
	s_cselect_b32 s27, s5, s25
	s_cselect_b32 s26, s15, s24
	v_add_u32_e32 v138, s52, v149
	s_cselect_b32 s25, s13, s50
	s_cselect_b32 s24, s21, s49
	s_add_i32 s55, 0, 0x14000
	ds_read_b128 v[144:147], v138
	ds_read_b128 v[154:157], v138 offset:1024
	ds_read_b128 v[158:161], v138 offset:2048
	ds_read_b128 v[162:165], v138 offset:3072
	v_add_u32_e32 v138, s55, v149
	ds_read_b128 v[166:169], v138
	ds_read_b128 v[170:173], v138 offset:1024
	ds_read_b128 v[174:177], v138 offset:2048
	ds_read_b128 v[178:181], v138 offset:3072
	v_lshl_add_u64 v[138:139], s[22:23], 0, v[136:137]
	s_add_i32 m0, s41, 0xc000
	ds_read_b128 v[182:185], v152
	ds_read_b128 v[186:189], v152 offset:1024
	ds_read_b128 v[190:193], v152 offset:2048
	ds_read_b128 v[194:197], v152 offset:3072
	ds_read_b128 v[198:201], v152 offset:4096
	ds_read_b128 v[202:205], v152 offset:5120
	ds_read_b128 v[224:227], v152 offset:6144
	ds_read_b128 v[228:231], v152 offset:7168
	global_load_lds_dwordx4 v[138:139], off
	v_lshl_add_u64 v[138:139], s[22:23], 0, v[142:143]
	s_add_i32 m0, s41, 0xe000
	s_nop 0
	global_load_lds_dwordx4 v[138:139], off
	s_waitcnt vmcnt(8)
	s_waitcnt lgkmcnt(0)
	s_setprio 1
	s_barrier
; #define PG8_STAGE(bufoff, gbase, voff) do { _Pragma("unroll") for (int _i = 0; _i < 2; ++_i) \
;         __builtin_amdgcn_global_load_lds((const unsigned*)((const char*)(gbase) + (voff)[_i]), (PG8_LAS unsigned*)(lds + (bufoff) + ldsw + _i * 8192), 16, 0, 0); } while (0)
; #define PG8_LDA(dst, b, h) do { _Pragma("unroll") for (int m = 0; m < 4; ++m) _Pragma("unroll") for (int k = 0; k < 2; ++k) dst[m][k] = *(const PG8_LAS bf16x8*)(lds + PG8_SA(b, h) + aoff + m * 2048 + k * 1024); } while (0)
; #define PG8_LDB(dst, b, h) do { _Pragma("unroll") for (int n = 0; n < 2; ++n) _Pragma("unroll") for (int k = 0; k < 2; ++k) dst[n][k] = *(const PG8_LAS bf16x8*)(lds + PG8_SB(b, h) + boff + n * 2048 + k * 1024); } while (0)
; #define PG8_MMA(ai, bj, At, Bt) do { __builtin_amdgcn_s_setprio(1); _Pragma("unroll") for (int m = 0; m < 4; ++m) _Pragma("unroll") for (int n = 0; n < 2; ++n) _Pragma("unroll") for (int k = 0; k < 2; ++k) \
;         acc[ai][bj][m][n] = __builtin_amdgcn_mfma_f32_16x16x32_bf16(Bt[n][k], At[m][k], acc[ai][bj][m][n], 0, 0, 0); __builtin_amdgcn_s_setprio(0); } while (0)
; #define PG8_WAIT_V(n) asm volatile("s_waitcnt vmcnt(" #n ")" ::: "memory")
; template <class Epi, class Sched, bool ALIGN_EPI = false, bool SP2 = false>
; __device__ __forceinline__ void gemm_phase(PG8_LAS unsigned char* lds, const Gemm g, const Sched& S, const Epi& E) {
;     ...
;             PG8_LDB(B0, 0, 0); PG8_LDB(B1, 0, 1); PG8_SCHED; PG8_LDA(At, 0, 0); PG8_STAGE(PG8_SA(1, 1), a1 + hstep, voffA);
;             PG8_WAIT_V(8); PG8_WAIT_L(0); PG8_BAR; PG8_MMA(0, 0, At, B0); PG8_MMA(0, 1, At, B1); PG8_BAR; PG8_SCHED;
;             PG8_LDA(At, 0, 1); PG8_STAGE(PG8_SB(0, 0), b2, voffB); PG8_STAGE(PG8_SB(0, 1), b2 + hstep, voffB); PG8_STAGE(PG8_SA(0, 0), a2, voffA);
;             PG8_WAIT_V(8); PG8_WAIT_L(0); PG8_BAR; PG8_MMA(1, 0, At, B0); PG8_MMA(1, 1, At, B1); PG8_BAR; PG8_SCHED;
;             PG8_LDB(B0, 1, 0); PG8_LDB(B1, 1, 1); PG8_SCHED; PG8_LDA(At, 1, 0); PG8_STAGE(PG8_SA(0, 1), a2 + hstep, voffA);
;             PG8_WAIT_V(8); PG8_WAIT_L(0); PG8_BAR; PG8_MMA(0, 0, At, B0); PG8_MMA(0, 1, At, B1); PG8_BAR; PG8_SCHED;
;             PG8_LDA(At, 1, 1); PG8_STAGE(PG8_SB(1, 0), b3, voffB); PG8_STAGE(PG8_SB(1, 1), b3 + hstep, voffB); PG8_STAGE(PG8_SA(1, 0), a3, voffA);
;             PG8_WAIT_V(8); PG8_WAIT_L(0); PG8_BAR; PG8_MMA(1, 0, At, B0); PG8_MMA(1, 1, At, B1); PG8_BAR; PG8_SCHED;
	v_mfma_f32_16x16x32_bf16 v[126:129], v[144:147], v[182:185], v[126:129]
	v_mfma_f32_16x16x32_bf16 v[122:125], v[158:161], v[182:185], v[122:125]
	v_mfma_f32_16x16x32_bf16 v[106:109], v[158:161], v[190:193], v[106:109]
	v_mfma_f32_16x16x32_bf16 v[110:113], v[144:147], v[190:193], v[110:113]
	v_mfma_f32_16x16x32_bf16 v[94:97], v[144:147], v[198:201], v[94:97]
	v_mfma_f32_16x16x32_bf16 v[90:93], v[158:161], v[198:201], v[90:93]
	v_mfma_f32_16x16x32_bf16 v[74:77], v[158:161], v[224:227], v[74:77]
	v_mfma_f32_16x16x32_bf16 v[78:81], v[144:147], v[224:227], v[78:81]
	v_mfma_f32_16x16x32_bf16 v[126:129], v[154:157], v[186:189], v[126:129]
	v_mfma_f32_16x16x32_bf16 v[122:125], v[162:165], v[186:189], v[122:125]
	v_mfma_f32_16x16x32_bf16 v[106:109], v[162:165], v[194:197], v[106:109]
	v_mfma_f32_16x16x32_bf16 v[110:113], v[154:157], v[194:197], v[110:113]
	v_mfma_f32_16x16x32_bf16 v[94:97], v[154:157], v[202:205], v[94:97]
	v_mfma_f32_16x16x32_bf16 v[90:93], v[162:165], v[202:205], v[90:93]
	v_mfma_f32_16x16x32_bf16 v[74:77], v[162:165], v[228:231], v[74:77]
	v_mfma_f32_16x16x32_bf16 v[78:81], v[154:157], v[228:231], v[78:81]
	v_mfma_f32_16x16x32_bf16 v[118:121], v[166:169], v[182:185], v[118:121]
	v_mfma_f32_16x16x32_bf16 v[114:117], v[174:177], v[182:185], v[114:117]
	v_mfma_f32_16x16x32_bf16 v[98:101], v[174:177], v[190:193], v[98:101]
	v_mfma_f32_16x16x32_bf16 v[102:105], v[166:169], v[190:193], v[102:105]
	v_mfma_f32_16x16x32_bf16 v[86:89], v[166:169], v[198:201], v[86:89]
	v_mfma_f32_16x16x32_bf16 v[82:85], v[174:177], v[198:201], v[82:85]
	v_mfma_f32_16x16x32_bf16 v[66:69], v[174:177], v[224:227], v[66:69]
	v_mfma_f32_16x16x32_bf16 v[70:73], v[166:169], v[224:227], v[70:73]
	v_mfma_f32_16x16x32_bf16 v[118:121], v[170:173], v[186:189], v[118:121]
	v_mfma_f32_16x16x32_bf16 v[114:117], v[178:181], v[186:189], v[114:117]
	v_mfma_f32_16x16x32_bf16 v[98:101], v[178:181], v[194:197], v[98:101]
	v_mfma_f32_16x16x32_bf16 v[102:105], v[170:173], v[194:197], v[102:105]
	v_mfma_f32_16x16x32_bf16 v[86:89], v[170:173], v[202:205], v[86:89]
	v_mfma_f32_16x16x32_bf16 v[82:85], v[178:181], v[202:205], v[82:85]
	v_mfma_f32_16x16x32_bf16 v[66:69], v[178:181], v[228:231], v[66:69]
	v_mfma_f32_16x16x32_bf16 v[70:73], v[170:173], v[228:231], v[70:73]
	s_barrier
	s_setprio 0
	s_add_i32 s52, s52, s31
	v_lshl_add_u64 v[138:139], s[24:25], 0, v[0:1]
	s_mov_b32 m0, s52
	ds_read_b128 v[182:185], v152 offset:16384
	ds_read_b128 v[186:189], v152 offset:17408
	ds_read_b128 v[190:193], v152 offset:18432
	ds_read_b128 v[194:197], v152 offset:19456
	ds_read_b128 v[198:201], v152 offset:20480
	ds_read_b128 v[202:205], v152 offset:21504
	ds_read_b128 v[224:227], v152 offset:22528
	ds_read_b128 v[228:231], v152 offset:23552
	global_load_lds_dwordx4 v[138:139], off
	s_add_i32 m0, s52, 0x2000
	s_add_u32 s52, s24, 0x40000
	v_lshl_add_u64 v[140:141], s[24:25], 0, v[134:135]
	s_addc_u32 s53, s25, 0
	s_add_i32 s55, s55, s31
	global_load_lds_dwordx4 v[140:141], off
	v_lshl_add_u64 v[232:233], s[52:53], 0, v[0:1]
	s_mov_b32 m0, s55
	v_lshl_add_u64 v[234:235], s[26:27], 0, v[132:133]
	global_load_lds_dwordx4 v[232:233], off
	v_lshl_add_u64 v[232:233], s[52:53], 0, v[134:135]
	s_add_i32 m0, s55, 0x2000
	s_nop 0
	global_load_lds_dwordx4 v[232:233], off
	v_lshl_add_u64 v[232:233], s[26:27], 0, v[130:131]
	s_mov_b32 m0, s41
	s_nop 0
	global_load_lds_dwordx4 v[232:233], off
	s_mov_b32 m0, s42
	s_nop 0
	global_load_lds_dwordx4 v[234:235], off
	s_waitcnt vmcnt(8)
	s_waitcnt lgkmcnt(0)
	s_setprio 1
	s_barrier
	v_mfma_f32_16x16x32_bf16 v[62:65], v[144:147], v[182:185], v[62:65]
	v_mfma_f32_16x16x32_bf16 v[58:61], v[158:161], v[182:185], v[58:61]
	v_mfma_f32_16x16x32_bf16 v[42:45], v[158:161], v[190:193], v[42:45]
	v_mfma_f32_16x16x32_bf16 v[46:49], v[144:147], v[190:193], v[46:49]
	v_mfma_f32_16x16x32_bf16 v[30:33], v[144:147], v[198:201], v[30:33]
	v_mfma_f32_16x16x32_bf16 v[26:29], v[158:161], v[198:201], v[26:29]
	v_mfma_f32_16x16x32_bf16 v[10:13], v[158:161], v[224:227], v[10:13]
	v_mfma_f32_16x16x32_bf16 v[14:17], v[144:147], v[224:227], v[14:17]
	v_mfma_f32_16x16x32_bf16 v[62:65], v[154:157], v[186:189], v[62:65]
	v_mfma_f32_16x16x32_bf16 v[58:61], v[162:165], v[186:189], v[58:61]
	v_mfma_f32_16x16x32_bf16 v[42:45], v[162:165], v[194:197], v[42:45]
	v_mfma_f32_16x16x32_bf16 v[46:49], v[154:157], v[194:197], v[46:49]
	v_mfma_f32_16x16x32_bf16 v[30:33], v[154:157], v[202:205], v[30:33]
	v_mfma_f32_16x16x32_bf16 v[26:29], v[162:165], v[202:205], v[26:29]
	v_mfma_f32_16x16x32_bf16 v[10:13], v[162:165], v[228:231], v[10:13]
	v_mfma_f32_16x16x32_bf16 v[14:17], v[154:157], v[228:231], v[14:17]
	v_mfma_f32_16x16x32_bf16 v[54:57], v[166:169], v[182:185], v[54:57]
	v_mfma_f32_16x16x32_bf16 v[50:53], v[174:177], v[182:185], v[50:53]
	v_mfma_f32_16x16x32_bf16 v[34:37], v[174:177], v[190:193], v[34:37]
	v_mfma_f32_16x16x32_bf16 v[38:41], v[166:169], v[190:193], v[38:41]
	v_mfma_f32_16x16x32_bf16 v[22:25], v[166:169], v[198:201], v[22:25]
	v_mfma_f32_16x16x32_bf16 v[18:21], v[174:177], v[198:201], v[18:21]
	v_mfma_f32_16x16x32_bf16 v[2:5], v[174:177], v[224:227], v[2:5]
	v_mfma_f32_16x16x32_bf16 v[6:9], v[166:169], v[224:227], v[6:9]
	v_mfma_f32_16x16x32_bf16 v[54:57], v[170:173], v[186:189], v[54:57]
	v_mfma_f32_16x16x32_bf16 v[50:53], v[178:181], v[186:189], v[50:53]
	v_mfma_f32_16x16x32_bf16 v[34:37], v[178:181], v[194:197], v[34:37]
	v_mfma_f32_16x16x32_bf16 v[38:41], v[170:173], v[194:197], v[38:41]
	v_mfma_f32_16x16x32_bf16 v[22:25], v[170:173], v[202:205], v[22:25]
	v_mfma_f32_16x16x32_bf16 v[18:21], v[178:181], v[202:205], v[18:21]
	v_mfma_f32_16x16x32_bf16 v[2:5], v[178:181], v[228:231], v[2:5]
	v_mfma_f32_16x16x32_bf16 v[6:9], v[170:173], v[228:231], v[6:9]
	s_barrier
; #define PG8_STAGE(bufoff, gbase, voff) do { _Pragma("unroll") for (int _i = 0; _i < 2; ++_i) \
;         __builtin_amdgcn_global_load_lds((const unsigned*)((const char*)(gbase) + (voff)[_i]), (PG8_LAS unsigned*)(lds + (bufoff) + ldsw + _i * 8192), 16, 0, 0); } while (0)
; #define PG8_LDA(dst, b, h) do { _Pragma("unroll") for (int m = 0; m < 4; ++m) _Pragma("unroll") for (int k = 0; k < 2; ++k) dst[m][k] = *(const PG8_LAS bf16x8*)(lds + PG8_SA(b, h) + aoff + m * 2048 + k * 1024); } while (0)
; #define PG8_LDB(dst, b, h) do { _Pragma("unroll") for (int n = 0; n < 2; ++n) _Pragma("unroll") for (int k = 0; k < 2; ++k) dst[n][k] = *(const PG8_LAS bf16x8*)(lds + PG8_SB(b, h) + boff + n * 2048 + k * 1024); } while (0)
; #define PG8_MMA(ai, bj, At, Bt) do { __builtin_amdgcn_s_setprio(1); _Pragma("unroll") for (int m = 0; m < 4; ++m) _Pragma("unroll") for (int n = 0; n < 2; ++n) _Pragma("unroll") for (int k = 0; k < 2; ++k) \
;         acc[ai][bj][m][n] = __builtin_amdgcn_mfma_f32_16x16x32_bf16(Bt[n][k], At[m][k], acc[ai][bj][m][n], 0, 0, 0); __builtin_amdgcn_s_setprio(0); } while (0)
; #define PG8_WAIT_V(n) asm volatile("s_waitcnt vmcnt(" #n ")" ::: "memory")
; #define PG8_WAIT_L(n) asm volatile("s_waitcnt lgkmcnt(" #n ")" ::: "memory")
; #define PG8_BAR __builtin_amdgcn_s_barrier()
; #define PG8_SCHED __builtin_amdgcn_sched_barrier(0)
; template <class Epi, class Sched, bool ALIGN_EPI = false, bool SP2 = false>
; __device__ __forceinline__ void gemm_phase(PG8_LAS unsigned char* lds, const Gemm g, const Sched& S, const Epi& E) {
;     ...
;             PG8_LDB(B0, 1, 0); PG8_LDB(B1, 1, 1); PG8_SCHED; PG8_LDA(At, 1, 0); PG8_STAGE(PG8_SA(0, 1), a2 + hstep, voffA);
;             PG8_WAIT_V(8); PG8_WAIT_L(0); PG8_BAR; PG8_MMA(0, 0, At, B0); PG8_MMA(0, 1, At, B1); PG8_BAR; PG8_SCHED;
;             PG8_LDA(At, 1, 1); PG8_STAGE(PG8_SB(1, 0), b3, voffB); PG8_STAGE(PG8_SB(1, 1), b3 + hstep, voffB); PG8_STAGE(PG8_SA(1, 0), a3, voffA);
;             PG8_WAIT_V(8); PG8_WAIT_L(0); PG8_BAR; PG8_MMA(1, 0, At, B0); PG8_MMA(1, 1, At, B1); PG8_BAR; PG8_SCHED;
	s_setprio 0
	s_add_i32 s52, 0, 0x18000
	v_add_u32_e32 v153, s52, v149
	s_add_i32 s53, 0, 0x1c000
	ds_read_b128 v[144:147], v153
	ds_read_b128 v[154:157], v153 offset:1024
	ds_read_b128 v[158:161], v153 offset:2048
	ds_read_b128 v[162:165], v153 offset:3072
	v_add_u32_e32 v153, s53, v149
	ds_read_b128 v[166:169], v153
	ds_read_b128 v[170:173], v153 offset:1024
	ds_read_b128 v[174:177], v153 offset:2048
	ds_read_b128 v[178:181], v153 offset:3072
	s_add_u32 s26, s26, 0x40000
	s_addc_u32 s27, s27, 0
	s_mov_b32 m0, s43
	v_lshl_add_u64 v[236:237], s[26:27], 0, v[130:131]
	ds_read_b128 v[182:185], v152 offset:32768
	ds_read_b128 v[186:189], v152 offset:33792
	ds_read_b128 v[190:193], v152 offset:34816
	ds_read_b128 v[194:197], v152 offset:35840
	ds_read_b128 v[198:201], v152 offset:36864
	ds_read_b128 v[202:205], v152 offset:37888
	ds_read_b128 v[224:227], v152 offset:38912
	ds_read_b128 v[228:231], v152 offset:39936
	global_load_lds_dwordx4 v[236:237], off
	v_lshl_add_u64 v[236:237], s[26:27], 0, v[132:133]
	s_mov_b32 m0, s44
	s_nop 0
	global_load_lds_dwordx4 v[236:237], off
	s_waitcnt vmcnt(8)
	s_waitcnt lgkmcnt(0)
	s_setprio 1
	s_barrier
	v_mfma_f32_16x16x32_bf16 v[126:129], v[144:147], v[182:185], v[126:129]
	v_mfma_f32_16x16x32_bf16 v[122:125], v[158:161], v[182:185], v[122:125]
	v_mfma_f32_16x16x32_bf16 v[106:109], v[158:161], v[190:193], v[106:109]
	v_mfma_f32_16x16x32_bf16 v[110:113], v[144:147], v[190:193], v[110:113]
	v_mfma_f32_16x16x32_bf16 v[94:97], v[144:147], v[198:201], v[94:97]
	v_mfma_f32_16x16x32_bf16 v[90:93], v[158:161], v[198:201], v[90:93]
	v_mfma_f32_16x16x32_bf16 v[74:77], v[158:161], v[224:227], v[74:77]
	v_mfma_f32_16x16x32_bf16 v[78:81], v[144:147], v[224:227], v[78:81]
	v_mfma_f32_16x16x32_bf16 v[126:129], v[154:157], v[186:189], v[126:129]
	v_mfma_f32_16x16x32_bf16 v[122:125], v[162:165], v[186:189], v[122:125]
	v_mfma_f32_16x16x32_bf16 v[106:109], v[162:165], v[194:197], v[106:109]
	v_mfma_f32_16x16x32_bf16 v[110:113], v[154:157], v[194:197], v[110:113]
	v_mfma_f32_16x16x32_bf16 v[94:97], v[154:157], v[202:205], v[94:97]
	v_mfma_f32_16x16x32_bf16 v[90:93], v[162:165], v[202:205], v[90:93]
	v_mfma_f32_16x16x32_bf16 v[74:77], v[162:165], v[228:231], v[74:77]
	v_mfma_f32_16x16x32_bf16 v[78:81], v[154:157], v[228:231], v[78:81]
	v_mfma_f32_16x16x32_bf16 v[118:121], v[166:169], v[182:185], v[118:121]
	v_mfma_f32_16x16x32_bf16 v[114:117], v[174:177], v[182:185], v[114:117]
	v_mfma_f32_16x16x32_bf16 v[98:101], v[174:177], v[190:193], v[98:101]
	v_mfma_f32_16x16x32_bf16 v[102:105], v[166:169], v[190:193], v[102:105]
	v_mfma_f32_16x16x32_bf16 v[86:89], v[166:169], v[198:201], v[86:89]
	v_mfma_f32_16x16x32_bf16 v[82:85], v[174:177], v[198:201], v[82:85]
	v_mfma_f32_16x16x32_bf16 v[66:69], v[174:177], v[224:227], v[66:69]
	v_mfma_f32_16x16x32_bf16 v[70:73], v[166:169], v[224:227], v[70:73]
	v_mfma_f32_16x16x32_bf16 v[118:121], v[170:173], v[186:189], v[118:121]
	v_mfma_f32_16x16x32_bf16 v[114:117], v[178:181], v[186:189], v[114:117]
	v_mfma_f32_16x16x32_bf16 v[98:101], v[178:181], v[194:197], v[98:101]
	v_mfma_f32_16x16x32_bf16 v[102:105], v[170:173], v[194:197], v[102:105]
	v_mfma_f32_16x16x32_bf16 v[86:89], v[170:173], v[202:205], v[86:89]
	v_mfma_f32_16x16x32_bf16 v[82:85], v[178:181], v[202:205], v[82:85]
	v_mfma_f32_16x16x32_bf16 v[66:69], v[178:181], v[228:231], v[66:69]
	v_mfma_f32_16x16x32_bf16 v[70:73], v[170:173], v[228:231], v[70:73]
	s_barrier
; #define PG8_STAGE(bufoff, gbase, voff) do { _Pragma("unroll") for (int _i = 0; _i < 2; ++_i) \
;         __builtin_amdgcn_global_load_lds((const unsigned*)((const char*)(gbase) + (voff)[_i]), (PG8_LAS unsigned*)(lds + (bufoff) + ldsw + _i * 8192), 16, 0, 0); } while (0)
; #define PG8_LDA(dst, b, h) do { _Pragma("unroll") for (int m = 0; m < 4; ++m) _Pragma("unroll") for (int k = 0; k < 2; ++k) dst[m][k] = *(const PG8_LAS bf16x8*)(lds + PG8_SA(b, h) + aoff + m * 2048 + k * 1024); } while (0)
; #define PG8_MMA(ai, bj, At, Bt) do { __builtin_amdgcn_s_setprio(1); _Pragma("unroll") for (int m = 0; m < 4; ++m) _Pragma("unroll") for (int n = 0; n < 2; ++n) _Pragma("unroll") for (int k = 0; k < 2; ++k) \
;         acc[ai][bj][m][n] = __builtin_amdgcn_mfma_f32_16x16x32_bf16(Bt[n][k], At[m][k], acc[ai][bj][m][n], 0, 0, 0); __builtin_amdgcn_s_setprio(0); } while (0)
; #define PG8_WAIT_V(n) asm volatile("s_waitcnt vmcnt(" #n ")" ::: "memory")
; #define PG8_WAIT_L(n) asm volatile("s_waitcnt lgkmcnt(" #n ")" ::: "memory")
; #define PG8_BAR __builtin_amdgcn_s_barrier()
; #define PG8_SCHED __builtin_amdgcn_sched_barrier(0)
; template <class Epi, class Sched, bool ALIGN_EPI = false, bool SP2 = false>
; __device__ __forceinline__ void gemm_phase(PG8_LAS unsigned char* lds, const Gemm g, const Sched& S, const Epi& E) {
;     ...
;         for (int t = 0; t < nt; t += 2) {
;             const bool last = (t == nt - 2);
;             const char* a1 = cA + (size_t)(t + 1) * kstep;
;             const char* a2 = last ? nA : cA + (size_t)(t + 2) * kstep; const char* b2 = last ? nB : cB + (size_t)(t + 2) * kstep;
;             const char* a3 = a2 + kstep; const char* b3 = b2 + kstep;
;     ...
;             PG8_LDA(At, 1, 1); PG8_STAGE(PG8_SB(1, 0), b3, voffB); PG8_STAGE(PG8_SB(1, 1), b3 + hstep, voffB); PG8_STAGE(PG8_SA(1, 0), a3, voffA);
;             PG8_WAIT_V(8); PG8_WAIT_L(0); PG8_BAR; PG8_MMA(1, 0, At, B0); PG8_MMA(1, 1, At, B1); PG8_BAR; PG8_SCHED;
	s_setprio 0
	s_add_i32 s26, s52, s31
	v_lshl_add_u64 v[138:139], v[138:139], 0, s[86:87]
	s_mov_b32 m0, s26
	ds_read_b128 v[182:185], v152 offset:49152
	ds_read_b128 v[186:189], v152 offset:50176
	ds_read_b128 v[190:193], v152 offset:51200
	ds_read_b128 v[194:197], v152 offset:52224
	ds_read_b128 v[198:201], v152 offset:53248
	ds_read_b128 v[202:205], v152 offset:54272
	ds_read_b128 v[224:227], v152 offset:55296
	ds_read_b128 v[228:231], v152 offset:56320
	global_load_lds_dwordx4 v[138:139], off
	s_add_i32 m0, s26, 0x2000
	s_add_u32 s24, s24, 0x40080
	v_lshl_add_u64 v[138:139], v[140:141], 0, s[86:87]
	s_addc_u32 s25, s25, 0
	s_add_i32 s26, s53, s31
	global_load_lds_dwordx4 v[138:139], off
	v_lshl_add_u64 v[138:139], s[24:25], 0, v[0:1]
	s_mov_b32 m0, s26
	s_nop 0
	global_load_lds_dwordx4 v[138:139], off
	v_lshl_add_u64 v[138:139], s[24:25], 0, v[134:135]
	s_add_i32 m0, s26, 0x2000
	s_nop 0
	global_load_lds_dwordx4 v[138:139], off
	v_lshl_add_u64 v[138:139], v[232:233], 0, s[86:87]
	s_mov_b32 m0, s45
	s_nop 0
	global_load_lds_dwordx4 v[138:139], off
	v_lshl_add_u64 v[138:139], v[234:235], 0, s[86:87]
	s_mov_b32 m0, s46
	s_nop 0
	global_load_lds_dwordx4 v[138:139], off
	s_waitcnt vmcnt(8)
	s_waitcnt lgkmcnt(0)
	s_setprio 1
	s_barrier
	v_mfma_f32_16x16x32_bf16 v[62:65], v[144:147], v[182:185], v[62:65]
	v_mfma_f32_16x16x32_bf16 v[58:61], v[158:161], v[182:185], v[58:61]
	v_mfma_f32_16x16x32_bf16 v[42:45], v[158:161], v[190:193], v[42:45]
	v_mfma_f32_16x16x32_bf16 v[46:49], v[144:147], v[190:193], v[46:49]
	v_mfma_f32_16x16x32_bf16 v[30:33], v[144:147], v[198:201], v[30:33]
	v_mfma_f32_16x16x32_bf16 v[26:29], v[158:161], v[198:201], v[26:29]
	v_mfma_f32_16x16x32_bf16 v[10:13], v[158:161], v[224:227], v[10:13]
	v_mfma_f32_16x16x32_bf16 v[14:17], v[144:147], v[224:227], v[14:17]
	v_mfma_f32_16x16x32_bf16 v[62:65], v[154:157], v[186:189], v[62:65]
	v_mfma_f32_16x16x32_bf16 v[58:61], v[162:165], v[186:189], v[58:61]
	v_mfma_f32_16x16x32_bf16 v[42:45], v[162:165], v[194:197], v[42:45]
	v_mfma_f32_16x16x32_bf16 v[46:49], v[154:157], v[194:197], v[46:49]
	v_mfma_f32_16x16x32_bf16 v[30:33], v[154:157], v[202:205], v[30:33]
	v_mfma_f32_16x16x32_bf16 v[26:29], v[162:165], v[202:205], v[26:29]
	v_mfma_f32_16x16x32_bf16 v[10:13], v[162:165], v[228:231], v[10:13]
	v_mfma_f32_16x16x32_bf16 v[14:17], v[154:157], v[228:231], v[14:17]
	v_mfma_f32_16x16x32_bf16 v[54:57], v[166:169], v[182:185], v[54:57]
	v_mfma_f32_16x16x32_bf16 v[50:53], v[174:177], v[182:185], v[50:53]
	v_mfma_f32_16x16x32_bf16 v[34:37], v[174:177], v[190:193], v[34:37]
	v_mfma_f32_16x16x32_bf16 v[38:41], v[166:169], v[190:193], v[38:41]
	v_mfma_f32_16x16x32_bf16 v[22:25], v[166:169], v[198:201], v[22:25]
	v_mfma_f32_16x16x32_bf16 v[18:21], v[174:177], v[198:201], v[18:21]
	v_mfma_f32_16x16x32_bf16 v[2:5], v[174:177], v[224:227], v[2:5]
	v_mfma_f32_16x16x32_bf16 v[6:9], v[166:169], v[224:227], v[6:9]
	v_mfma_f32_16x16x32_bf16 v[54:57], v[170:173], v[186:189], v[54:57]
	v_mfma_f32_16x16x32_bf16 v[50:53], v[178:181], v[186:189], v[50:53]
	v_mfma_f32_16x16x32_bf16 v[34:37], v[178:181], v[194:197], v[34:37]
	v_mfma_f32_16x16x32_bf16 v[38:41], v[170:173], v[194:197], v[38:41]
	v_mfma_f32_16x16x32_bf16 v[22:25], v[170:173], v[202:205], v[22:25]
	v_mfma_f32_16x16x32_bf16 v[18:21], v[178:181], v[202:205], v[18:21]
	v_mfma_f32_16x16x32_bf16 v[2:5], v[178:181], v[228:231], v[2:5]
	v_mfma_f32_16x16x32_bf16 v[6:9], v[170:173], v[228:231], v[6:9]
	s_barrier
	s_setprio 0
	s_add_i32 s51, s51, 2
	s_add_u32 s22, s22, 0x100
	s_addc_u32 s23, s23, 0
	s_add_u32 s49, s49, 0x100
	s_addc_u32 s50, s50, 0
	s_cmp_gt_u32 s51, 13
	s_cbranch_scc0 .LBB0_225

; #define PG8_STAGE(bufoff, gbase, voff) do { _Pragma("unroll") for (int _i = 0; _i < 2; ++_i) \
;         __builtin_amdgcn_global_load_lds((const unsigned*)((const char*)(gbase) + (voff)[_i]), (PG8_LAS unsigned*)(lds + (bufoff) + ldsw + _i * 8192), 16, 0, 0); } while (0)
; #define PG8_LDA(dst, b, h) do { _Pragma("unroll") for (int m = 0; m < 4; ++m) _Pragma("unroll") for (int k = 0; k < 2; ++k) dst[m][k] = *(const PG8_LAS bf16x8*)(lds + PG8_SA(b, h) + aoff + m * 2048 + k * 1024); } while (0)
; #define PG8_LDB(dst, b, h) do { _Pragma("unroll") for (int n = 0; n < 2; ++n) _Pragma("unroll") for (int k = 0; k < 2; ++k) dst[n][k] = *(const PG8_LAS bf16x8*)(lds + PG8_SB(b, h) + boff + n * 2048 + k * 1024); } while (0)
; template <class Epi, class Sched, bool ALIGN_EPI = false, bool SP2 = false>
; __device__ __forceinline__ void gemm_phase(PG8_LAS unsigned char* lds, const Gemm g, const Sched& S, const Epi& E) {
;     ...
;         for (int t = 0; t < nt; t += 2) {
;             const bool last = (t == nt - 2);
;             const char* a1 = cA + (size_t)(t + 1) * kstep;
;             const char* a2 = last ? nA : cA + (size_t)(t + 2) * kstep; const char* b2 = last ? nB : cB + (size_t)(t + 2) * kstep;
;             const char* a3 = a2 + kstep; const char* b3 = b2 + kstep;
;             if (last && has_next) S.a_ready(nxt);
;             if constexpr (SP2) {
;             PG8_LDB(B0, 0, 0); PG8_LDB(B1, 0, 1); PG8_SCHED; PG8_LDA(At, 0, 0); PG8_STAGE(PG8_SA(1, 1), a1 + hstep, voffA);
;             PG8_WAIT_V(8); PG8_WAIT_L(0); PG8_BAR; PG8_MMA(0, 0, At, B0); PG8_MMA(0, 1, At, B1); PG8_BAR; PG8_SCHED;
;             PG8_LDA(At, 0, 1); PG8_STAGE(PG8_SB(0, 0), b2, voffB); PG8_STAGE(PG8_SB(0, 1), b2 + hstep, voffB); PG8_STAGE(PG8_SA(0, 0), a2, voffA);
;             PG8_WAIT_V(8); PG8_WAIT_L(0); PG8_BAR; PG8_MMA(1, 0, At, B0); PG8_MMA(1, 1, At, B1); PG8_BAR; PG8_SCHED;
;             PG8_LDB(B0, 1, 0); PG8_LDB(B1, 1, 1); PG8_SCHED; PG8_LDA(At, 1, 0); PG8_STAGE(PG8_SA(0, 1), a2 + hstep, voffA);
;             PG8_WAIT_V(8); PG8_WAIT_L(0); PG8_BAR; PG8_MMA(0, 0, At, B0); PG8_MMA(0, 1, At, B1); PG8_BAR; PG8_SCHED;
;             PG8_LDA(At, 1, 1); PG8_STAGE(PG8_SB(1, 0), b3, voffB); PG8_STAGE(PG8_SB(1, 1), b3 + hstep, voffB); PG8_STAGE(PG8_SA(1, 0), a3, voffA);
;             PG8_WAIT_V(8); PG8_WAIT_L(0); PG8_BAR; PG8_MMA(1, 0, At, B0); PG8_MMA(1, 1, At, B1); PG8_BAR; PG8_SCHED;
.LBB0_362:
	s_add_u32 s16, s14, 0x100
	s_addc_u32 s17, s15, 0
	s_add_i32 s50, 0, 0x10000
	s_cmp_eq_u32 s49, 40
	s_cselect_b32 s21, s7, s17
	s_cselect_b32 s20, s6, s16
	v_add_u32_e32 v138, s50, v149
	s_cselect_b32 s19, s13, s48
	s_cselect_b32 s18, s12, s47
	s_add_i32 s51, 0, 0x14000
	ds_read_b128 v[144:147], v138
	ds_read_b128 v[152:155], v138 offset:1024
	ds_read_b128 v[156:159], v138 offset:2048
	ds_read_b128 v[160:163], v138 offset:3072
	v_add_u32_e32 v138, s51, v149
	ds_read_b128 v[164:167], v138
	ds_read_b128 v[168:171], v138 offset:1024
	ds_read_b128 v[172:175], v138 offset:2048
	ds_read_b128 v[176:179], v138 offset:3072
	v_lshl_add_u64 v[138:139], s[14:15], 0, v[136:137]
	s_add_i32 m0, s26, 0xc000
	ds_read_b128 v[180:183], v151
	ds_read_b128 v[184:187], v151 offset:1024
	ds_read_b128 v[188:191], v151 offset:2048
	ds_read_b128 v[192:195], v151 offset:3072
	ds_read_b128 v[196:199], v151 offset:4096
	ds_read_b128 v[200:203], v151 offset:5120
	ds_read_b128 v[224:227], v151 offset:6144
	ds_read_b128 v[228:231], v151 offset:7168
	global_load_lds_dwordx4 v[138:139], off
	v_lshl_add_u64 v[138:139], s[14:15], 0, v[142:143]
	s_add_i32 m0, s26, 0xe000
	s_nop 0
	global_load_lds_dwordx4 v[138:139], off
	s_waitcnt vmcnt(8)
	s_waitcnt lgkmcnt(0)
	s_setprio 1
	s_barrier
	v_mfma_f32_16x16x32_bf16 v[126:129], v[144:147], v[180:183], v[126:129]
	v_mfma_f32_16x16x32_bf16 v[122:125], v[156:159], v[180:183], v[122:125]
	v_mfma_f32_16x16x32_bf16 v[106:109], v[156:159], v[188:191], v[106:109]
	v_mfma_f32_16x16x32_bf16 v[110:113], v[144:147], v[188:191], v[110:113]
	v_mfma_f32_16x16x32_bf16 v[94:97], v[144:147], v[196:199], v[94:97]
	v_mfma_f32_16x16x32_bf16 v[90:93], v[156:159], v[196:199], v[90:93]
	v_mfma_f32_16x16x32_bf16 v[74:77], v[156:159], v[224:227], v[74:77]
	v_mfma_f32_16x16x32_bf16 v[78:81], v[144:147], v[224:227], v[78:81]
	v_mfma_f32_16x16x32_bf16 v[126:129], v[152:155], v[184:187], v[126:129]
	v_mfma_f32_16x16x32_bf16 v[122:125], v[160:163], v[184:187], v[122:125]
	v_mfma_f32_16x16x32_bf16 v[106:109], v[160:163], v[192:195], v[106:109]
	v_mfma_f32_16x16x32_bf16 v[110:113], v[152:155], v[192:195], v[110:113]
	v_mfma_f32_16x16x32_bf16 v[94:97], v[152:155], v[200:203], v[94:97]
	v_mfma_f32_16x16x32_bf16 v[90:93], v[160:163], v[200:203], v[90:93]
	v_mfma_f32_16x16x32_bf16 v[74:77], v[160:163], v[228:231], v[74:77]
	v_mfma_f32_16x16x32_bf16 v[78:81], v[152:155], v[228:231], v[78:81]
	v_mfma_f32_16x16x32_bf16 v[118:121], v[164:167], v[180:183], v[118:121]
	v_mfma_f32_16x16x32_bf16 v[114:117], v[172:175], v[180:183], v[114:117]
	v_mfma_f32_16x16x32_bf16 v[98:101], v[172:175], v[188:191], v[98:101]
	v_mfma_f32_16x16x32_bf16 v[102:105], v[164:167], v[188:191], v[102:105]
	v_mfma_f32_16x16x32_bf16 v[86:89], v[164:167], v[196:199], v[86:89]
	v_mfma_f32_16x16x32_bf16 v[82:85], v[172:175], v[196:199], v[82:85]
	v_mfma_f32_16x16x32_bf16 v[66:69], v[172:175], v[224:227], v[66:69]
	v_mfma_f32_16x16x32_bf16 v[70:73], v[164:167], v[224:227], v[70:73]
	v_mfma_f32_16x16x32_bf16 v[118:121], v[168:171], v[184:187], v[118:121]
	v_mfma_f32_16x16x32_bf16 v[114:117], v[176:179], v[184:187], v[114:117]
	v_mfma_f32_16x16x32_bf16 v[98:101], v[176:179], v[192:195], v[98:101]
	v_mfma_f32_16x16x32_bf16 v[102:105], v[168:171], v[192:195], v[102:105]
	v_mfma_f32_16x16x32_bf16 v[86:89], v[168:171], v[200:203], v[86:89]
	v_mfma_f32_16x16x32_bf16 v[82:85], v[176:179], v[200:203], v[82:85]
	v_mfma_f32_16x16x32_bf16 v[66:69], v[176:179], v[228:231], v[66:69]
	v_mfma_f32_16x16x32_bf16 v[70:73], v[168:171], v[228:231], v[70:73]
	s_barrier
	s_setprio 0
	s_add_i32 s14, s50, s23
	v_lshl_add_u64 v[138:139], s[18:19], 0, v[0:1]
	s_mov_b32 m0, s14
	ds_read_b128 v[180:183], v151 offset:16384
	ds_read_b128 v[184:187], v151 offset:17408
	ds_read_b128 v[188:191], v151 offset:18432
	ds_read_b128 v[192:195], v151 offset:19456
	ds_read_b128 v[196:199], v151 offset:20480
	ds_read_b128 v[200:203], v151 offset:21504
	ds_read_b128 v[224:227], v151 offset:22528
	ds_read_b128 v[228:231], v151 offset:23552
	global_load_lds_dwordx4 v[138:139], off
	s_add_i32 m0, s14, 0x2000
	s_add_u32 s14, s18, 0xb0000
	v_lshl_add_u64 v[140:141], s[18:19], 0, v[134:135]
	s_addc_u32 s15, s19, 0
	s_add_i32 s50, s51, s23
	global_load_lds_dwordx4 v[140:141], off
	v_lshl_add_u64 v[204:205], s[14:15], 0, v[0:1]
	s_mov_b32 m0, s50
	v_lshl_add_u64 v[232:233], s[20:21], 0, v[132:133]
	global_load_lds_dwordx4 v[204:205], off
	v_lshl_add_u64 v[204:205], s[14:15], 0, v[134:135]
	s_add_i32 m0, s50, 0x2000
	s_nop 0
	global_load_lds_dwordx4 v[204:205], off
	v_lshl_add_u64 v[204:205], s[20:21], 0, v[130:131]
	s_mov_b32 m0, s26
	s_nop 0
	global_load_lds_dwordx4 v[204:205], off
	s_mov_b32 m0, s27
	s_nop 0
	global_load_lds_dwordx4 v[232:233], off
	s_waitcnt vmcnt(8)
	s_waitcnt lgkmcnt(0)
	s_setprio 1
	s_barrier
; #define PG8_STAGE(bufoff, gbase, voff) do { _Pragma("unroll") for (int _i = 0; _i < 2; ++_i) \
;         __builtin_amdgcn_global_load_lds((const unsigned*)((const char*)(gbase) + (voff)[_i]), (PG8_LAS unsigned*)(lds + (bufoff) + ldsw + _i * 8192), 16, 0, 0); } while (0)
; #define PG8_LDA(dst, b, h) do { _Pragma("unroll") for (int m = 0; m < 4; ++m) _Pragma("unroll") for (int k = 0; k < 2; ++k) dst[m][k] = *(const PG8_LAS bf16x8*)(lds + PG8_SA(b, h) + aoff + m * 2048 + k * 1024); } while (0)
; #define PG8_LDB(dst, b, h) do { _Pragma("unroll") for (int n = 0; n < 2; ++n) _Pragma("unroll") for (int k = 0; k < 2; ++k) dst[n][k] = *(const PG8_LAS bf16x8*)(lds + PG8_SB(b, h) + boff + n * 2048 + k * 1024); } while (0)
; #define PG8_MMA(ai, bj, At, Bt) do { __builtin_amdgcn_s_setprio(1); _Pragma("unroll") for (int m = 0; m < 4; ++m) _Pragma("unroll") for (int n = 0; n < 2; ++n) _Pragma("unroll") for (int k = 0; k < 2; ++k) \
;         acc[ai][bj][m][n] = __builtin_amdgcn_mfma_f32_16x16x32_bf16(Bt[n][k], At[m][k], acc[ai][bj][m][n], 0, 0, 0); __builtin_amdgcn_s_setprio(0); } while (0)
; #define PG8_WAIT_V(n) asm volatile("s_waitcnt vmcnt(" #n ")" ::: "memory")
; #define PG8_WAIT_L(n) asm volatile("s_waitcnt lgkmcnt(" #n ")" ::: "memory")
; #define PG8_BAR __builtin_amdgcn_s_barrier()
; #define PG8_SCHED __builtin_amdgcn_sched_barrier(0)
; template <class Epi, class Sched, bool ALIGN_EPI = false, bool SP2 = false>
; __device__ __forceinline__ void gemm_phase(PG8_LAS unsigned char* lds, const Gemm g, const Sched& S, const Epi& E) {
;     ...
;             PG8_WAIT_V(8); PG8_WAIT_L(0); PG8_BAR; PG8_MMA(1, 0, At, B0); PG8_MMA(1, 1, At, B1); PG8_BAR; PG8_SCHED;
;             PG8_LDB(B0, 1, 0); PG8_LDB(B1, 1, 1); PG8_SCHED; PG8_LDA(At, 1, 0); PG8_STAGE(PG8_SA(0, 1), a2 + hstep, voffA);
;             PG8_WAIT_V(8); PG8_WAIT_L(0); PG8_BAR; PG8_MMA(0, 0, At, B0); PG8_MMA(0, 1, At, B1); PG8_BAR; PG8_SCHED;
	v_mfma_f32_16x16x32_bf16 v[62:65], v[144:147], v[180:183], v[62:65]
	v_mfma_f32_16x16x32_bf16 v[58:61], v[156:159], v[180:183], v[58:61]
	v_mfma_f32_16x16x32_bf16 v[42:45], v[156:159], v[188:191], v[42:45]
	v_mfma_f32_16x16x32_bf16 v[46:49], v[144:147], v[188:191], v[46:49]
	v_mfma_f32_16x16x32_bf16 v[30:33], v[144:147], v[196:199], v[30:33]
	v_mfma_f32_16x16x32_bf16 v[26:29], v[156:159], v[196:199], v[26:29]
	v_mfma_f32_16x16x32_bf16 v[10:13], v[156:159], v[224:227], v[10:13]
	v_mfma_f32_16x16x32_bf16 v[14:17], v[144:147], v[224:227], v[14:17]
	v_mfma_f32_16x16x32_bf16 v[62:65], v[152:155], v[184:187], v[62:65]
	v_mfma_f32_16x16x32_bf16 v[58:61], v[160:163], v[184:187], v[58:61]
	v_mfma_f32_16x16x32_bf16 v[42:45], v[160:163], v[192:195], v[42:45]
	v_mfma_f32_16x16x32_bf16 v[46:49], v[152:155], v[192:195], v[46:49]
	v_mfma_f32_16x16x32_bf16 v[30:33], v[152:155], v[200:203], v[30:33]
	v_mfma_f32_16x16x32_bf16 v[26:29], v[160:163], v[200:203], v[26:29]
	v_mfma_f32_16x16x32_bf16 v[10:13], v[160:163], v[228:231], v[10:13]
	v_mfma_f32_16x16x32_bf16 v[14:17], v[152:155], v[228:231], v[14:17]
	v_mfma_f32_16x16x32_bf16 v[54:57], v[164:167], v[180:183], v[54:57]
	v_mfma_f32_16x16x32_bf16 v[50:53], v[172:175], v[180:183], v[50:53]
	v_mfma_f32_16x16x32_bf16 v[34:37], v[172:175], v[188:191], v[34:37]
	v_mfma_f32_16x16x32_bf16 v[38:41], v[164:167], v[188:191], v[38:41]
	v_mfma_f32_16x16x32_bf16 v[22:25], v[164:167], v[196:199], v[22:25]
	v_mfma_f32_16x16x32_bf16 v[18:21], v[172:175], v[196:199], v[18:21]
	v_mfma_f32_16x16x32_bf16 v[2:5], v[172:175], v[224:227], v[2:5]
	v_mfma_f32_16x16x32_bf16 v[6:9], v[164:167], v[224:227], v[6:9]
	v_mfma_f32_16x16x32_bf16 v[54:57], v[168:171], v[184:187], v[54:57]
	v_mfma_f32_16x16x32_bf16 v[50:53], v[176:179], v[184:187], v[50:53]
	v_mfma_f32_16x16x32_bf16 v[34:37], v[176:179], v[192:195], v[34:37]
	v_mfma_f32_16x16x32_bf16 v[38:41], v[168:171], v[192:195], v[38:41]
	v_mfma_f32_16x16x32_bf16 v[22:25], v[168:171], v[200:203], v[22:25]
	v_mfma_f32_16x16x32_bf16 v[18:21], v[176:179], v[200:203], v[18:21]
	v_mfma_f32_16x16x32_bf16 v[2:5], v[176:179], v[228:231], v[2:5]
	v_mfma_f32_16x16x32_bf16 v[6:9], v[168:171], v[228:231], v[6:9]
	s_barrier
	s_setprio 0
	s_add_i32 s50, 0, 0x18000
	s_add_i32 s51, 0, 0x1c000
	v_add_u32_e32 v160, s50, v149
	v_add_u32_e32 v176, s51, v149
	ds_read_b128 v[144:147], v160
	ds_read_b128 v[152:155], v160 offset:1024
	ds_read_b128 v[156:159], v160 offset:2048
	ds_read_b128 v[160:163], v160 offset:3072
	ds_read_b128 v[164:167], v176
	ds_read_b128 v[168:171], v176 offset:1024
	ds_read_b128 v[172:175], v176 offset:2048
	ds_read_b128 v[176:179], v176 offset:3072
	s_add_u32 s14, s20, 0xb0000
	s_addc_u32 s15, s21, 0
	s_mov_b32 m0, s29
	v_lshl_add_u64 v[234:235], s[14:15], 0, v[130:131]
	ds_read_b128 v[180:183], v151 offset:32768
	ds_read_b128 v[184:187], v151 offset:33792
	ds_read_b128 v[188:191], v151 offset:34816
	ds_read_b128 v[192:195], v151 offset:35840
	ds_read_b128 v[196:199], v151 offset:36864
	ds_read_b128 v[200:203], v151 offset:37888
	ds_read_b128 v[224:227], v151 offset:38912
	ds_read_b128 v[228:231], v151 offset:39936
	global_load_lds_dwordx4 v[234:235], off
	v_lshl_add_u64 v[234:235], s[14:15], 0, v[132:133]
	s_mov_b32 m0, s30
	s_nop 0
	global_load_lds_dwordx4 v[234:235], off
	s_waitcnt vmcnt(8)
	s_waitcnt lgkmcnt(0)
	s_setprio 1
	s_barrier
	v_mfma_f32_16x16x32_bf16 v[126:129], v[144:147], v[180:183], v[126:129]
	v_mfma_f32_16x16x32_bf16 v[122:125], v[156:159], v[180:183], v[122:125]
	v_mfma_f32_16x16x32_bf16 v[106:109], v[156:159], v[188:191], v[106:109]
	v_mfma_f32_16x16x32_bf16 v[110:113], v[144:147], v[188:191], v[110:113]
	v_mfma_f32_16x16x32_bf16 v[94:97], v[144:147], v[196:199], v[94:97]
	v_mfma_f32_16x16x32_bf16 v[90:93], v[156:159], v[196:199], v[90:93]
	v_mfma_f32_16x16x32_bf16 v[74:77], v[156:159], v[224:227], v[74:77]
	v_mfma_f32_16x16x32_bf16 v[78:81], v[144:147], v[224:227], v[78:81]
	v_mfma_f32_16x16x32_bf16 v[126:129], v[152:155], v[184:187], v[126:129]
	v_mfma_f32_16x16x32_bf16 v[122:125], v[160:163], v[184:187], v[122:125]
	v_mfma_f32_16x16x32_bf16 v[106:109], v[160:163], v[192:195], v[106:109]
	v_mfma_f32_16x16x32_bf16 v[110:113], v[152:155], v[192:195], v[110:113]
	v_mfma_f32_16x16x32_bf16 v[94:97], v[152:155], v[200:203], v[94:97]
	v_mfma_f32_16x16x32_bf16 v[90:93], v[160:163], v[200:203], v[90:93]
	v_mfma_f32_16x16x32_bf16 v[74:77], v[160:163], v[228:231], v[74:77]
	v_mfma_f32_16x16x32_bf16 v[78:81], v[152:155], v[228:231], v[78:81]
	v_mfma_f32_16x16x32_bf16 v[118:121], v[164:167], v[180:183], v[118:121]
	v_mfma_f32_16x16x32_bf16 v[114:117], v[172:175], v[180:183], v[114:117]
	v_mfma_f32_16x16x32_bf16 v[98:101], v[172:175], v[188:191], v[98:101]
	v_mfma_f32_16x16x32_bf16 v[102:105], v[164:167], v[188:191], v[102:105]
	v_mfma_f32_16x16x32_bf16 v[86:89], v[164:167], v[196:199], v[86:89]
	v_mfma_f32_16x16x32_bf16 v[82:85], v[172:175], v[196:199], v[82:85]
	v_mfma_f32_16x16x32_bf16 v[66:69], v[172:175], v[224:227], v[66:69]
	v_mfma_f32_16x16x32_bf16 v[70:73], v[164:167], v[224:227], v[70:73]
	v_mfma_f32_16x16x32_bf16 v[118:121], v[168:171], v[184:187], v[118:121]
	v_mfma_f32_16x16x32_bf16 v[114:117], v[176:179], v[184:187], v[114:117]
	v_mfma_f32_16x16x32_bf16 v[98:101], v[176:179], v[192:195], v[98:101]
	v_mfma_f32_16x16x32_bf16 v[102:105], v[168:171], v[192:195], v[102:105]
	v_mfma_f32_16x16x32_bf16 v[86:89], v[168:171], v[200:203], v[86:89]
	v_mfma_f32_16x16x32_bf16 v[82:85], v[176:179], v[200:203], v[82:85]
	v_mfma_f32_16x16x32_bf16 v[66:69], v[176:179], v[228:231], v[66:69]
	v_mfma_f32_16x16x32_bf16 v[70:73], v[168:171], v[228:231], v[70:73]
	s_barrier
; #define PG8_STAGE(bufoff, gbase, voff) do { _Pragma("unroll") for (int _i = 0; _i < 2; ++_i) \
;         __builtin_amdgcn_global_load_lds((const unsigned*)((const char*)(gbase) + (voff)[_i]), (PG8_LAS unsigned*)(lds + (bufoff) + ldsw + _i * 8192), 16, 0, 0); } while (0)
; #define PG8_LDA(dst, b, h) do { _Pragma("unroll") for (int m = 0; m < 4; ++m) _Pragma("unroll") for (int k = 0; k < 2; ++k) dst[m][k] = *(const PG8_LAS bf16x8*)(lds + PG8_SA(b, h) + aoff + m * 2048 + k * 1024); } while (0)
; #define PG8_MMA(ai, bj, At, Bt) do { __builtin_amdgcn_s_setprio(1); _Pragma("unroll") for (int m = 0; m < 4; ++m) _Pragma("unroll") for (int n = 0; n < 2; ++n) _Pragma("unroll") for (int k = 0; k < 2; ++k) \
;         acc[ai][bj][m][n] = __builtin_amdgcn_mfma_f32_16x16x32_bf16(Bt[n][k], At[m][k], acc[ai][bj][m][n], 0, 0, 0); __builtin_amdgcn_s_setprio(0); } while (0)
; #define PG8_WAIT_V(n) asm volatile("s_waitcnt vmcnt(" #n ")" ::: "memory")
; #define PG8_WAIT_L(n) asm volatile("s_waitcnt lgkmcnt(" #n ")" ::: "memory")
; #define PG8_BAR __builtin_amdgcn_s_barrier()
; #define PG8_SCHED __builtin_amdgcn_sched_barrier(0)
; template <class Epi, class Sched, bool ALIGN_EPI = false, bool SP2 = false>
; __device__ __forceinline__ void gemm_phase(PG8_LAS unsigned char* lds, const Gemm g, const Sched& S, const Epi& E) {
;     ...
;             PG8_LDA(At, 1, 1); PG8_STAGE(PG8_SB(1, 0), b3, voffB); PG8_STAGE(PG8_SB(1, 1), b3 + hstep, voffB); PG8_STAGE(PG8_SA(1, 0), a3, voffA);
;             PG8_WAIT_V(8); PG8_WAIT_L(0); PG8_BAR; PG8_MMA(1, 0, At, B0); PG8_MMA(1, 1, At, B1); PG8_BAR; PG8_SCHED;
;     __device__ __forceinline__ void operator()(const f32x4 (&acc)[2][2][4][2], const Unit& u, int wr, int wc, int fr, int fq) const {
;     ...
;                 const int row = row0 + ai * 128 + m * 16; float p = 0.f;
; #pragma unroll
;                 for (int bj = 0; bj < 2; ++bj) {
;                     const size_t off = (size_t)row * D + col0 + bj * 128;
;                     const u32x4 xx = *(const u32x4*)(xb + off);
	s_setprio 0
	s_add_i32 s14, s50, s23
	v_lshl_add_u64 v[138:139], v[138:139], 0, s[86:87]
	s_mov_b32 m0, s14
	ds_read_b128 v[180:183], v151 offset:49152
	ds_read_b128 v[184:187], v151 offset:50176
	ds_read_b128 v[188:191], v151 offset:51200
	ds_read_b128 v[192:195], v151 offset:52224
	ds_read_b128 v[196:199], v151 offset:53248
	ds_read_b128 v[200:203], v151 offset:54272
	ds_read_b128 v[224:227], v151 offset:55296
	ds_read_b128 v[228:231], v151 offset:56320
	global_load_lds_dwordx4 v[138:139], off
	s_add_i32 m0, s14, 0x2000
	s_add_u32 s14, s18, 0xb0080
	v_lshl_add_u64 v[138:139], v[140:141], 0, s[86:87]
	s_addc_u32 s15, s19, 0
	s_add_i32 s18, s51, s23
	global_load_lds_dwordx4 v[138:139], off
	v_lshl_add_u64 v[138:139], s[14:15], 0, v[0:1]
	s_mov_b32 m0, s18
	s_nop 0
	global_load_lds_dwordx4 v[138:139], off
	v_lshl_add_u64 v[138:139], s[14:15], 0, v[134:135]
	s_add_i32 m0, s18, 0x2000
	s_nop 0
	global_load_lds_dwordx4 v[138:139], off
	v_lshl_add_u64 v[138:139], v[204:205], 0, s[86:87]
	s_mov_b32 m0, s38
	s_nop 0
	global_load_lds_dwordx4 v[138:139], off
	v_lshl_add_u64 v[138:139], v[232:233], 0, s[86:87]
	s_mov_b32 m0, s39
	s_nop 0
	global_load_lds_dwordx4 v[138:139], off
	s_waitcnt vmcnt(8)
	s_waitcnt lgkmcnt(0)
	s_setprio 1
	s_barrier
	v_mfma_f32_16x16x32_bf16 v[62:65], v[144:147], v[180:183], v[62:65]
	v_mfma_f32_16x16x32_bf16 v[58:61], v[156:159], v[180:183], v[58:61]
	v_mfma_f32_16x16x32_bf16 v[42:45], v[156:159], v[188:191], v[42:45]
	v_mfma_f32_16x16x32_bf16 v[46:49], v[144:147], v[188:191], v[46:49]
	v_mfma_f32_16x16x32_bf16 v[30:33], v[144:147], v[196:199], v[30:33]
	v_mfma_f32_16x16x32_bf16 v[26:29], v[156:159], v[196:199], v[26:29]
	v_mfma_f32_16x16x32_bf16 v[10:13], v[156:159], v[224:227], v[10:13]
	v_mfma_f32_16x16x32_bf16 v[14:17], v[144:147], v[224:227], v[14:17]
	v_mfma_f32_16x16x32_bf16 v[62:65], v[152:155], v[184:187], v[62:65]
	v_mfma_f32_16x16x32_bf16 v[58:61], v[160:163], v[184:187], v[58:61]
	v_mfma_f32_16x16x32_bf16 v[42:45], v[160:163], v[192:195], v[42:45]
	v_mfma_f32_16x16x32_bf16 v[46:49], v[152:155], v[192:195], v[46:49]
	v_mfma_f32_16x16x32_bf16 v[30:33], v[152:155], v[200:203], v[30:33]
	v_mfma_f32_16x16x32_bf16 v[26:29], v[160:163], v[200:203], v[26:29]
	v_mfma_f32_16x16x32_bf16 v[10:13], v[160:163], v[228:231], v[10:13]
	v_mfma_f32_16x16x32_bf16 v[14:17], v[152:155], v[228:231], v[14:17]
	v_mfma_f32_16x16x32_bf16 v[54:57], v[164:167], v[180:183], v[54:57]
	v_mfma_f32_16x16x32_bf16 v[50:53], v[172:175], v[180:183], v[50:53]
	v_mfma_f32_16x16x32_bf16 v[34:37], v[172:175], v[188:191], v[34:37]
	v_mfma_f32_16x16x32_bf16 v[38:41], v[164:167], v[188:191], v[38:41]
	v_mfma_f32_16x16x32_bf16 v[22:25], v[164:167], v[196:199], v[22:25]
	v_mfma_f32_16x16x32_bf16 v[18:21], v[172:175], v[196:199], v[18:21]
	v_mfma_f32_16x16x32_bf16 v[2:5], v[172:175], v[224:227], v[2:5]
	v_mfma_f32_16x16x32_bf16 v[6:9], v[164:167], v[224:227], v[6:9]
	v_mfma_f32_16x16x32_bf16 v[54:57], v[168:171], v[184:187], v[54:57]
	v_mfma_f32_16x16x32_bf16 v[50:53], v[176:179], v[184:187], v[50:53]
	v_mfma_f32_16x16x32_bf16 v[34:37], v[176:179], v[192:195], v[34:37]
	v_mfma_f32_16x16x32_bf16 v[38:41], v[168:171], v[192:195], v[38:41]
	v_mfma_f32_16x16x32_bf16 v[22:25], v[168:171], v[200:203], v[22:25]
	v_mfma_f32_16x16x32_bf16 v[18:21], v[176:179], v[200:203], v[18:21]
	v_mfma_f32_16x16x32_bf16 v[2:5], v[176:179], v[228:231], v[2:5]
	v_mfma_f32_16x16x32_bf16 v[6:9], v[168:171], v[228:231], v[6:9]
	s_barrier
	s_setprio 0
	s_add_i32 s49, s49, 2
	s_add_u32 s47, s47, 0x100
	s_addc_u32 s48, s48, 0
	s_cmp_gt_u32 s49, 41
	s_mov_b64 s[14:15], s[16:17]
	s_cbranch_scc0 .LBB0_362
	v_lshl_add_u32 v138, s46, 8, v148
	v_lshl_or_b32 v139, s45, 8, v150
	v_lshlrev_b32_e32 v138, 11, v138
	v_lshl_add_u32 v138, v139, 1, v138
	global_load_dwordx4 v[152:155], v138, s[34:35]
	global_load_dwordx4 v[156:159], v138, s[34:35] offset:256
	v_add_u32_e32 v139, 0x8000, v138
	global_load_dwordx4 v[160:163], v139, s[34:35]
	global_load_dwordx4 v[164:167], v139, s[34:35] offset:256
	v_add_u32_e32 v139, 0x10000, v138
	global_load_dwordx4 v[168:171], v139, s[34:35]
	global_load_dwordx4 v[172:175], v139, s[34:35] offset:256
	v_add_u32_e32 v139, 0x18000, v138
	global_load_dwordx4 v[176:179], v139, s[34:35]
	global_load_dwordx4 v[180:183], v139, s[34:35] offset:256
	v_add_u32_e32 v139, 0x40000, v138
	global_load_dwordx4 v[184:187], v139, s[34:35]
	global_load_dwordx4 v[188:191], v139, s[34:35] offset:256
	v_add_u32_e32 v139, 0x48000, v138
	global_load_dwordx4 v[192:195], v139, s[34:35]
	global_load_dwordx4 v[196:199], v139, s[34:35] offset:256
	v_add_u32_e32 v139, 0x50000, v138
	global_load_dwordx4 v[200:203], v139, s[34:35]
	global_load_dwordx4 v[224:227], v139, s[34:35] offset:256
	v_add_u32_e32 v139, 0x58000, v138
	global_load_dwordx4 v[228:231], v139, s[34:35]
	global_load_dwordx4 v[232:235], v139, s[34:35] offset:256
	s_and_b64 vcc, exec, s[10:11]
	s_cbranch_vccz .LBB0_365
	s_barrier

; #define PG8_STAGE(bufoff, gbase, voff) do { _Pragma("unroll") for (int _i = 0; _i < 2; ++_i) \
;         __builtin_amdgcn_global_load_lds((const unsigned*)((const char*)(gbase) + (voff)[_i]), (PG8_LAS unsigned*)(lds + (bufoff) + ldsw + _i * 8192), 16, 0, 0); } while (0)
; #define PG8_LDA(dst, b, h) do { _Pragma("unroll") for (int m = 0; m < 4; ++m) _Pragma("unroll") for (int k = 0; k < 2; ++k) dst[m][k] = *(const PG8_LAS bf16x8*)(lds + PG8_SA(b, h) + aoff + m * 2048 + k * 1024); } while (0)
; template <class Epi, class Sched, bool ALIGN_EPI = false, bool SP2 = false>
; __device__ __forceinline__ void gemm_phase(PG8_LAS unsigned char* lds, const Gemm g, const Sched& S, const Epi& E) {
;     ...
;         const bool has_next = S.next(ui + 1, nxt);
;         const char* nA = has_next ? (const char*)g.A + (size_t)nxt.pm * tstep : cA; const char* nB = has_next ? (const char*)g.Bt + (size_t)nxt.pn * tstep : cB;
;         for (int t = 0; t < nt; t += 2) {
;             const bool last = (t == nt - 2);
;             const char* a1 = cA + (size_t)(t + 1) * kstep;
;             const char* a2 = last ? nA : cA + (size_t)(t + 2) * kstep; const char* b2 = last ? nB : cB + (size_t)(t + 2) * kstep;
;             const char* a3 = a2 + kstep; const char* b3 = b2 + kstep;
;             if (last && has_next) S.a_ready(nxt);
;             if constexpr (SP2) {
;             PG8_LDB(B0, 0, 0); PG8_LDB(B1, 0, 1); PG8_SCHED; PG8_LDA(At, 0, 0); PG8_STAGE(PG8_SA(1, 1), a1 + hstep, voffA);
;             PG8_WAIT_V(8); PG8_WAIT_L(0); PG8_BAR; PG8_MMA(0, 0, At, B0); PG8_MMA(0, 1, At, B1); PG8_BAR; PG8_SCHED;
;             PG8_LDA(At, 0, 1); PG8_STAGE(PG8_SB(0, 0), b2, voffB); PG8_STAGE(PG8_SB(0, 1), b2 + hstep, voffB); PG8_STAGE(PG8_SA(0, 0), a2, voffA);
;             PG8_WAIT_V(8); PG8_WAIT_L(0); PG8_BAR; PG8_MMA(1, 0, At, B0); PG8_MMA(1, 1, At, B1); PG8_BAR; PG8_SCHED;
;             PG8_LDB(B0, 1, 0); PG8_LDB(B1, 1, 1); PG8_SCHED; PG8_LDA(At, 1, 0); PG8_STAGE(PG8_SA(0, 1), a2 + hstep, voffA);
;             PG8_WAIT_V(8); PG8_WAIT_L(0); PG8_BAR; PG8_MMA(0, 0, At, B0); PG8_MMA(0, 1, At, B1); PG8_BAR; PG8_SCHED;
;             PG8_LDA(At, 1, 1); PG8_STAGE(PG8_SB(1, 0), b3, voffB); PG8_STAGE(PG8_SB(1, 1), b3 + hstep, voffB); PG8_STAGE(PG8_SA(1, 0), a3, voffA);
;             PG8_WAIT_V(8); PG8_WAIT_L(0); PG8_BAR; PG8_MMA(1, 0, At, B0); PG8_MMA(1, 1, At, B1); PG8_BAR; PG8_SCHED;
.LBB0_491:
	s_ashr_i32 s15, s14, 31
	s_lshl_b64 s[16:17], s[14:15], 19
	s_add_u32 s16, s34, s16
	s_addc_u32 s17, s35, s17
	s_and_b64 s[18:19], s[2:3], exec
	s_cselect_b32 s5, s17, s9
	s_cselect_b32 s7, s16, s8
	s_ashr_i32 s13, s12, 31
	s_lshl_b64 s[18:19], s[12:13], 19
	s_add_u32 s18, s27, s18
	s_addc_u32 s19, s29, s19
	s_and_b64 s[22:23], s[2:3], exec
	s_cselect_b32 s13, s19, s21
	s_cselect_b32 s15, s18, s20
	s_add_u32 s8, s8, 0x40080
	s_addc_u32 s9, s9, 0
	s_add_u32 s45, s20, 0x100
	s_addc_u32 s46, s21, 0
	s_mov_b32 s47, -2
	s_add_u32 s20, s8, 0xfffc0080
	s_addc_u32 s21, s9, -1
	s_add_i32 s48, 0, 0x10000
	s_cmp_eq_u32 s47, 12
	s_cselect_b32 s23, s5, s21
	s_cselect_b32 s22, s7, s20
	v_add_u32_e32 v138, s48, v161
	s_cselect_b32 s21, s13, s46
	s_cselect_b32 s20, s15, s45
	s_add_i32 s50, 0, 0x14000
	ds_read_b128 v[144:147], v138
	ds_read_b128 v[148:151], v138 offset:1024
	ds_read_b128 v[152:155], v138 offset:2048
	ds_read_b128 v[156:159], v138 offset:3072
	v_add_u32_e32 v138, s50, v161
	ds_read_b128 v[166:169], v138
	ds_read_b128 v[170:173], v138 offset:1024
	ds_read_b128 v[174:177], v138 offset:2048
	ds_read_b128 v[178:181], v138 offset:3072
	v_lshl_add_u64 v[138:139], s[8:9], 0, v[136:137]
	s_add_i32 m0, s30, 0xc000
	ds_read_b128 v[182:185], v164
	ds_read_b128 v[186:189], v164 offset:1024
	ds_read_b128 v[190:193], v164 offset:2048
	ds_read_b128 v[194:197], v164 offset:3072
	ds_read_b128 v[198:201], v164 offset:4096
	ds_read_b128 v[202:205], v164 offset:5120
	ds_read_b128 v[224:227], v164 offset:6144
	ds_read_b128 v[228:231], v164 offset:7168
	global_load_lds_dwordx4 v[138:139], off
	v_lshl_add_u64 v[138:139], s[8:9], 0, v[142:143]
	s_add_i32 m0, s30, 0xe000
	s_nop 0
	global_load_lds_dwordx4 v[138:139], off
	s_waitcnt vmcnt(8)
	s_waitcnt lgkmcnt(0)
	s_setprio 1
	s_barrier
	v_mfma_f32_16x16x32_bf16 v[126:129], v[144:147], v[182:185], 0
	v_mfma_f32_16x16x32_bf16 v[122:125], v[152:155], v[182:185], 0
	v_mfma_f32_16x16x32_bf16 v[110:113], v[144:147], v[190:193], 0
	v_mfma_f32_16x16x32_bf16 v[106:109], v[152:155], v[190:193], 0
	v_mfma_f32_16x16x32_bf16 v[94:97], v[144:147], v[198:201], 0
	v_mfma_f32_16x16x32_bf16 v[90:93], v[152:155], v[198:201], 0
	v_mfma_f32_16x16x32_bf16 v[78:81], v[144:147], v[224:227], 0
	v_mfma_f32_16x16x32_bf16 v[74:77], v[152:155], v[224:227], 0
	v_mfma_f32_16x16x32_bf16 v[126:129], v[148:151], v[186:189], v[126:129]
	v_mfma_f32_16x16x32_bf16 v[122:125], v[156:159], v[186:189], v[122:125]
	v_mfma_f32_16x16x32_bf16 v[106:109], v[156:159], v[194:197], v[106:109]
	v_mfma_f32_16x16x32_bf16 v[110:113], v[148:151], v[194:197], v[110:113]
	v_mfma_f32_16x16x32_bf16 v[94:97], v[148:151], v[202:205], v[94:97]
	v_mfma_f32_16x16x32_bf16 v[90:93], v[156:159], v[202:205], v[90:93]
	v_mfma_f32_16x16x32_bf16 v[74:77], v[156:159], v[228:231], v[74:77]
	v_mfma_f32_16x16x32_bf16 v[78:81], v[148:151], v[228:231], v[78:81]
	v_mfma_f32_16x16x32_bf16 v[118:121], v[166:169], v[182:185], 0
	v_mfma_f32_16x16x32_bf16 v[114:117], v[174:177], v[182:185], 0
	v_mfma_f32_16x16x32_bf16 v[102:105], v[166:169], v[190:193], 0
	v_mfma_f32_16x16x32_bf16 v[98:101], v[174:177], v[190:193], 0
	v_mfma_f32_16x16x32_bf16 v[86:89], v[166:169], v[198:201], 0
	v_mfma_f32_16x16x32_bf16 v[82:85], v[174:177], v[198:201], 0
	v_mfma_f32_16x16x32_bf16 v[70:73], v[166:169], v[224:227], 0
	v_mfma_f32_16x16x32_bf16 v[66:69], v[174:177], v[224:227], 0
	v_mfma_f32_16x16x32_bf16 v[118:121], v[170:173], v[186:189], v[118:121]
	v_mfma_f32_16x16x32_bf16 v[114:117], v[178:181], v[186:189], v[114:117]
	v_mfma_f32_16x16x32_bf16 v[98:101], v[178:181], v[194:197], v[98:101]
	v_mfma_f32_16x16x32_bf16 v[102:105], v[170:173], v[194:197], v[102:105]
	v_mfma_f32_16x16x32_bf16 v[86:89], v[170:173], v[202:205], v[86:89]
	v_mfma_f32_16x16x32_bf16 v[82:85], v[178:181], v[202:205], v[82:85]
	v_mfma_f32_16x16x32_bf16 v[66:69], v[178:181], v[228:231], v[66:69]
	v_mfma_f32_16x16x32_bf16 v[70:73], v[170:173], v[228:231], v[70:73]
	s_barrier
	s_setprio 0
	s_add_i32 s48, s48, s26
	v_lshl_add_u64 v[138:139], s[20:21], 0, v[0:1]
	s_mov_b32 m0, s48
	ds_read_b128 v[182:185], v164 offset:16384
	ds_read_b128 v[186:189], v164 offset:17408
	ds_read_b128 v[190:193], v164 offset:18432
	ds_read_b128 v[194:197], v164 offset:19456
	ds_read_b128 v[198:201], v164 offset:20480
	ds_read_b128 v[202:205], v164 offset:21504
	ds_read_b128 v[224:227], v164 offset:22528
	ds_read_b128 v[228:231], v164 offset:23552
	global_load_lds_dwordx4 v[138:139], off
	s_add_i32 m0, s48, 0x2000
	s_add_u32 s48, s20, 0x40000
	v_lshl_add_u64 v[140:141], s[20:21], 0, v[134:135]
	s_addc_u32 s49, s21, 0
	s_add_i32 s50, s50, s26
	global_load_lds_dwordx4 v[140:141], off
	v_lshl_add_u64 v[232:233], s[48:49], 0, v[0:1]
	s_mov_b32 m0, s50
	v_lshl_add_u64 v[234:235], s[22:23], 0, v[132:133]
	global_load_lds_dwordx4 v[232:233], off
	v_lshl_add_u64 v[232:233], s[48:49], 0, v[134:135]
	s_add_i32 m0, s50, 0x2000
	s_nop 0
	global_load_lds_dwordx4 v[232:233], off
	v_lshl_add_u64 v[232:233], s[22:23], 0, v[130:131]
	s_mov_b32 m0, s30
	s_nop 0
	global_load_lds_dwordx4 v[232:233], off
	s_mov_b32 m0, s31
	s_nop 0
	global_load_lds_dwordx4 v[234:235], off
	s_waitcnt vmcnt(8)
	s_waitcnt lgkmcnt(0)
	s_setprio 1
	s_barrier
; #define PG8_STAGE(bufoff, gbase, voff) do { _Pragma("unroll") for (int _i = 0; _i < 2; ++_i) \
;         __builtin_amdgcn_global_load_lds((const unsigned*)((const char*)(gbase) + (voff)[_i]), (PG8_LAS unsigned*)(lds + (bufoff) + ldsw + _i * 8192), 16, 0, 0); } while (0)
; #define PG8_LDA(dst, b, h) do { _Pragma("unroll") for (int m = 0; m < 4; ++m) _Pragma("unroll") for (int k = 0; k < 2; ++k) dst[m][k] = *(const PG8_LAS bf16x8*)(lds + PG8_SA(b, h) + aoff + m * 2048 + k * 1024); } while (0)
; #define PG8_LDB(dst, b, h) do { _Pragma("unroll") for (int n = 0; n < 2; ++n) _Pragma("unroll") for (int k = 0; k < 2; ++k) dst[n][k] = *(const PG8_LAS bf16x8*)(lds + PG8_SB(b, h) + boff + n * 2048 + k * 1024); } while (0)
; #define PG8_MMA(ai, bj, At, Bt) do { __builtin_amdgcn_s_setprio(1); _Pragma("unroll") for (int m = 0; m < 4; ++m) _Pragma("unroll") for (int n = 0; n < 2; ++n) _Pragma("unroll") for (int k = 0; k < 2; ++k) \
;         acc[ai][bj][m][n] = __builtin_amdgcn_mfma_f32_16x16x32_bf16(Bt[n][k], At[m][k], acc[ai][bj][m][n], 0, 0, 0); __builtin_amdgcn_s_setprio(0); } while (0)
; #define PG8_WAIT_V(n) asm volatile("s_waitcnt vmcnt(" #n ")" ::: "memory")
; #define PG8_WAIT_L(n) asm volatile("s_waitcnt lgkmcnt(" #n ")" ::: "memory")
; #define PG8_BAR __builtin_amdgcn_s_barrier()
; #define PG8_SCHED __builtin_amdgcn_sched_barrier(0)
; template <class Epi, class Sched, bool ALIGN_EPI = false, bool SP2 = false>
; __device__ __forceinline__ void gemm_phase(PG8_LAS unsigned char* lds, const Gemm g, const Sched& S, const Epi& E) {
;     ...
;             PG8_WAIT_V(8); PG8_WAIT_L(0); PG8_BAR; PG8_MMA(0, 0, At, B0); PG8_MMA(0, 1, At, B1); PG8_BAR; PG8_SCHED;
;             PG8_LDA(At, 0, 1); PG8_STAGE(PG8_SB(0, 0), b2, voffB); PG8_STAGE(PG8_SB(0, 1), b2 + hstep, voffB); PG8_STAGE(PG8_SA(0, 0), a2, voffA);
;             PG8_WAIT_V(8); PG8_WAIT_L(0); PG8_BAR; PG8_MMA(1, 0, At, B0); PG8_MMA(1, 1, At, B1); PG8_BAR; PG8_SCHED;
;             PG8_LDB(B0, 1, 0); PG8_LDB(B1, 1, 1); PG8_SCHED; PG8_LDA(At, 1, 0); PG8_STAGE(PG8_SA(0, 1), a2 + hstep, voffA);
;             PG8_WAIT_V(8); PG8_WAIT_L(0); PG8_BAR; PG8_MMA(0, 0, At, B0); PG8_MMA(0, 1, At, B1); PG8_BAR; PG8_SCHED;
	v_mfma_f32_16x16x32_bf16 v[62:65], v[144:147], v[182:185], 0
	v_mfma_f32_16x16x32_bf16 v[58:61], v[152:155], v[182:185], 0
	v_mfma_f32_16x16x32_bf16 v[46:49], v[144:147], v[190:193], 0
	v_mfma_f32_16x16x32_bf16 v[42:45], v[152:155], v[190:193], 0
	v_mfma_f32_16x16x32_bf16 v[30:33], v[144:147], v[198:201], 0
	v_mfma_f32_16x16x32_bf16 v[26:29], v[152:155], v[198:201], 0
	v_mfma_f32_16x16x32_bf16 v[14:17], v[144:147], v[224:227], 0
	v_mfma_f32_16x16x32_bf16 v[10:13], v[152:155], v[224:227], 0
	v_mfma_f32_16x16x32_bf16 v[62:65], v[148:151], v[186:189], v[62:65]
	v_mfma_f32_16x16x32_bf16 v[58:61], v[156:159], v[186:189], v[58:61]
	v_mfma_f32_16x16x32_bf16 v[42:45], v[156:159], v[194:197], v[42:45]
	v_mfma_f32_16x16x32_bf16 v[46:49], v[148:151], v[194:197], v[46:49]
	v_mfma_f32_16x16x32_bf16 v[30:33], v[148:151], v[202:205], v[30:33]
	v_mfma_f32_16x16x32_bf16 v[26:29], v[156:159], v[202:205], v[26:29]
	v_mfma_f32_16x16x32_bf16 v[10:13], v[156:159], v[228:231], v[10:13]
	v_mfma_f32_16x16x32_bf16 v[14:17], v[148:151], v[228:231], v[14:17]
	v_mfma_f32_16x16x32_bf16 v[54:57], v[166:169], v[182:185], 0
	v_mfma_f32_16x16x32_bf16 v[50:53], v[174:177], v[182:185], 0
	v_mfma_f32_16x16x32_bf16 v[38:41], v[166:169], v[190:193], 0
	v_mfma_f32_16x16x32_bf16 v[34:37], v[174:177], v[190:193], 0
	v_mfma_f32_16x16x32_bf16 v[22:25], v[166:169], v[198:201], 0
	v_mfma_f32_16x16x32_bf16 v[18:21], v[174:177], v[198:201], 0
	v_mfma_f32_16x16x32_bf16 v[6:9], v[166:169], v[224:227], 0
	v_mfma_f32_16x16x32_bf16 v[2:5], v[174:177], v[224:227], 0
	v_mfma_f32_16x16x32_bf16 v[54:57], v[170:173], v[186:189], v[54:57]
	v_mfma_f32_16x16x32_bf16 v[50:53], v[178:181], v[186:189], v[50:53]
	v_mfma_f32_16x16x32_bf16 v[34:37], v[178:181], v[194:197], v[34:37]
	v_mfma_f32_16x16x32_bf16 v[38:41], v[170:173], v[194:197], v[38:41]
	v_mfma_f32_16x16x32_bf16 v[22:25], v[170:173], v[202:205], v[22:25]
	v_mfma_f32_16x16x32_bf16 v[18:21], v[178:181], v[202:205], v[18:21]
	v_mfma_f32_16x16x32_bf16 v[2:5], v[178:181], v[228:231], v[2:5]
	v_mfma_f32_16x16x32_bf16 v[6:9], v[170:173], v[228:231], v[6:9]
	s_barrier
	s_setprio 0
	s_add_i32 s48, 0, 0x18000
	s_add_i32 s49, 0, 0x1c000
	v_add_u32_e32 v156, s48, v161
	v_add_u32_e32 v165, s49, v161
	ds_read_b128 v[144:147], v156
	ds_read_b128 v[148:151], v156 offset:1024
	ds_read_b128 v[152:155], v156 offset:2048
	ds_read_b128 v[156:159], v156 offset:3072
	ds_read_b128 v[166:169], v165
	ds_read_b128 v[170:173], v165 offset:1024
	ds_read_b128 v[174:177], v165 offset:2048
	ds_read_b128 v[178:181], v165 offset:3072
	s_add_u32 s22, s22, 0x40000
	s_addc_u32 s23, s23, 0
	s_mov_b32 m0, s38
	v_lshl_add_u64 v[236:237], s[22:23], 0, v[130:131]
	ds_read_b128 v[182:185], v164 offset:32768
	ds_read_b128 v[186:189], v164 offset:33792
	ds_read_b128 v[190:193], v164 offset:34816
	ds_read_b128 v[194:197], v164 offset:35840
	ds_read_b128 v[198:201], v164 offset:36864
	ds_read_b128 v[202:205], v164 offset:37888
	ds_read_b128 v[224:227], v164 offset:38912
	ds_read_b128 v[228:231], v164 offset:39936
	global_load_lds_dwordx4 v[236:237], off
	v_lshl_add_u64 v[236:237], s[22:23], 0, v[132:133]
	s_mov_b32 m0, s39
	s_nop 0
	global_load_lds_dwordx4 v[236:237], off
	s_waitcnt vmcnt(8)
	s_waitcnt lgkmcnt(0)
	s_setprio 1
	s_barrier
	v_mfma_f32_16x16x32_bf16 v[126:129], v[144:147], v[182:185], v[126:129]
	v_mfma_f32_16x16x32_bf16 v[122:125], v[152:155], v[182:185], v[122:125]
	v_mfma_f32_16x16x32_bf16 v[106:109], v[152:155], v[190:193], v[106:109]
	v_mfma_f32_16x16x32_bf16 v[110:113], v[144:147], v[190:193], v[110:113]
	v_mfma_f32_16x16x32_bf16 v[94:97], v[144:147], v[198:201], v[94:97]
	v_mfma_f32_16x16x32_bf16 v[90:93], v[152:155], v[198:201], v[90:93]
	v_mfma_f32_16x16x32_bf16 v[74:77], v[152:155], v[224:227], v[74:77]
	v_mfma_f32_16x16x32_bf16 v[78:81], v[144:147], v[224:227], v[78:81]
	v_mfma_f32_16x16x32_bf16 v[126:129], v[148:151], v[186:189], v[126:129]
	v_mfma_f32_16x16x32_bf16 v[122:125], v[156:159], v[186:189], v[122:125]
	v_mfma_f32_16x16x32_bf16 v[106:109], v[156:159], v[194:197], v[106:109]
	v_mfma_f32_16x16x32_bf16 v[110:113], v[148:151], v[194:197], v[110:113]
	v_mfma_f32_16x16x32_bf16 v[94:97], v[148:151], v[202:205], v[94:97]
	v_mfma_f32_16x16x32_bf16 v[90:93], v[156:159], v[202:205], v[90:93]
	v_mfma_f32_16x16x32_bf16 v[74:77], v[156:159], v[228:231], v[74:77]
	v_mfma_f32_16x16x32_bf16 v[78:81], v[148:151], v[228:231], v[78:81]
	v_mfma_f32_16x16x32_bf16 v[118:121], v[166:169], v[182:185], v[118:121]
	v_mfma_f32_16x16x32_bf16 v[114:117], v[174:177], v[182:185], v[114:117]
	v_mfma_f32_16x16x32_bf16 v[98:101], v[174:177], v[190:193], v[98:101]
	v_mfma_f32_16x16x32_bf16 v[102:105], v[166:169], v[190:193], v[102:105]
	v_mfma_f32_16x16x32_bf16 v[86:89], v[166:169], v[198:201], v[86:89]
	v_mfma_f32_16x16x32_bf16 v[82:85], v[174:177], v[198:201], v[82:85]
	v_mfma_f32_16x16x32_bf16 v[66:69], v[174:177], v[224:227], v[66:69]
	v_mfma_f32_16x16x32_bf16 v[70:73], v[166:169], v[224:227], v[70:73]
	v_mfma_f32_16x16x32_bf16 v[118:121], v[170:173], v[186:189], v[118:121]
	v_mfma_f32_16x16x32_bf16 v[114:117], v[178:181], v[186:189], v[114:117]
	v_mfma_f32_16x16x32_bf16 v[98:101], v[178:181], v[194:197], v[98:101]
	v_mfma_f32_16x16x32_bf16 v[102:105], v[170:173], v[194:197], v[102:105]
	v_mfma_f32_16x16x32_bf16 v[86:89], v[170:173], v[202:205], v[86:89]
	v_mfma_f32_16x16x32_bf16 v[82:85], v[178:181], v[202:205], v[82:85]
	v_mfma_f32_16x16x32_bf16 v[66:69], v[178:181], v[228:231], v[66:69]
	v_mfma_f32_16x16x32_bf16 v[70:73], v[170:173], v[228:231], v[70:73]
	s_barrier
; #define PG8_STAGE(bufoff, gbase, voff) do { _Pragma("unroll") for (int _i = 0; _i < 2; ++_i) \
;         __builtin_amdgcn_global_load_lds((const unsigned*)((const char*)(gbase) + (voff)[_i]), (PG8_LAS unsigned*)(lds + (bufoff) + ldsw + _i * 8192), 16, 0, 0); } while (0)
; #define PG8_LDA(dst, b, h) do { _Pragma("unroll") for (int m = 0; m < 4; ++m) _Pragma("unroll") for (int k = 0; k < 2; ++k) dst[m][k] = *(const PG8_LAS bf16x8*)(lds + PG8_SA(b, h) + aoff + m * 2048 + k * 1024); } while (0)
; #define PG8_LDB(dst, b, h) do { _Pragma("unroll") for (int n = 0; n < 2; ++n) _Pragma("unroll") for (int k = 0; k < 2; ++k) dst[n][k] = *(const PG8_LAS bf16x8*)(lds + PG8_SB(b, h) + boff + n * 2048 + k * 1024); } while (0)
; #define PG8_MMA(ai, bj, At, Bt) do { __builtin_amdgcn_s_setprio(1); _Pragma("unroll") for (int m = 0; m < 4; ++m) _Pragma("unroll") for (int n = 0; n < 2; ++n) _Pragma("unroll") for (int k = 0; k < 2; ++k) \
;         acc[ai][bj][m][n] = __builtin_amdgcn_mfma_f32_16x16x32_bf16(Bt[n][k], At[m][k], acc[ai][bj][m][n], 0, 0, 0); __builtin_amdgcn_s_setprio(0); } while (0)
; #define PG8_WAIT_V(n) asm volatile("s_waitcnt vmcnt(" #n ")" ::: "memory")
; #define PG8_BAR __builtin_amdgcn_s_barrier()
; template <class Epi, class Sched, bool ALIGN_EPI = false, bool SP2 = false>
; __device__ __forceinline__ void gemm_phase(PG8_LAS unsigned char* lds, const Gemm g, const Sched& S, const Epi& E) {
;     ...
;         for (int t = 0; t < nt; t += 2) {
;             const bool last = (t == nt - 2);
;             const char* a1 = cA + (size_t)(t + 1) * kstep;
;             const char* a2 = last ? nA : cA + (size_t)(t + 2) * kstep; const char* b2 = last ? nB : cB + (size_t)(t + 2) * kstep;
;             const char* a3 = a2 + kstep; const char* b3 = b2 + kstep;
;             if (last && has_next) S.a_ready(nxt);
;             if constexpr (SP2) {
;             PG8_LDB(B0, 0, 0); PG8_LDB(B1, 0, 1); PG8_SCHED; PG8_LDA(At, 0, 0); PG8_STAGE(PG8_SA(1, 1), a1 + hstep, voffA);
;             PG8_WAIT_V(8); PG8_WAIT_L(0); PG8_BAR; PG8_MMA(0, 0, At, B0); PG8_MMA(0, 1, At, B1); PG8_BAR; PG8_SCHED;
;     ...
;             PG8_LDA(At, 1, 1); PG8_STAGE(PG8_SB(1, 0), b3, voffB); PG8_STAGE(PG8_SB(1, 1), b3 + hstep, voffB); PG8_STAGE(PG8_SA(1, 0), a3, voffA);
;             PG8_WAIT_V(8); PG8_WAIT_L(0); PG8_BAR; PG8_MMA(1, 0, At, B0); PG8_MMA(1, 1, At, B1); PG8_BAR; PG8_SCHED;
	s_setprio 0
	s_add_i32 s22, s48, s26
	v_lshl_add_u64 v[138:139], v[138:139], 0, s[86:87]
	s_mov_b32 m0, s22
	ds_read_b128 v[182:185], v164 offset:49152
	ds_read_b128 v[186:189], v164 offset:50176
	ds_read_b128 v[190:193], v164 offset:51200
	ds_read_b128 v[194:197], v164 offset:52224
	ds_read_b128 v[198:201], v164 offset:53248
	ds_read_b128 v[202:205], v164 offset:54272
	ds_read_b128 v[224:227], v164 offset:55296
	ds_read_b128 v[228:231], v164 offset:56320
	global_load_lds_dwordx4 v[138:139], off
	s_add_i32 m0, s22, 0x2000
	s_add_u32 s20, s20, 0x40080
	v_lshl_add_u64 v[138:139], v[140:141], 0, s[86:87]
	s_addc_u32 s21, s21, 0
	s_add_i32 s22, s49, s26
	global_load_lds_dwordx4 v[138:139], off
	v_lshl_add_u64 v[138:139], s[20:21], 0, v[0:1]
	s_mov_b32 m0, s22
	s_nop 0
	global_load_lds_dwordx4 v[138:139], off
	v_lshl_add_u64 v[138:139], s[20:21], 0, v[134:135]
	s_add_i32 m0, s22, 0x2000
	s_nop 0
	global_load_lds_dwordx4 v[138:139], off
	v_lshl_add_u64 v[138:139], v[232:233], 0, s[86:87]
	s_mov_b32 m0, s41
	s_nop 0
	global_load_lds_dwordx4 v[138:139], off
	v_lshl_add_u64 v[138:139], v[234:235], 0, s[86:87]
	s_mov_b32 m0, s42
	s_nop 0
	global_load_lds_dwordx4 v[138:139], off
	s_waitcnt vmcnt(8)
	s_waitcnt lgkmcnt(0)
	s_setprio 1
	s_barrier
	v_mfma_f32_16x16x32_bf16 v[62:65], v[144:147], v[182:185], v[62:65]
	v_mfma_f32_16x16x32_bf16 v[58:61], v[152:155], v[182:185], v[58:61]
	v_mfma_f32_16x16x32_bf16 v[42:45], v[152:155], v[190:193], v[42:45]
	v_mfma_f32_16x16x32_bf16 v[46:49], v[144:147], v[190:193], v[46:49]
	v_mfma_f32_16x16x32_bf16 v[30:33], v[144:147], v[198:201], v[30:33]
	v_mfma_f32_16x16x32_bf16 v[26:29], v[152:155], v[198:201], v[26:29]
	v_mfma_f32_16x16x32_bf16 v[10:13], v[152:155], v[224:227], v[10:13]
	v_mfma_f32_16x16x32_bf16 v[14:17], v[144:147], v[224:227], v[14:17]
	v_mfma_f32_16x16x32_bf16 v[62:65], v[148:151], v[186:189], v[62:65]
	v_mfma_f32_16x16x32_bf16 v[58:61], v[156:159], v[186:189], v[58:61]
	v_mfma_f32_16x16x32_bf16 v[42:45], v[156:159], v[194:197], v[42:45]
	v_mfma_f32_16x16x32_bf16 v[46:49], v[148:151], v[194:197], v[46:49]
	v_mfma_f32_16x16x32_bf16 v[30:33], v[148:151], v[202:205], v[30:33]
	v_mfma_f32_16x16x32_bf16 v[26:29], v[156:159], v[202:205], v[26:29]
	v_mfma_f32_16x16x32_bf16 v[10:13], v[156:159], v[228:231], v[10:13]
	v_mfma_f32_16x16x32_bf16 v[14:17], v[148:151], v[228:231], v[14:17]
	v_mfma_f32_16x16x32_bf16 v[54:57], v[166:169], v[182:185], v[54:57]
	v_mfma_f32_16x16x32_bf16 v[50:53], v[174:177], v[182:185], v[50:53]
	v_mfma_f32_16x16x32_bf16 v[34:37], v[174:177], v[190:193], v[34:37]
	v_mfma_f32_16x16x32_bf16 v[38:41], v[166:169], v[190:193], v[38:41]
	v_mfma_f32_16x16x32_bf16 v[22:25], v[166:169], v[198:201], v[22:25]
	v_mfma_f32_16x16x32_bf16 v[18:21], v[174:177], v[198:201], v[18:21]
	v_mfma_f32_16x16x32_bf16 v[2:5], v[174:177], v[224:227], v[2:5]
	v_mfma_f32_16x16x32_bf16 v[6:9], v[166:169], v[224:227], v[6:9]
	v_mfma_f32_16x16x32_bf16 v[54:57], v[170:173], v[186:189], v[54:57]
	v_mfma_f32_16x16x32_bf16 v[50:53], v[178:181], v[186:189], v[50:53]
	v_mfma_f32_16x16x32_bf16 v[34:37], v[178:181], v[194:197], v[34:37]
	v_mfma_f32_16x16x32_bf16 v[38:41], v[170:173], v[194:197], v[38:41]
	v_mfma_f32_16x16x32_bf16 v[22:25], v[170:173], v[202:205], v[22:25]
	v_mfma_f32_16x16x32_bf16 v[18:21], v[178:181], v[202:205], v[18:21]
	v_mfma_f32_16x16x32_bf16 v[2:5], v[178:181], v[228:231], v[2:5]
	v_mfma_f32_16x16x32_bf16 v[6:9], v[170:173], v[228:231], v[6:9]
	s_barrier
	s_setprio 0
	s_add_i32 s47, s47, 2
	s_add_u32 s8, s8, 0x100
	s_addc_u32 s9, s9, 0
	s_add_u32 s45, s45, 0x100
	s_addc_u32 s46, s46, 0
	s_cmp_gt_u32 s47, 13
	s_cbranch_scc1 .Lpeel_exit_pj
.LBB0_492:
	s_add_u32 s20, s8, 0xfffc0080
	s_addc_u32 s21, s9, -1
	s_add_i32 s48, 0, 0x10000
	s_cmp_eq_u32 s47, 12
	s_cselect_b32 s23, s5, s21
	s_cselect_b32 s22, s7, s20
	v_add_u32_e32 v138, s48, v161
	s_cselect_b32 s21, s13, s46
	s_cselect_b32 s20, s15, s45
	s_add_i32 s50, 0, 0x14000
	ds_read_b128 v[144:147], v138
	ds_read_b128 v[148:151], v138 offset:1024
	ds_read_b128 v[152:155], v138 offset:2048
	ds_read_b128 v[156:159], v138 offset:3072
	v_add_u32_e32 v138, s50, v161
	ds_read_b128 v[166:169], v138
	ds_read_b128 v[170:173], v138 offset:1024
	ds_read_b128 v[174:177], v138 offset:2048
	ds_read_b128 v[178:181], v138 offset:3072
	v_lshl_add_u64 v[138:139], s[8:9], 0, v[136:137]
	s_add_i32 m0, s30, 0xc000
	ds_read_b128 v[182:185], v164
	ds_read_b128 v[186:189], v164 offset:1024
	ds_read_b128 v[190:193], v164 offset:2048
	ds_read_b128 v[194:197], v164 offset:3072
	ds_read_b128 v[198:201], v164 offset:4096
	ds_read_b128 v[202:205], v164 offset:5120
	ds_read_b128 v[224:227], v164 offset:6144
	ds_read_b128 v[228:231], v164 offset:7168
	global_load_lds_dwordx4 v[138:139], off
	v_lshl_add_u64 v[138:139], s[8:9], 0, v[142:143]
	s_add_i32 m0, s30, 0xe000
	s_nop 0
	global_load_lds_dwordx4 v[138:139], off
	s_waitcnt vmcnt(8)
	s_waitcnt lgkmcnt(0)
	s_setprio 1
	s_barrier
; #define PG8_STAGE(bufoff, gbase, voff) do { _Pragma("unroll") for (int _i = 0; _i < 2; ++_i) \
;         __builtin_amdgcn_global_load_lds((const unsigned*)((const char*)(gbase) + (voff)[_i]), (PG8_LAS unsigned*)(lds + (bufoff) + ldsw + _i * 8192), 16, 0, 0); } while (0)
; #define PG8_LDA(dst, b, h) do { _Pragma("unroll") for (int m = 0; m < 4; ++m) _Pragma("unroll") for (int k = 0; k < 2; ++k) dst[m][k] = *(const PG8_LAS bf16x8*)(lds + PG8_SA(b, h) + aoff + m * 2048 + k * 1024); } while (0)
; #define PG8_LDB(dst, b, h) do { _Pragma("unroll") for (int n = 0; n < 2; ++n) _Pragma("unroll") for (int k = 0; k < 2; ++k) dst[n][k] = *(const PG8_LAS bf16x8*)(lds + PG8_SB(b, h) + boff + n * 2048 + k * 1024); } while (0)
; #define PG8_MMA(ai, bj, At, Bt) do { __builtin_amdgcn_s_setprio(1); _Pragma("unroll") for (int m = 0; m < 4; ++m) _Pragma("unroll") for (int n = 0; n < 2; ++n) _Pragma("unroll") for (int k = 0; k < 2; ++k) \
;         acc[ai][bj][m][n] = __builtin_amdgcn_mfma_f32_16x16x32_bf16(Bt[n][k], At[m][k], acc[ai][bj][m][n], 0, 0, 0); __builtin_amdgcn_s_setprio(0); } while (0)
; #define PG8_WAIT_V(n) asm volatile("s_waitcnt vmcnt(" #n ")" ::: "memory")
; #define PG8_WAIT_L(n) asm volatile("s_waitcnt lgkmcnt(" #n ")" ::: "memory")
; #define PG8_BAR __builtin_amdgcn_s_barrier()
; #define PG8_SCHED __builtin_amdgcn_sched_barrier(0)
; template <class Epi, class Sched, bool ALIGN_EPI = false, bool SP2 = false>
; __device__ __forceinline__ void gemm_phase(PG8_LAS unsigned char* lds, const Gemm g, const Sched& S, const Epi& E) {
;     ...
;             PG8_WAIT_V(8); PG8_WAIT_L(0); PG8_BAR; PG8_MMA(0, 0, At, B0); PG8_MMA(0, 1, At, B1); PG8_BAR; PG8_SCHED;
;             PG8_LDA(At, 0, 1); PG8_STAGE(PG8_SB(0, 0), b2, voffB); PG8_STAGE(PG8_SB(0, 1), b2 + hstep, voffB); PG8_STAGE(PG8_SA(0, 0), a2, voffA);
;             PG8_WAIT_V(8); PG8_WAIT_L(0); PG8_BAR; PG8_MMA(1, 0, At, B0); PG8_MMA(1, 1, At, B1); PG8_BAR; PG8_SCHED;
;             PG8_LDB(B0, 1, 0); PG8_LDB(B1, 1, 1); PG8_SCHED; PG8_LDA(At, 1, 0); PG8_STAGE(PG8_SA(0, 1), a2 + hstep, voffA);
;             PG8_WAIT_V(8); PG8_WAIT_L(0); PG8_BAR; PG8_MMA(0, 0, At, B0); PG8_MMA(0, 1, At, B1); PG8_BAR; PG8_SCHED;
	v_mfma_f32_16x16x32_bf16 v[126:129], v[144:147], v[182:185], v[126:129]
	v_mfma_f32_16x16x32_bf16 v[122:125], v[152:155], v[182:185], v[122:125]
	v_mfma_f32_16x16x32_bf16 v[106:109], v[152:155], v[190:193], v[106:109]
	v_mfma_f32_16x16x32_bf16 v[110:113], v[144:147], v[190:193], v[110:113]
	v_mfma_f32_16x16x32_bf16 v[94:97], v[144:147], v[198:201], v[94:97]
	v_mfma_f32_16x16x32_bf16 v[90:93], v[152:155], v[198:201], v[90:93]
	v_mfma_f32_16x16x32_bf16 v[74:77], v[152:155], v[224:227], v[74:77]
	v_mfma_f32_16x16x32_bf16 v[78:81], v[144:147], v[224:227], v[78:81]
	v_mfma_f32_16x16x32_bf16 v[126:129], v[148:151], v[186:189], v[126:129]
	v_mfma_f32_16x16x32_bf16 v[122:125], v[156:159], v[186:189], v[122:125]
	v_mfma_f32_16x16x32_bf16 v[106:109], v[156:159], v[194:197], v[106:109]
	v_mfma_f32_16x16x32_bf16 v[110:113], v[148:151], v[194:197], v[110:113]
	v_mfma_f32_16x16x32_bf16 v[94:97], v[148:151], v[202:205], v[94:97]
	v_mfma_f32_16x16x32_bf16 v[90:93], v[156:159], v[202:205], v[90:93]
	v_mfma_f32_16x16x32_bf16 v[74:77], v[156:159], v[228:231], v[74:77]
	v_mfma_f32_16x16x32_bf16 v[78:81], v[148:151], v[228:231], v[78:81]
	v_mfma_f32_16x16x32_bf16 v[118:121], v[166:169], v[182:185], v[118:121]
	v_mfma_f32_16x16x32_bf16 v[114:117], v[174:177], v[182:185], v[114:117]
	v_mfma_f32_16x16x32_bf16 v[98:101], v[174:177], v[190:193], v[98:101]
	v_mfma_f32_16x16x32_bf16 v[102:105], v[166:169], v[190:193], v[102:105]
	v_mfma_f32_16x16x32_bf16 v[86:89], v[166:169], v[198:201], v[86:89]
	v_mfma_f32_16x16x32_bf16 v[82:85], v[174:177], v[198:201], v[82:85]
	v_mfma_f32_16x16x32_bf16 v[66:69], v[174:177], v[224:227], v[66:69]
	v_mfma_f32_16x16x32_bf16 v[70:73], v[166:169], v[224:227], v[70:73]
	v_mfma_f32_16x16x32_bf16 v[118:121], v[170:173], v[186:189], v[118:121]
	v_mfma_f32_16x16x32_bf16 v[114:117], v[178:181], v[186:189], v[114:117]
	v_mfma_f32_16x16x32_bf16 v[98:101], v[178:181], v[194:197], v[98:101]
	v_mfma_f32_16x16x32_bf16 v[102:105], v[170:173], v[194:197], v[102:105]
	v_mfma_f32_16x16x32_bf16 v[86:89], v[170:173], v[202:205], v[86:89]
	v_mfma_f32_16x16x32_bf16 v[82:85], v[178:181], v[202:205], v[82:85]
	v_mfma_f32_16x16x32_bf16 v[66:69], v[178:181], v[228:231], v[66:69]
	v_mfma_f32_16x16x32_bf16 v[70:73], v[170:173], v[228:231], v[70:73]
	s_barrier
	s_setprio 0
	s_add_i32 s48, s48, s26
	v_lshl_add_u64 v[138:139], s[20:21], 0, v[0:1]
	s_mov_b32 m0, s48
	ds_read_b128 v[182:185], v164 offset:16384
	ds_read_b128 v[186:189], v164 offset:17408
	ds_read_b128 v[190:193], v164 offset:18432
	ds_read_b128 v[194:197], v164 offset:19456
	ds_read_b128 v[198:201], v164 offset:20480
	ds_read_b128 v[202:205], v164 offset:21504
	ds_read_b128 v[224:227], v164 offset:22528
	ds_read_b128 v[228:231], v164 offset:23552
	global_load_lds_dwordx4 v[138:139], off
	s_add_i32 m0, s48, 0x2000
	s_add_u32 s48, s20, 0x40000
	v_lshl_add_u64 v[140:141], s[20:21], 0, v[134:135]
	s_addc_u32 s49, s21, 0
	s_add_i32 s50, s50, s26
	global_load_lds_dwordx4 v[140:141], off
	v_lshl_add_u64 v[232:233], s[48:49], 0, v[0:1]
	s_mov_b32 m0, s50
	v_lshl_add_u64 v[234:235], s[22:23], 0, v[132:133]
	global_load_lds_dwordx4 v[232:233], off
	v_lshl_add_u64 v[232:233], s[48:49], 0, v[134:135]
	s_add_i32 m0, s50, 0x2000
	s_nop 0
	global_load_lds_dwordx4 v[232:233], off
	v_lshl_add_u64 v[232:233], s[22:23], 0, v[130:131]
	s_mov_b32 m0, s30
	s_nop 0
	global_load_lds_dwordx4 v[232:233], off
	s_mov_b32 m0, s31
	s_nop 0
	global_load_lds_dwordx4 v[234:235], off
	s_waitcnt vmcnt(8)
	s_waitcnt lgkmcnt(0)
	s_setprio 1
	s_barrier
	v_mfma_f32_16x16x32_bf16 v[62:65], v[144:147], v[182:185], v[62:65]
	v_mfma_f32_16x16x32_bf16 v[58:61], v[152:155], v[182:185], v[58:61]
	v_mfma_f32_16x16x32_bf16 v[42:45], v[152:155], v[190:193], v[42:45]
	v_mfma_f32_16x16x32_bf16 v[46:49], v[144:147], v[190:193], v[46:49]
	v_mfma_f32_16x16x32_bf16 v[30:33], v[144:147], v[198:201], v[30:33]
	v_mfma_f32_16x16x32_bf16 v[26:29], v[152:155], v[198:201], v[26:29]
	v_mfma_f32_16x16x32_bf16 v[10:13], v[152:155], v[224:227], v[10:13]
	v_mfma_f32_16x16x32_bf16 v[14:17], v[144:147], v[224:227], v[14:17]
	v_mfma_f32_16x16x32_bf16 v[62:65], v[148:151], v[186:189], v[62:65]
	v_mfma_f32_16x16x32_bf16 v[58:61], v[156:159], v[186:189], v[58:61]
	v_mfma_f32_16x16x32_bf16 v[42:45], v[156:159], v[194:197], v[42:45]
	v_mfma_f32_16x16x32_bf16 v[46:49], v[148:151], v[194:197], v[46:49]
	v_mfma_f32_16x16x32_bf16 v[30:33], v[148:151], v[202:205], v[30:33]
	v_mfma_f32_16x16x32_bf16 v[26:29], v[156:159], v[202:205], v[26:29]
	v_mfma_f32_16x16x32_bf16 v[10:13], v[156:159], v[228:231], v[10:13]
	v_mfma_f32_16x16x32_bf16 v[14:17], v[148:151], v[228:231], v[14:17]
	v_mfma_f32_16x16x32_bf16 v[54:57], v[166:169], v[182:185], v[54:57]
	v_mfma_f32_16x16x32_bf16 v[50:53], v[174:177], v[182:185], v[50:53]
	v_mfma_f32_16x16x32_bf16 v[34:37], v[174:177], v[190:193], v[34:37]
	v_mfma_f32_16x16x32_bf16 v[38:41], v[166:169], v[190:193], v[38:41]
	v_mfma_f32_16x16x32_bf16 v[22:25], v[166:169], v[198:201], v[22:25]
	v_mfma_f32_16x16x32_bf16 v[18:21], v[174:177], v[198:201], v[18:21]
	v_mfma_f32_16x16x32_bf16 v[2:5], v[174:177], v[224:227], v[2:5]
	v_mfma_f32_16x16x32_bf16 v[6:9], v[166:169], v[224:227], v[6:9]
	v_mfma_f32_16x16x32_bf16 v[54:57], v[170:173], v[186:189], v[54:57]
	v_mfma_f32_16x16x32_bf16 v[50:53], v[178:181], v[186:189], v[50:53]
	v_mfma_f32_16x16x32_bf16 v[34:37], v[178:181], v[194:197], v[34:37]
	v_mfma_f32_16x16x32_bf16 v[38:41], v[170:173], v[194:197], v[38:41]
	v_mfma_f32_16x16x32_bf16 v[22:25], v[170:173], v[202:205], v[22:25]
	v_mfma_f32_16x16x32_bf16 v[18:21], v[178:181], v[202:205], v[18:21]
	v_mfma_f32_16x16x32_bf16 v[2:5], v[178:181], v[228:231], v[2:5]
	v_mfma_f32_16x16x32_bf16 v[6:9], v[170:173], v[228:231], v[6:9]
	s_barrier
; #define PG8_STAGE(bufoff, gbase, voff) do { _Pragma("unroll") for (int _i = 0; _i < 2; ++_i) \
;         __builtin_amdgcn_global_load_lds((const unsigned*)((const char*)(gbase) + (voff)[_i]), (PG8_LAS unsigned*)(lds + (bufoff) + ldsw + _i * 8192), 16, 0, 0); } while (0)
; #define PG8_LDA(dst, b, h) do { _Pragma("unroll") for (int m = 0; m < 4; ++m) _Pragma("unroll") for (int k = 0; k < 2; ++k) dst[m][k] = *(const PG8_LAS bf16x8*)(lds + PG8_SA(b, h) + aoff + m * 2048 + k * 1024); } while (0)
; #define PG8_LDB(dst, b, h) do { _Pragma("unroll") for (int n = 0; n < 2; ++n) _Pragma("unroll") for (int k = 0; k < 2; ++k) dst[n][k] = *(const PG8_LAS bf16x8*)(lds + PG8_SB(b, h) + boff + n * 2048 + k * 1024); } while (0)
; #define PG8_MMA(ai, bj, At, Bt) do { __builtin_amdgcn_s_setprio(1); _Pragma("unroll") for (int m = 0; m < 4; ++m) _Pragma("unroll") for (int n = 0; n < 2; ++n) _Pragma("unroll") for (int k = 0; k < 2; ++k) \
;         acc[ai][bj][m][n] = __builtin_amdgcn_mfma_f32_16x16x32_bf16(Bt[n][k], At[m][k], acc[ai][bj][m][n], 0, 0, 0); __builtin_amdgcn_s_setprio(0); } while (0)
; #define PG8_WAIT_V(n) asm volatile("s_waitcnt vmcnt(" #n ")" ::: "memory")
; #define PG8_WAIT_L(n) asm volatile("s_waitcnt lgkmcnt(" #n ")" ::: "memory")
; #define PG8_BAR __builtin_amdgcn_s_barrier()
; #define PG8_SCHED __builtin_amdgcn_sched_barrier(0)
; template <class Epi, class Sched, bool ALIGN_EPI = false, bool SP2 = false>
; __device__ __forceinline__ void gemm_phase(PG8_LAS unsigned char* lds, const Gemm g, const Sched& S, const Epi& E) {
;     ...
;             PG8_LDB(B0, 1, 0); PG8_LDB(B1, 1, 1); PG8_SCHED; PG8_LDA(At, 1, 0); PG8_STAGE(PG8_SA(0, 1), a2 + hstep, voffA);
;             PG8_WAIT_V(8); PG8_WAIT_L(0); PG8_BAR; PG8_MMA(0, 0, At, B0); PG8_MMA(0, 1, At, B1); PG8_BAR; PG8_SCHED;
	s_setprio 0
	s_add_i32 s48, 0, 0x18000
	s_add_i32 s49, 0, 0x1c000
	v_add_u32_e32 v156, s48, v161
	v_add_u32_e32 v165, s49, v161
	ds_read_b128 v[144:147], v156
	ds_read_b128 v[148:151], v156 offset:1024
	ds_read_b128 v[152:155], v156 offset:2048
	ds_read_b128 v[156:159], v156 offset:3072
	ds_read_b128 v[166:169], v165
	ds_read_b128 v[170:173], v165 offset:1024
	ds_read_b128 v[174:177], v165 offset:2048
	ds_read_b128 v[178:181], v165 offset:3072
	s_add_u32 s22, s22, 0x40000
	s_addc_u32 s23, s23, 0
	s_mov_b32 m0, s38
	v_lshl_add_u64 v[236:237], s[22:23], 0, v[130:131]
	ds_read_b128 v[182:185], v164 offset:32768
	ds_read_b128 v[186:189], v164 offset:33792
	ds_read_b128 v[190:193], v164 offset:34816
	ds_read_b128 v[194:197], v164 offset:35840
	ds_read_b128 v[198:201], v164 offset:36864
	ds_read_b128 v[202:205], v164 offset:37888
	ds_read_b128 v[224:227], v164 offset:38912
	ds_read_b128 v[228:231], v164 offset:39936
	global_load_lds_dwordx4 v[236:237], off
	v_lshl_add_u64 v[236:237], s[22:23], 0, v[132:133]
	s_mov_b32 m0, s39
	s_nop 0
	global_load_lds_dwordx4 v[236:237], off
	s_waitcnt vmcnt(8)
	s_waitcnt lgkmcnt(0)
	s_setprio 1
	s_barrier
	v_mfma_f32_16x16x32_bf16 v[126:129], v[144:147], v[182:185], v[126:129]
	v_mfma_f32_16x16x32_bf16 v[122:125], v[152:155], v[182:185], v[122:125]
	v_mfma_f32_16x16x32_bf16 v[106:109], v[152:155], v[190:193], v[106:109]
	v_mfma_f32_16x16x32_bf16 v[110:113], v[144:147], v[190:193], v[110:113]
	v_mfma_f32_16x16x32_bf16 v[94:97], v[144:147], v[198:201], v[94:97]
	v_mfma_f32_16x16x32_bf16 v[90:93], v[152:155], v[198:201], v[90:93]
	v_mfma_f32_16x16x32_bf16 v[74:77], v[152:155], v[224:227], v[74:77]
	v_mfma_f32_16x16x32_bf16 v[78:81], v[144:147], v[224:227], v[78:81]
	v_mfma_f32_16x16x32_bf16 v[126:129], v[148:151], v[186:189], v[126:129]
	v_mfma_f32_16x16x32_bf16 v[122:125], v[156:159], v[186:189], v[122:125]
	v_mfma_f32_16x16x32_bf16 v[106:109], v[156:159], v[194:197], v[106:109]
	v_mfma_f32_16x16x32_bf16 v[110:113], v[148:151], v[194:197], v[110:113]
	v_mfma_f32_16x16x32_bf16 v[94:97], v[148:151], v[202:205], v[94:97]
	v_mfma_f32_16x16x32_bf16 v[90:93], v[156:159], v[202:205], v[90:93]
	v_mfma_f32_16x16x32_bf16 v[74:77], v[156:159], v[228:231], v[74:77]
	v_mfma_f32_16x16x32_bf16 v[78:81], v[148:151], v[228:231], v[78:81]
	v_mfma_f32_16x16x32_bf16 v[118:121], v[166:169], v[182:185], v[118:121]
	v_mfma_f32_16x16x32_bf16 v[114:117], v[174:177], v[182:185], v[114:117]
	v_mfma_f32_16x16x32_bf16 v[98:101], v[174:177], v[190:193], v[98:101]
	v_mfma_f32_16x16x32_bf16 v[102:105], v[166:169], v[190:193], v[102:105]
	v_mfma_f32_16x16x32_bf16 v[86:89], v[166:169], v[198:201], v[86:89]
	v_mfma_f32_16x16x32_bf16 v[82:85], v[174:177], v[198:201], v[82:85]
	v_mfma_f32_16x16x32_bf16 v[66:69], v[174:177], v[224:227], v[66:69]
	v_mfma_f32_16x16x32_bf16 v[70:73], v[166:169], v[224:227], v[70:73]
	v_mfma_f32_16x16x32_bf16 v[118:121], v[170:173], v[186:189], v[118:121]
	v_mfma_f32_16x16x32_bf16 v[114:117], v[178:181], v[186:189], v[114:117]
	v_mfma_f32_16x16x32_bf16 v[98:101], v[178:181], v[194:197], v[98:101]
	v_mfma_f32_16x16x32_bf16 v[102:105], v[170:173], v[194:197], v[102:105]
	v_mfma_f32_16x16x32_bf16 v[86:89], v[170:173], v[202:205], v[86:89]
	v_mfma_f32_16x16x32_bf16 v[82:85], v[178:181], v[202:205], v[82:85]
	v_mfma_f32_16x16x32_bf16 v[66:69], v[178:181], v[228:231], v[66:69]
	v_mfma_f32_16x16x32_bf16 v[70:73], v[170:173], v[228:231], v[70:73]
	s_barrier
; #define PG8_STAGE(bufoff, gbase, voff) do { _Pragma("unroll") for (int _i = 0; _i < 2; ++_i) \
;         __builtin_amdgcn_global_load_lds((const unsigned*)((const char*)(gbase) + (voff)[_i]), (PG8_LAS unsigned*)(lds + (bufoff) + ldsw + _i * 8192), 16, 0, 0); } while (0)
; #define PG8_LDA(dst, b, h) do { _Pragma("unroll") for (int m = 0; m < 4; ++m) _Pragma("unroll") for (int k = 0; k < 2; ++k) dst[m][k] = *(const PG8_LAS bf16x8*)(lds + PG8_SA(b, h) + aoff + m * 2048 + k * 1024); } while (0)
; #define PG8_MMA(ai, bj, At, Bt) do { __builtin_amdgcn_s_setprio(1); _Pragma("unroll") for (int m = 0; m < 4; ++m) _Pragma("unroll") for (int n = 0; n < 2; ++n) _Pragma("unroll") for (int k = 0; k < 2; ++k) \
;         acc[ai][bj][m][n] = __builtin_amdgcn_mfma_f32_16x16x32_bf16(Bt[n][k], At[m][k], acc[ai][bj][m][n], 0, 0, 0); __builtin_amdgcn_s_setprio(0); } while (0)
; #define PG8_WAIT_V(n) asm volatile("s_waitcnt vmcnt(" #n ")" ::: "memory")
; #define PG8_WAIT_L(n) asm volatile("s_waitcnt lgkmcnt(" #n ")" ::: "memory")
; #define PG8_BAR __builtin_amdgcn_s_barrier()
; #define PG8_SCHED __builtin_amdgcn_sched_barrier(0)
; template <class Epi, class Sched, bool ALIGN_EPI = false, bool SP2 = false>
; __device__ __forceinline__ void gemm_phase(PG8_LAS unsigned char* lds, const Gemm g, const Sched& S, const Epi& E) {
;     ...
;         for (int t = 0; t < nt; t += 2) {
;             const bool last = (t == nt - 2);
;             const char* a1 = cA + (size_t)(t + 1) * kstep;
;             const char* a2 = last ? nA : cA + (size_t)(t + 2) * kstep; const char* b2 = last ? nB : cB + (size_t)(t + 2) * kstep;
;             const char* a3 = a2 + kstep; const char* b3 = b2 + kstep;
;     ...
;             PG8_LDA(At, 1, 1); PG8_STAGE(PG8_SB(1, 0), b3, voffB); PG8_STAGE(PG8_SB(1, 1), b3 + hstep, voffB); PG8_STAGE(PG8_SA(1, 0), a3, voffA);
;             PG8_WAIT_V(8); PG8_WAIT_L(0); PG8_BAR; PG8_MMA(1, 0, At, B0); PG8_MMA(1, 1, At, B1); PG8_BAR; PG8_SCHED;
	s_setprio 0
	s_add_i32 s22, s48, s26
	v_lshl_add_u64 v[138:139], v[138:139], 0, s[86:87]
	s_mov_b32 m0, s22
	ds_read_b128 v[182:185], v164 offset:49152
	ds_read_b128 v[186:189], v164 offset:50176
	ds_read_b128 v[190:193], v164 offset:51200
	ds_read_b128 v[194:197], v164 offset:52224
	ds_read_b128 v[198:201], v164 offset:53248
	ds_read_b128 v[202:205], v164 offset:54272
	ds_read_b128 v[224:227], v164 offset:55296
	ds_read_b128 v[228:231], v164 offset:56320
	global_load_lds_dwordx4 v[138:139], off
	s_add_i32 m0, s22, 0x2000
	s_add_u32 s20, s20, 0x40080
	v_lshl_add_u64 v[138:139], v[140:141], 0, s[86:87]
	s_addc_u32 s21, s21, 0
	s_add_i32 s22, s49, s26
	global_load_lds_dwordx4 v[138:139], off
	v_lshl_add_u64 v[138:139], s[20:21], 0, v[0:1]
	s_mov_b32 m0, s22
	s_nop 0
	global_load_lds_dwordx4 v[138:139], off
	v_lshl_add_u64 v[138:139], s[20:21], 0, v[134:135]
	s_add_i32 m0, s22, 0x2000
	s_nop 0
	global_load_lds_dwordx4 v[138:139], off
	v_lshl_add_u64 v[138:139], v[232:233], 0, s[86:87]
	s_mov_b32 m0, s41
	s_nop 0
	global_load_lds_dwordx4 v[138:139], off
	v_lshl_add_u64 v[138:139], v[234:235], 0, s[86:87]
	s_mov_b32 m0, s42
	s_nop 0
	global_load_lds_dwordx4 v[138:139], off
	s_waitcnt vmcnt(8)
	s_waitcnt lgkmcnt(0)
	s_setprio 1
	s_barrier
	v_mfma_f32_16x16x32_bf16 v[62:65], v[144:147], v[182:185], v[62:65]
	v_mfma_f32_16x16x32_bf16 v[58:61], v[152:155], v[182:185], v[58:61]
	v_mfma_f32_16x16x32_bf16 v[42:45], v[152:155], v[190:193], v[42:45]
	v_mfma_f32_16x16x32_bf16 v[46:49], v[144:147], v[190:193], v[46:49]
	v_mfma_f32_16x16x32_bf16 v[30:33], v[144:147], v[198:201], v[30:33]
	v_mfma_f32_16x16x32_bf16 v[26:29], v[152:155], v[198:201], v[26:29]
	v_mfma_f32_16x16x32_bf16 v[10:13], v[152:155], v[224:227], v[10:13]
	v_mfma_f32_16x16x32_bf16 v[14:17], v[144:147], v[224:227], v[14:17]
	v_mfma_f32_16x16x32_bf16 v[62:65], v[148:151], v[186:189], v[62:65]
	v_mfma_f32_16x16x32_bf16 v[58:61], v[156:159], v[186:189], v[58:61]
	v_mfma_f32_16x16x32_bf16 v[42:45], v[156:159], v[194:197], v[42:45]
	v_mfma_f32_16x16x32_bf16 v[46:49], v[148:151], v[194:197], v[46:49]
	v_mfma_f32_16x16x32_bf16 v[30:33], v[148:151], v[202:205], v[30:33]
	v_mfma_f32_16x16x32_bf16 v[26:29], v[156:159], v[202:205], v[26:29]
	v_mfma_f32_16x16x32_bf16 v[10:13], v[156:159], v[228:231], v[10:13]
	v_mfma_f32_16x16x32_bf16 v[14:17], v[148:151], v[228:231], v[14:17]
	v_mfma_f32_16x16x32_bf16 v[54:57], v[166:169], v[182:185], v[54:57]
	v_mfma_f32_16x16x32_bf16 v[50:53], v[174:177], v[182:185], v[50:53]
	v_mfma_f32_16x16x32_bf16 v[34:37], v[174:177], v[190:193], v[34:37]
	v_mfma_f32_16x16x32_bf16 v[38:41], v[166:169], v[190:193], v[38:41]
	v_mfma_f32_16x16x32_bf16 v[22:25], v[166:169], v[198:201], v[22:25]
	v_mfma_f32_16x16x32_bf16 v[18:21], v[174:177], v[198:201], v[18:21]
	v_mfma_f32_16x16x32_bf16 v[2:5], v[174:177], v[224:227], v[2:5]
	v_mfma_f32_16x16x32_bf16 v[6:9], v[166:169], v[224:227], v[6:9]
	v_mfma_f32_16x16x32_bf16 v[54:57], v[170:173], v[186:189], v[54:57]
	v_mfma_f32_16x16x32_bf16 v[50:53], v[178:181], v[186:189], v[50:53]
	v_mfma_f32_16x16x32_bf16 v[34:37], v[178:181], v[194:197], v[34:37]
	v_mfma_f32_16x16x32_bf16 v[38:41], v[170:173], v[194:197], v[38:41]
	v_mfma_f32_16x16x32_bf16 v[22:25], v[170:173], v[202:205], v[22:25]
	v_mfma_f32_16x16x32_bf16 v[18:21], v[178:181], v[202:205], v[18:21]
	v_mfma_f32_16x16x32_bf16 v[2:5], v[178:181], v[228:231], v[2:5]
	v_mfma_f32_16x16x32_bf16 v[6:9], v[170:173], v[228:231], v[6:9]
	s_barrier
	s_setprio 0
	s_add_i32 s47, s47, 2
	s_add_u32 s8, s8, 0x100
	s_addc_u32 s9, s9, 0
	s_add_u32 s45, s45, 0x100
	s_addc_u32 s46, s46, 0
	s_cmp_gt_u32 s47, 13
	s_cbranch_scc0 .LBB0_492

; #define PG8_STAGE(bufoff, gbase, voff) do { _Pragma("unroll") for (int _i = 0; _i < 2; ++_i) \
;         __builtin_amdgcn_global_load_lds((const unsigned*)((const char*)(gbase) + (voff)[_i]), (PG8_LAS unsigned*)(lds + (bufoff) + ldsw + _i * 8192), 16, 0, 0); } while (0)
; #define PG8_LDA(dst, b, h) do { _Pragma("unroll") for (int m = 0; m < 4; ++m) _Pragma("unroll") for (int k = 0; k < 2; ++k) dst[m][k] = *(const PG8_LAS bf16x8*)(lds + PG8_SA(b, h) + aoff + m * 2048 + k * 1024); } while (0)
; #define PG8_LDB(dst, b, h) do { _Pragma("unroll") for (int n = 0; n < 2; ++n) _Pragma("unroll") for (int k = 0; k < 2; ++k) dst[n][k] = *(const PG8_LAS bf16x8*)(lds + PG8_SB(b, h) + boff + n * 2048 + k * 1024); } while (0)
; template <class Epi, class Sched, bool ALIGN_EPI = false, bool SP2 = false>
; __device__ __forceinline__ void gemm_phase(PG8_LAS unsigned char* lds, const Gemm g, const Sched& S, const Epi& E) {
;     ...
;         for (int t = 0; t < nt; t += 2) {
;             const bool last = (t == nt - 2);
;             const char* a1 = cA + (size_t)(t + 1) * kstep;
;             const char* a2 = last ? nA : cA + (size_t)(t + 2) * kstep; const char* b2 = last ? nB : cB + (size_t)(t + 2) * kstep;
;             const char* a3 = a2 + kstep; const char* b3 = b2 + kstep;
;             if (last && has_next) S.a_ready(nxt);
;             if constexpr (SP2) {
;             PG8_LDB(B0, 0, 0); PG8_LDB(B1, 0, 1); PG8_SCHED; PG8_LDA(At, 0, 0); PG8_STAGE(PG8_SA(1, 1), a1 + hstep, voffA);
;             PG8_WAIT_V(8); PG8_WAIT_L(0); PG8_BAR; PG8_MMA(0, 0, At, B0); PG8_MMA(0, 1, At, B1); PG8_BAR; PG8_SCHED;
;             PG8_LDA(At, 0, 1); PG8_STAGE(PG8_SB(0, 0), b2, voffB); PG8_STAGE(PG8_SB(0, 1), b2 + hstep, voffB); PG8_STAGE(PG8_SA(0, 0), a2, voffA);
;             PG8_WAIT_V(8); PG8_WAIT_L(0); PG8_BAR; PG8_MMA(1, 0, At, B0); PG8_MMA(1, 1, At, B1); PG8_BAR; PG8_SCHED;
;             PG8_LDB(B0, 1, 0); PG8_LDB(B1, 1, 1); PG8_SCHED; PG8_LDA(At, 1, 0); PG8_STAGE(PG8_SA(0, 1), a2 + hstep, voffA);
;             PG8_WAIT_V(8); PG8_WAIT_L(0); PG8_BAR; PG8_MMA(0, 0, At, B0); PG8_MMA(0, 1, At, B1); PG8_BAR; PG8_SCHED;
;             PG8_LDA(At, 1, 1); PG8_STAGE(PG8_SB(1, 0), b3, voffB); PG8_STAGE(PG8_SB(1, 1), b3 + hstep, voffB); PG8_STAGE(PG8_SA(1, 0), a3, voffA);
;             PG8_WAIT_V(8); PG8_WAIT_L(0); PG8_BAR; PG8_MMA(1, 0, At, B0); PG8_MMA(1, 1, At, B1); PG8_BAR; PG8_SCHED;
.LBB0_891:
	s_add_u32 s18, s16, 0xfffe0080
	s_addc_u32 s19, s17, -1
	s_add_i32 s46, 0, 0x10000
	s_cmp_eq_u32 s45, 4
	s_cselect_b32 s21, s9, s19
	s_cselect_b32 s20, s41, s18
	v_add_u32_e32 v148, s46, v151
	s_cselect_b32 s19, s7, s44
	s_cselect_b32 s18, s42, s43
	s_add_i32 s48, 0, 0x14000
	ds_read_b128 v[138:141], v148
	ds_read_b128 v[144:147], v148 offset:1024
	ds_read_b128 v[154:157], v148 offset:2048
	ds_read_b128 v[158:161], v148 offset:3072
	v_add_u32_e32 v148, s48, v151
	ds_read_b128 v[162:165], v148
	ds_read_b128 v[166:169], v148 offset:1024
	ds_read_b128 v[170:173], v148 offset:2048
	ds_read_b128 v[174:177], v148 offset:3072
	v_lshl_add_u64 v[148:149], s[16:17], 0, v[136:137]
	s_add_i32 m0, s27, 0xc000
	ds_read_b128 v[178:181], v153
	ds_read_b128 v[182:185], v153 offset:1024
	ds_read_b128 v[186:189], v153 offset:2048
	ds_read_b128 v[190:193], v153 offset:3072
	ds_read_b128 v[194:197], v153 offset:4096
	ds_read_b128 v[198:201], v153 offset:5120
	ds_read_b128 v[202:205], v153 offset:6144
	ds_read_b128 v[224:227], v153 offset:7168
	global_load_lds_dwordx4 v[148:149], off
	v_lshl_add_u64 v[148:149], s[16:17], 0, v[142:143]
	s_add_i32 m0, s27, 0xe000
	s_nop 0
	global_load_lds_dwordx4 v[148:149], off
	s_waitcnt vmcnt(8)
	s_waitcnt lgkmcnt(0)
	s_setprio 1
	s_barrier
	v_mfma_f32_16x16x32_bf16 v[126:129], v[138:141], v[178:181], v[126:129]
	v_mfma_f32_16x16x32_bf16 v[122:125], v[154:157], v[178:181], v[122:125]
	v_mfma_f32_16x16x32_bf16 v[106:109], v[154:157], v[186:189], v[106:109]
	v_mfma_f32_16x16x32_bf16 v[110:113], v[138:141], v[186:189], v[110:113]
	v_mfma_f32_16x16x32_bf16 v[94:97], v[138:141], v[194:197], v[94:97]
	v_mfma_f32_16x16x32_bf16 v[90:93], v[154:157], v[194:197], v[90:93]
	v_mfma_f32_16x16x32_bf16 v[74:77], v[154:157], v[202:205], v[74:77]
	v_mfma_f32_16x16x32_bf16 v[78:81], v[138:141], v[202:205], v[78:81]
	v_mfma_f32_16x16x32_bf16 v[126:129], v[144:147], v[182:185], v[126:129]
	v_mfma_f32_16x16x32_bf16 v[122:125], v[158:161], v[182:185], v[122:125]
	v_mfma_f32_16x16x32_bf16 v[106:109], v[158:161], v[190:193], v[106:109]
	v_mfma_f32_16x16x32_bf16 v[110:113], v[144:147], v[190:193], v[110:113]
	v_mfma_f32_16x16x32_bf16 v[94:97], v[144:147], v[198:201], v[94:97]
	v_mfma_f32_16x16x32_bf16 v[90:93], v[158:161], v[198:201], v[90:93]
	v_mfma_f32_16x16x32_bf16 v[74:77], v[158:161], v[224:227], v[74:77]
	v_mfma_f32_16x16x32_bf16 v[78:81], v[144:147], v[224:227], v[78:81]
	v_mfma_f32_16x16x32_bf16 v[118:121], v[162:165], v[178:181], v[118:121]
	v_mfma_f32_16x16x32_bf16 v[114:117], v[170:173], v[178:181], v[114:117]
	v_mfma_f32_16x16x32_bf16 v[98:101], v[170:173], v[186:189], v[98:101]
	v_mfma_f32_16x16x32_bf16 v[102:105], v[162:165], v[186:189], v[102:105]
	v_mfma_f32_16x16x32_bf16 v[86:89], v[162:165], v[194:197], v[86:89]
	v_mfma_f32_16x16x32_bf16 v[82:85], v[170:173], v[194:197], v[82:85]
	v_mfma_f32_16x16x32_bf16 v[66:69], v[170:173], v[202:205], v[66:69]
	v_mfma_f32_16x16x32_bf16 v[70:73], v[162:165], v[202:205], v[70:73]
	v_mfma_f32_16x16x32_bf16 v[118:121], v[166:169], v[182:185], v[118:121]
	v_mfma_f32_16x16x32_bf16 v[114:117], v[174:177], v[182:185], v[114:117]
	v_mfma_f32_16x16x32_bf16 v[98:101], v[174:177], v[190:193], v[98:101]
	v_mfma_f32_16x16x32_bf16 v[102:105], v[166:169], v[190:193], v[102:105]
	v_mfma_f32_16x16x32_bf16 v[86:89], v[166:169], v[198:201], v[86:89]
	v_mfma_f32_16x16x32_bf16 v[82:85], v[174:177], v[198:201], v[82:85]
	v_mfma_f32_16x16x32_bf16 v[66:69], v[174:177], v[224:227], v[66:69]
	v_mfma_f32_16x16x32_bf16 v[70:73], v[166:169], v[224:227], v[70:73]
	s_barrier
	s_setprio 0
	s_add_i32 s46, s46, s26
	v_lshl_add_u64 v[148:149], s[18:19], 0, v[0:1]
	s_mov_b32 m0, s46
	ds_read_b128 v[178:181], v153 offset:16384
	ds_read_b128 v[182:185], v153 offset:17408
	ds_read_b128 v[186:189], v153 offset:18432
	ds_read_b128 v[190:193], v153 offset:19456
	ds_read_b128 v[194:197], v153 offset:20480
	ds_read_b128 v[198:201], v153 offset:21504
	ds_read_b128 v[202:205], v153 offset:22528
	ds_read_b128 v[224:227], v153 offset:23552
	global_load_lds_dwordx4 v[148:149], off
	s_add_i32 m0, s46, 0x2000
	s_add_u32 s46, s18, 0x20000
	v_lshl_add_u64 v[228:229], s[18:19], 0, v[134:135]
	s_addc_u32 s47, s19, 0
	s_add_i32 s48, s48, s26
	global_load_lds_dwordx4 v[228:229], off
	v_lshl_add_u64 v[230:231], s[46:47], 0, v[0:1]
	s_mov_b32 m0, s48
	v_lshl_add_u64 v[232:233], s[20:21], 0, v[132:133]
	global_load_lds_dwordx4 v[230:231], off
	v_lshl_add_u64 v[230:231], s[46:47], 0, v[134:135]
	s_add_i32 m0, s48, 0x2000
	s_nop 0
	global_load_lds_dwordx4 v[230:231], off
	v_lshl_add_u64 v[230:231], s[20:21], 0, v[130:131]
	s_mov_b32 m0, s27
	s_nop 0
	global_load_lds_dwordx4 v[230:231], off
	s_mov_b32 m0, s28
	s_nop 0
	global_load_lds_dwordx4 v[232:233], off
	s_waitcnt vmcnt(8)
	s_waitcnt lgkmcnt(0)
	s_setprio 1
	s_barrier
; #define PG8_STAGE(bufoff, gbase, voff) do { _Pragma("unroll") for (int _i = 0; _i < 2; ++_i) \
;         __builtin_amdgcn_global_load_lds((const unsigned*)((const char*)(gbase) + (voff)[_i]), (PG8_LAS unsigned*)(lds + (bufoff) + ldsw + _i * 8192), 16, 0, 0); } while (0)
; #define PG8_LDA(dst, b, h) do { _Pragma("unroll") for (int m = 0; m < 4; ++m) _Pragma("unroll") for (int k = 0; k < 2; ++k) dst[m][k] = *(const PG8_LAS bf16x8*)(lds + PG8_SA(b, h) + aoff + m * 2048 + k * 1024); } while (0)
; #define PG8_LDB(dst, b, h) do { _Pragma("unroll") for (int n = 0; n < 2; ++n) _Pragma("unroll") for (int k = 0; k < 2; ++k) dst[n][k] = *(const PG8_LAS bf16x8*)(lds + PG8_SB(b, h) + boff + n * 2048 + k * 1024); } while (0)
; #define PG8_MMA(ai, bj, At, Bt) do { __builtin_amdgcn_s_setprio(1); _Pragma("unroll") for (int m = 0; m < 4; ++m) _Pragma("unroll") for (int n = 0; n < 2; ++n) _Pragma("unroll") for (int k = 0; k < 2; ++k) \
;         acc[ai][bj][m][n] = __builtin_amdgcn_mfma_f32_16x16x32_bf16(Bt[n][k], At[m][k], acc[ai][bj][m][n], 0, 0, 0); __builtin_amdgcn_s_setprio(0); } while (0)
; #define PG8_WAIT_V(n) asm volatile("s_waitcnt vmcnt(" #n ")" ::: "memory")
; #define PG8_WAIT_L(n) asm volatile("s_waitcnt lgkmcnt(" #n ")" ::: "memory")
; #define PG8_BAR __builtin_amdgcn_s_barrier()
; #define PG8_SCHED __builtin_amdgcn_sched_barrier(0)
; template <class Epi, class Sched, bool ALIGN_EPI = false, bool SP2 = false>
; __device__ __forceinline__ void gemm_phase(PG8_LAS unsigned char* lds, const Gemm g, const Sched& S, const Epi& E) {
;     ...
;             PG8_WAIT_V(8); PG8_WAIT_L(0); PG8_BAR; PG8_MMA(1, 0, At, B0); PG8_MMA(1, 1, At, B1); PG8_BAR; PG8_SCHED;
;             PG8_LDB(B0, 1, 0); PG8_LDB(B1, 1, 1); PG8_SCHED; PG8_LDA(At, 1, 0); PG8_STAGE(PG8_SA(0, 1), a2 + hstep, voffA);
;             PG8_WAIT_V(8); PG8_WAIT_L(0); PG8_BAR; PG8_MMA(0, 0, At, B0); PG8_MMA(0, 1, At, B1); PG8_BAR; PG8_SCHED;
	v_mfma_f32_16x16x32_bf16 v[62:65], v[138:141], v[178:181], v[62:65]
	v_mfma_f32_16x16x32_bf16 v[58:61], v[154:157], v[178:181], v[58:61]
	v_mfma_f32_16x16x32_bf16 v[42:45], v[154:157], v[186:189], v[42:45]
	v_mfma_f32_16x16x32_bf16 v[46:49], v[138:141], v[186:189], v[46:49]
	v_mfma_f32_16x16x32_bf16 v[30:33], v[138:141], v[194:197], v[30:33]
	v_mfma_f32_16x16x32_bf16 v[26:29], v[154:157], v[194:197], v[26:29]
	v_mfma_f32_16x16x32_bf16 v[10:13], v[154:157], v[202:205], v[10:13]
	v_mfma_f32_16x16x32_bf16 v[14:17], v[138:141], v[202:205], v[14:17]
	v_mfma_f32_16x16x32_bf16 v[62:65], v[144:147], v[182:185], v[62:65]
	v_mfma_f32_16x16x32_bf16 v[58:61], v[158:161], v[182:185], v[58:61]
	v_mfma_f32_16x16x32_bf16 v[42:45], v[158:161], v[190:193], v[42:45]
	v_mfma_f32_16x16x32_bf16 v[46:49], v[144:147], v[190:193], v[46:49]
	v_mfma_f32_16x16x32_bf16 v[30:33], v[144:147], v[198:201], v[30:33]
	v_mfma_f32_16x16x32_bf16 v[26:29], v[158:161], v[198:201], v[26:29]
	v_mfma_f32_16x16x32_bf16 v[10:13], v[158:161], v[224:227], v[10:13]
	v_mfma_f32_16x16x32_bf16 v[14:17], v[144:147], v[224:227], v[14:17]
	v_mfma_f32_16x16x32_bf16 v[54:57], v[162:165], v[178:181], v[54:57]
	v_mfma_f32_16x16x32_bf16 v[50:53], v[170:173], v[178:181], v[50:53]
	v_mfma_f32_16x16x32_bf16 v[34:37], v[170:173], v[186:189], v[34:37]
	v_mfma_f32_16x16x32_bf16 v[38:41], v[162:165], v[186:189], v[38:41]
	v_mfma_f32_16x16x32_bf16 v[22:25], v[162:165], v[194:197], v[22:25]
	v_mfma_f32_16x16x32_bf16 v[18:21], v[170:173], v[194:197], v[18:21]
	v_mfma_f32_16x16x32_bf16 v[2:5], v[170:173], v[202:205], v[2:5]
	v_mfma_f32_16x16x32_bf16 v[6:9], v[162:165], v[202:205], v[6:9]
	v_mfma_f32_16x16x32_bf16 v[54:57], v[166:169], v[182:185], v[54:57]
	v_mfma_f32_16x16x32_bf16 v[50:53], v[174:177], v[182:185], v[50:53]
	v_mfma_f32_16x16x32_bf16 v[34:37], v[174:177], v[190:193], v[34:37]
	v_mfma_f32_16x16x32_bf16 v[38:41], v[166:169], v[190:193], v[38:41]
	v_mfma_f32_16x16x32_bf16 v[22:25], v[166:169], v[198:201], v[22:25]
	v_mfma_f32_16x16x32_bf16 v[18:21], v[174:177], v[198:201], v[18:21]
	v_mfma_f32_16x16x32_bf16 v[2:5], v[174:177], v[224:227], v[2:5]
	v_mfma_f32_16x16x32_bf16 v[6:9], v[166:169], v[224:227], v[6:9]
	s_barrier
	s_setprio 0
	s_add_i32 s46, 0, 0x18000
	s_add_i32 s47, 0, 0x1c000
	v_add_u32_e32 v158, s46, v151
	v_add_u32_e32 v174, s47, v151
	ds_read_b128 v[138:141], v158
	ds_read_b128 v[144:147], v158 offset:1024
	ds_read_b128 v[154:157], v158 offset:2048
	ds_read_b128 v[158:161], v158 offset:3072
	ds_read_b128 v[162:165], v174
	ds_read_b128 v[166:169], v174 offset:1024
	ds_read_b128 v[170:173], v174 offset:2048
	ds_read_b128 v[174:177], v174 offset:3072
	s_add_u32 s20, s20, 0x20000
	s_addc_u32 s21, s21, 0
	s_mov_b32 m0, s29
	v_lshl_add_u64 v[234:235], s[20:21], 0, v[130:131]
	ds_read_b128 v[178:181], v153 offset:32768
	ds_read_b128 v[182:185], v153 offset:33792
	ds_read_b128 v[186:189], v153 offset:34816
	ds_read_b128 v[190:193], v153 offset:35840
	ds_read_b128 v[194:197], v153 offset:36864
	ds_read_b128 v[198:201], v153 offset:37888
	ds_read_b128 v[202:205], v153 offset:38912
	ds_read_b128 v[224:227], v153 offset:39936
	global_load_lds_dwordx4 v[234:235], off
	v_lshl_add_u64 v[234:235], s[20:21], 0, v[132:133]
	s_mov_b32 m0, s30
	s_nop 0
	global_load_lds_dwordx4 v[234:235], off
	s_waitcnt vmcnt(8)
	s_waitcnt lgkmcnt(0)
	s_setprio 1
	s_barrier
	v_mfma_f32_16x16x32_bf16 v[126:129], v[138:141], v[178:181], v[126:129]
	v_mfma_f32_16x16x32_bf16 v[122:125], v[154:157], v[178:181], v[122:125]
	v_mfma_f32_16x16x32_bf16 v[106:109], v[154:157], v[186:189], v[106:109]
	v_mfma_f32_16x16x32_bf16 v[110:113], v[138:141], v[186:189], v[110:113]
	v_mfma_f32_16x16x32_bf16 v[94:97], v[138:141], v[194:197], v[94:97]
	v_mfma_f32_16x16x32_bf16 v[90:93], v[154:157], v[194:197], v[90:93]
	v_mfma_f32_16x16x32_bf16 v[74:77], v[154:157], v[202:205], v[74:77]
	v_mfma_f32_16x16x32_bf16 v[78:81], v[138:141], v[202:205], v[78:81]
	v_mfma_f32_16x16x32_bf16 v[126:129], v[144:147], v[182:185], v[126:129]
	v_mfma_f32_16x16x32_bf16 v[122:125], v[158:161], v[182:185], v[122:125]
	v_mfma_f32_16x16x32_bf16 v[106:109], v[158:161], v[190:193], v[106:109]
	v_mfma_f32_16x16x32_bf16 v[110:113], v[144:147], v[190:193], v[110:113]
	v_mfma_f32_16x16x32_bf16 v[94:97], v[144:147], v[198:201], v[94:97]
	v_mfma_f32_16x16x32_bf16 v[90:93], v[158:161], v[198:201], v[90:93]
	v_mfma_f32_16x16x32_bf16 v[74:77], v[158:161], v[224:227], v[74:77]
	v_mfma_f32_16x16x32_bf16 v[78:81], v[144:147], v[224:227], v[78:81]
	v_mfma_f32_16x16x32_bf16 v[118:121], v[162:165], v[178:181], v[118:121]
	v_mfma_f32_16x16x32_bf16 v[114:117], v[170:173], v[178:181], v[114:117]
	v_mfma_f32_16x16x32_bf16 v[98:101], v[170:173], v[186:189], v[98:101]
	v_mfma_f32_16x16x32_bf16 v[102:105], v[162:165], v[186:189], v[102:105]
	v_mfma_f32_16x16x32_bf16 v[86:89], v[162:165], v[194:197], v[86:89]
	v_mfma_f32_16x16x32_bf16 v[82:85], v[170:173], v[194:197], v[82:85]
	v_mfma_f32_16x16x32_bf16 v[66:69], v[170:173], v[202:205], v[66:69]
	v_mfma_f32_16x16x32_bf16 v[70:73], v[162:165], v[202:205], v[70:73]
	v_mfma_f32_16x16x32_bf16 v[118:121], v[166:169], v[182:185], v[118:121]
	v_mfma_f32_16x16x32_bf16 v[114:117], v[174:177], v[182:185], v[114:117]
	v_mfma_f32_16x16x32_bf16 v[98:101], v[174:177], v[190:193], v[98:101]
	v_mfma_f32_16x16x32_bf16 v[102:105], v[166:169], v[190:193], v[102:105]
	v_mfma_f32_16x16x32_bf16 v[86:89], v[166:169], v[198:201], v[86:89]
	v_mfma_f32_16x16x32_bf16 v[82:85], v[174:177], v[198:201], v[82:85]
	v_mfma_f32_16x16x32_bf16 v[66:69], v[174:177], v[224:227], v[66:69]
	v_mfma_f32_16x16x32_bf16 v[70:73], v[166:169], v[224:227], v[70:73]
	s_barrier
; #define PG8_STAGE(bufoff, gbase, voff) do { _Pragma("unroll") for (int _i = 0; _i < 2; ++_i) \
;         __builtin_amdgcn_global_load_lds((const unsigned*)((const char*)(gbase) + (voff)[_i]), (PG8_LAS unsigned*)(lds + (bufoff) + ldsw + _i * 8192), 16, 0, 0); } while (0)
; #define PG8_LDA(dst, b, h) do { _Pragma("unroll") for (int m = 0; m < 4; ++m) _Pragma("unroll") for (int k = 0; k < 2; ++k) dst[m][k] = *(const PG8_LAS bf16x8*)(lds + PG8_SA(b, h) + aoff + m * 2048 + k * 1024); } while (0)
; #define PG8_MMA(ai, bj, At, Bt) do { __builtin_amdgcn_s_setprio(1); _Pragma("unroll") for (int m = 0; m < 4; ++m) _Pragma("unroll") for (int n = 0; n < 2; ++n) _Pragma("unroll") for (int k = 0; k < 2; ++k) \
;         acc[ai][bj][m][n] = __builtin_amdgcn_mfma_f32_16x16x32_bf16(Bt[n][k], At[m][k], acc[ai][bj][m][n], 0, 0, 0); __builtin_amdgcn_s_setprio(0); } while (0)
; #define PG8_WAIT_V(n) asm volatile("s_waitcnt vmcnt(" #n ")" ::: "memory")
; #define PG8_WAIT_L(n) asm volatile("s_waitcnt lgkmcnt(" #n ")" ::: "memory")
; #define PG8_BAR __builtin_amdgcn_s_barrier()
; #define PG8_SCHED __builtin_amdgcn_sched_barrier(0)
; template <class Epi, class Sched, bool ALIGN_EPI = false, bool SP2 = false>
; __device__ __forceinline__ void gemm_phase(PG8_LAS unsigned char* lds, const Gemm g, const Sched& S, const Epi& E) {
;     ...
;             PG8_LDA(At, 1, 1); PG8_STAGE(PG8_SB(1, 0), b3, voffB); PG8_STAGE(PG8_SB(1, 1), b3 + hstep, voffB); PG8_STAGE(PG8_SA(1, 0), a3, voffA);
;             PG8_WAIT_V(8); PG8_WAIT_L(0); PG8_BAR; PG8_MMA(1, 0, At, B0); PG8_MMA(1, 1, At, B1); PG8_BAR; PG8_SCHED;
;     __device__ __forceinline__ void operator()(const f32x4 (&acc)[2][2][4][2], const Unit& u, int wr, int wc, int fr, int fq) const {
;     ...
;                 const int row = row0 + ai * 128 + m * 16;
; #pragma unroll
;                 for (int bj = 0; bj < 2; ++bj) {
;                     const int c = col0 + bj * 128;
;                     const u32x4 g = *(const u32x4*)(G + (size_t)row * P2W + c);
	s_setprio 0
	s_add_i32 s20, s46, s26
	v_lshl_add_u64 v[148:149], v[148:149], 0, s[86:87]
	s_mov_b32 m0, s20
	ds_read_b128 v[178:181], v153 offset:49152
	ds_read_b128 v[182:185], v153 offset:50176
	ds_read_b128 v[186:189], v153 offset:51200
	ds_read_b128 v[190:193], v153 offset:52224
	ds_read_b128 v[194:197], v153 offset:53248
	ds_read_b128 v[198:201], v153 offset:54272
	ds_read_b128 v[202:205], v153 offset:55296
	ds_read_b128 v[224:227], v153 offset:56320
	global_load_lds_dwordx4 v[148:149], off
	s_add_i32 m0, s20, 0x2000
	s_add_u32 s18, s18, 0x20080
	v_lshl_add_u64 v[148:149], v[228:229], 0, s[86:87]
	s_addc_u32 s19, s19, 0
	s_add_i32 s20, s47, s26
	global_load_lds_dwordx4 v[148:149], off
	v_lshl_add_u64 v[148:149], s[18:19], 0, v[0:1]
	s_mov_b32 m0, s20
	s_nop 0
	global_load_lds_dwordx4 v[148:149], off
	v_lshl_add_u64 v[148:149], s[18:19], 0, v[134:135]
	s_add_i32 m0, s20, 0x2000
	s_nop 0
	global_load_lds_dwordx4 v[148:149], off
	v_lshl_add_u64 v[148:149], v[230:231], 0, s[86:87]
	s_mov_b32 m0, s31
	s_nop 0
	global_load_lds_dwordx4 v[148:149], off
	v_lshl_add_u64 v[148:149], v[232:233], 0, s[86:87]
	s_mov_b32 m0, s38
	s_nop 0
	global_load_lds_dwordx4 v[148:149], off
	s_waitcnt vmcnt(8)
	s_waitcnt lgkmcnt(0)
	s_setprio 1
	s_barrier
	v_mfma_f32_16x16x32_bf16 v[62:65], v[138:141], v[178:181], v[62:65]
	v_mfma_f32_16x16x32_bf16 v[58:61], v[154:157], v[178:181], v[58:61]
	v_mfma_f32_16x16x32_bf16 v[42:45], v[154:157], v[186:189], v[42:45]
	v_mfma_f32_16x16x32_bf16 v[46:49], v[138:141], v[186:189], v[46:49]
	v_mfma_f32_16x16x32_bf16 v[30:33], v[138:141], v[194:197], v[30:33]
	v_mfma_f32_16x16x32_bf16 v[26:29], v[154:157], v[194:197], v[26:29]
	v_mfma_f32_16x16x32_bf16 v[10:13], v[154:157], v[202:205], v[10:13]
	v_mfma_f32_16x16x32_bf16 v[14:17], v[138:141], v[202:205], v[14:17]
	v_mfma_f32_16x16x32_bf16 v[62:65], v[144:147], v[182:185], v[62:65]
	v_mfma_f32_16x16x32_bf16 v[58:61], v[158:161], v[182:185], v[58:61]
	v_mfma_f32_16x16x32_bf16 v[42:45], v[158:161], v[190:193], v[42:45]
	v_mfma_f32_16x16x32_bf16 v[46:49], v[144:147], v[190:193], v[46:49]
	v_mfma_f32_16x16x32_bf16 v[30:33], v[144:147], v[198:201], v[30:33]
	v_mfma_f32_16x16x32_bf16 v[26:29], v[158:161], v[198:201], v[26:29]
	v_mfma_f32_16x16x32_bf16 v[10:13], v[158:161], v[224:227], v[10:13]
	v_mfma_f32_16x16x32_bf16 v[14:17], v[144:147], v[224:227], v[14:17]
	v_mfma_f32_16x16x32_bf16 v[54:57], v[162:165], v[178:181], v[54:57]
	v_mfma_f32_16x16x32_bf16 v[50:53], v[170:173], v[178:181], v[50:53]
	v_mfma_f32_16x16x32_bf16 v[34:37], v[170:173], v[186:189], v[34:37]
	v_mfma_f32_16x16x32_bf16 v[38:41], v[162:165], v[186:189], v[38:41]
	v_mfma_f32_16x16x32_bf16 v[22:25], v[162:165], v[194:197], v[22:25]
	v_mfma_f32_16x16x32_bf16 v[18:21], v[170:173], v[194:197], v[18:21]
	v_mfma_f32_16x16x32_bf16 v[2:5], v[170:173], v[202:205], v[2:5]
	v_mfma_f32_16x16x32_bf16 v[6:9], v[162:165], v[202:205], v[6:9]
	v_mfma_f32_16x16x32_bf16 v[54:57], v[166:169], v[182:185], v[54:57]
	v_mfma_f32_16x16x32_bf16 v[50:53], v[174:177], v[182:185], v[50:53]
	v_mfma_f32_16x16x32_bf16 v[34:37], v[174:177], v[190:193], v[34:37]
	v_mfma_f32_16x16x32_bf16 v[38:41], v[166:169], v[190:193], v[38:41]
	v_mfma_f32_16x16x32_bf16 v[22:25], v[166:169], v[198:201], v[22:25]
	v_mfma_f32_16x16x32_bf16 v[18:21], v[174:177], v[198:201], v[18:21]
	v_mfma_f32_16x16x32_bf16 v[2:5], v[174:177], v[224:227], v[2:5]
	v_mfma_f32_16x16x32_bf16 v[6:9], v[166:169], v[224:227], v[6:9]
	s_barrier
	s_setprio 0
	s_add_i32 s45, s45, 2
	s_add_u32 s16, s16, 0x100
	s_addc_u32 s17, s17, 0
	s_add_u32 s43, s43, 0x100
	s_addc_u32 s44, s44, 0
	s_cmp_gt_u32 s45, 5
	s_cbranch_scc0 .LBB0_891
	v_lshl_add_u32 v140, s14, 8, v150
	v_lshl_or_b32 v141, s15, 8, v152
	v_mul_lo_u32 v138, v140, s83
	v_lshlrev_b32_e32 v139, 11, v140
	v_lshl_add_u32 v138, v141, 1, v138
	v_lshl_add_u32 v139, v141, 1, v139
	global_load_dwordx4 v[144:147], v138, s[74:75]
	global_load_dwordx4 v[156:159], v138, s[74:75] offset:256
	v_add_u32_e32 v140, 0x1a000, v138
	global_load_dwordx4 v[160:163], v140, s[74:75]
	global_load_dwordx4 v[164:167], v140, s[74:75] offset:256
	v_add_u32_e32 v140, 0x34000, v138
	global_load_dwordx4 v[168:171], v140, s[74:75]
	global_load_dwordx4 v[172:175], v140, s[74:75] offset:256
	v_add_u32_e32 v140, 0x4e000, v138
	global_load_dwordx4 v[176:179], v140, s[74:75]
	global_load_dwordx4 v[180:183], v140, s[74:75] offset:256
	v_add_u32_e32 v140, 0xd0000, v138
	global_load_dwordx4 v[184:187], v140, s[74:75]
	global_load_dwordx4 v[188:191], v140, s[74:75] offset:256
	v_add_u32_e32 v140, 0xea000, v138
	global_load_dwordx4 v[192:195], v140, s[74:75]
	global_load_dwordx4 v[196:199], v140, s[74:75] offset:256
	v_add_u32_e32 v140, 0x104000, v138
	global_load_dwordx4 v[200:203], v140, s[74:75]
	global_load_dwordx4 v[224:227], v140, s[74:75] offset:256
	v_add_u32_e32 v140, 0x11e000, v138
	global_load_dwordx4 v[228:231], v140, s[74:75]
	global_load_dwordx4 v[232:235], v140, s[74:75] offset:256
	s_and_b64 vcc, exec, s[4:5]
	s_cbranch_vccz .LBB0_894
	s_barrier

; #define PG8_STAGE(bufoff, gbase, voff) do { _Pragma("unroll") for (int _i = 0; _i < 2; ++_i) \
;         __builtin_amdgcn_global_load_lds((const unsigned*)((const char*)(gbase) + (voff)[_i]), (PG8_LAS unsigned*)(lds + (bufoff) + ldsw + _i * 8192), 16, 0, 0); } while (0)
; #define PG8_LDA(dst, b, h) do { _Pragma("unroll") for (int m = 0; m < 4; ++m) _Pragma("unroll") for (int k = 0; k < 2; ++k) dst[m][k] = *(const PG8_LAS bf16x8*)(lds + PG8_SA(b, h) + aoff + m * 2048 + k * 1024); } while (0)
; #define PG8_LDB(dst, b, h) do { _Pragma("unroll") for (int n = 0; n < 2; ++n) _Pragma("unroll") for (int k = 0; k < 2; ++k) dst[n][k] = *(const PG8_LAS bf16x8*)(lds + PG8_SB(b, h) + boff + n * 2048 + k * 1024); } while (0)
; template <class Epi, class Sched, bool ALIGN_EPI = false, bool SP2 = false>
; __device__ __forceinline__ void gemm_phase(PG8_LAS unsigned char* lds, const Gemm g, const Sched& S, const Epi& E) {
;     ...
;         for (int t = 0; t < nt; t += 2) {
;             const bool last = (t == nt - 2);
;             const char* a1 = cA + (size_t)(t + 1) * kstep;
;             const char* a2 = last ? nA : cA + (size_t)(t + 2) * kstep; const char* b2 = last ? nB : cB + (size_t)(t + 2) * kstep;
;             const char* a3 = a2 + kstep; const char* b3 = b2 + kstep;
;             if (last && has_next) S.a_ready(nxt);
;             if constexpr (SP2) {
;             PG8_LDB(B0, 0, 0); PG8_LDB(B1, 0, 1); PG8_SCHED; PG8_LDA(At, 0, 0); PG8_STAGE(PG8_SA(1, 1), a1 + hstep, voffA);
;             PG8_WAIT_V(8); PG8_WAIT_L(0); PG8_BAR; PG8_MMA(0, 0, At, B0); PG8_MMA(0, 1, At, B1); PG8_BAR; PG8_SCHED;
;             PG8_LDA(At, 0, 1); PG8_STAGE(PG8_SB(0, 0), b2, voffB); PG8_STAGE(PG8_SB(0, 1), b2 + hstep, voffB); PG8_STAGE(PG8_SA(0, 0), a2, voffA);
;             PG8_WAIT_V(8); PG8_WAIT_L(0); PG8_BAR; PG8_MMA(1, 0, At, B0); PG8_MMA(1, 1, At, B1); PG8_BAR; PG8_SCHED;
;             PG8_LDB(B0, 1, 0); PG8_LDB(B1, 1, 1); PG8_SCHED; PG8_LDA(At, 1, 0); PG8_STAGE(PG8_SA(0, 1), a2 + hstep, voffA);
;             PG8_WAIT_V(8); PG8_WAIT_L(0); PG8_BAR; PG8_MMA(0, 0, At, B0); PG8_MMA(0, 1, At, B1); PG8_BAR; PG8_SCHED;
;             PG8_LDA(At, 1, 1); PG8_STAGE(PG8_SB(1, 0), b3, voffB); PG8_STAGE(PG8_SB(1, 1), b3 + hstep, voffB); PG8_STAGE(PG8_SA(1, 0), a3, voffA);
;             PG8_WAIT_V(8); PG8_WAIT_L(0); PG8_BAR; PG8_MMA(1, 0, At, B0); PG8_MMA(1, 1, At, B1); PG8_BAR; PG8_SCHED;
.LBB0_919:
	s_add_u32 s12, s10, 0x100
	s_addc_u32 s13, s11, 0
	s_add_i32 s44, 0, 0x10000
	s_cmp_eq_u32 s43, 16
	s_cselect_b32 s17, s5, s13
	s_cselect_b32 s16, s4, s12
	v_add_u32_e32 v148, s44, v151
	s_cselect_b32 s15, s9, s42
	s_cselect_b32 s14, s8, s41
	s_add_i32 s45, 0, 0x14000
	ds_read_b128 v[138:141], v148
	ds_read_b128 v[144:147], v148 offset:1024
	ds_read_b128 v[154:157], v148 offset:2048
	ds_read_b128 v[158:161], v148 offset:3072
	v_add_u32_e32 v148, s45, v151
	ds_read_b128 v[162:165], v148
	ds_read_b128 v[166:169], v148 offset:1024
	ds_read_b128 v[170:173], v148 offset:2048
	ds_read_b128 v[174:177], v148 offset:3072
	v_lshl_add_u64 v[148:149], s[10:11], 0, v[136:137]
	s_add_i32 m0, s23, 0xc000
	ds_read_b128 v[178:181], v153
	ds_read_b128 v[182:185], v153 offset:1024
	ds_read_b128 v[186:189], v153 offset:2048
	ds_read_b128 v[190:193], v153 offset:3072
	ds_read_b128 v[194:197], v153 offset:4096
	ds_read_b128 v[198:201], v153 offset:5120
	ds_read_b128 v[202:205], v153 offset:6144
	ds_read_b128 v[224:227], v153 offset:7168
	global_load_lds_dwordx4 v[148:149], off
	v_lshl_add_u64 v[148:149], s[10:11], 0, v[142:143]
	s_add_i32 m0, s23, 0xe000
	s_nop 0
	global_load_lds_dwordx4 v[148:149], off
	s_waitcnt vmcnt(8)
	s_waitcnt lgkmcnt(0)
	s_setprio 1
	s_barrier
	v_mfma_f32_16x16x32_bf16 v[126:129], v[138:141], v[178:181], v[126:129]
	v_mfma_f32_16x16x32_bf16 v[122:125], v[154:157], v[178:181], v[122:125]
	v_mfma_f32_16x16x32_bf16 v[106:109], v[154:157], v[186:189], v[106:109]
	v_mfma_f32_16x16x32_bf16 v[110:113], v[138:141], v[186:189], v[110:113]
	v_mfma_f32_16x16x32_bf16 v[94:97], v[138:141], v[194:197], v[94:97]
	v_mfma_f32_16x16x32_bf16 v[90:93], v[154:157], v[194:197], v[90:93]
	v_mfma_f32_16x16x32_bf16 v[74:77], v[154:157], v[202:205], v[74:77]
	v_mfma_f32_16x16x32_bf16 v[78:81], v[138:141], v[202:205], v[78:81]
	v_mfma_f32_16x16x32_bf16 v[126:129], v[144:147], v[182:185], v[126:129]
	v_mfma_f32_16x16x32_bf16 v[122:125], v[158:161], v[182:185], v[122:125]
	v_mfma_f32_16x16x32_bf16 v[106:109], v[158:161], v[190:193], v[106:109]
	v_mfma_f32_16x16x32_bf16 v[110:113], v[144:147], v[190:193], v[110:113]
	v_mfma_f32_16x16x32_bf16 v[94:97], v[144:147], v[198:201], v[94:97]
	v_mfma_f32_16x16x32_bf16 v[90:93], v[158:161], v[198:201], v[90:93]
	v_mfma_f32_16x16x32_bf16 v[74:77], v[158:161], v[224:227], v[74:77]
	v_mfma_f32_16x16x32_bf16 v[78:81], v[144:147], v[224:227], v[78:81]
	v_mfma_f32_16x16x32_bf16 v[118:121], v[162:165], v[178:181], v[118:121]
	v_mfma_f32_16x16x32_bf16 v[114:117], v[170:173], v[178:181], v[114:117]
	v_mfma_f32_16x16x32_bf16 v[98:101], v[170:173], v[186:189], v[98:101]
	v_mfma_f32_16x16x32_bf16 v[102:105], v[162:165], v[186:189], v[102:105]
	v_mfma_f32_16x16x32_bf16 v[86:89], v[162:165], v[194:197], v[86:89]
	v_mfma_f32_16x16x32_bf16 v[82:85], v[170:173], v[194:197], v[82:85]
	v_mfma_f32_16x16x32_bf16 v[66:69], v[170:173], v[202:205], v[66:69]
	v_mfma_f32_16x16x32_bf16 v[70:73], v[162:165], v[202:205], v[70:73]
	v_mfma_f32_16x16x32_bf16 v[118:121], v[166:169], v[182:185], v[118:121]
	v_mfma_f32_16x16x32_bf16 v[114:117], v[174:177], v[182:185], v[114:117]
	v_mfma_f32_16x16x32_bf16 v[98:101], v[174:177], v[190:193], v[98:101]
	v_mfma_f32_16x16x32_bf16 v[102:105], v[166:169], v[190:193], v[102:105]
	v_mfma_f32_16x16x32_bf16 v[86:89], v[166:169], v[198:201], v[86:89]
	v_mfma_f32_16x16x32_bf16 v[82:85], v[174:177], v[198:201], v[82:85]
	v_mfma_f32_16x16x32_bf16 v[66:69], v[174:177], v[224:227], v[66:69]
	v_mfma_f32_16x16x32_bf16 v[70:73], v[166:169], v[224:227], v[70:73]
	s_barrier
	s_setprio 0
	s_add_i32 s10, s44, s20
	v_lshl_add_u64 v[148:149], s[14:15], 0, v[0:1]
	s_mov_b32 m0, s10
	ds_read_b128 v[178:181], v153 offset:16384
	ds_read_b128 v[182:185], v153 offset:17408
	ds_read_b128 v[186:189], v153 offset:18432
	ds_read_b128 v[190:193], v153 offset:19456
	ds_read_b128 v[194:197], v153 offset:20480
	ds_read_b128 v[198:201], v153 offset:21504
	ds_read_b128 v[202:205], v153 offset:22528
	ds_read_b128 v[224:227], v153 offset:23552
	global_load_lds_dwordx4 v[148:149], off
	s_add_i32 m0, s10, 0x2000
	s_add_u32 s10, s14, 0x50000
	v_lshl_add_u64 v[228:229], s[14:15], 0, v[134:135]
	s_addc_u32 s11, s15, 0
	s_add_i32 s44, s45, s20
	global_load_lds_dwordx4 v[228:229], off
	v_lshl_add_u64 v[230:231], s[10:11], 0, v[0:1]
	s_mov_b32 m0, s44
	v_lshl_add_u64 v[232:233], s[16:17], 0, v[132:133]
	global_load_lds_dwordx4 v[230:231], off
	v_lshl_add_u64 v[230:231], s[10:11], 0, v[134:135]
	s_add_i32 m0, s44, 0x2000
	s_nop 0
	global_load_lds_dwordx4 v[230:231], off
	v_lshl_add_u64 v[230:231], s[16:17], 0, v[130:131]
	s_mov_b32 m0, s23
	s_nop 0
	global_load_lds_dwordx4 v[230:231], off
	s_mov_b32 m0, s24
	s_nop 0
	global_load_lds_dwordx4 v[232:233], off
	s_waitcnt vmcnt(8)
	s_waitcnt lgkmcnt(0)
	s_setprio 1
	s_barrier
; #define PG8_STAGE(bufoff, gbase, voff) do { _Pragma("unroll") for (int _i = 0; _i < 2; ++_i) \
;         __builtin_amdgcn_global_load_lds((const unsigned*)((const char*)(gbase) + (voff)[_i]), (PG8_LAS unsigned*)(lds + (bufoff) + ldsw + _i * 8192), 16, 0, 0); } while (0)
; #define PG8_LDA(dst, b, h) do { _Pragma("unroll") for (int m = 0; m < 4; ++m) _Pragma("unroll") for (int k = 0; k < 2; ++k) dst[m][k] = *(const PG8_LAS bf16x8*)(lds + PG8_SA(b, h) + aoff + m * 2048 + k * 1024); } while (0)
; #define PG8_LDB(dst, b, h) do { _Pragma("unroll") for (int n = 0; n < 2; ++n) _Pragma("unroll") for (int k = 0; k < 2; ++k) dst[n][k] = *(const PG8_LAS bf16x8*)(lds + PG8_SB(b, h) + boff + n * 2048 + k * 1024); } while (0)
; #define PG8_MMA(ai, bj, At, Bt) do { __builtin_amdgcn_s_setprio(1); _Pragma("unroll") for (int m = 0; m < 4; ++m) _Pragma("unroll") for (int n = 0; n < 2; ++n) _Pragma("unroll") for (int k = 0; k < 2; ++k) \
;         acc[ai][bj][m][n] = __builtin_amdgcn_mfma_f32_16x16x32_bf16(Bt[n][k], At[m][k], acc[ai][bj][m][n], 0, 0, 0); __builtin_amdgcn_s_setprio(0); } while (0)
; #define PG8_WAIT_V(n) asm volatile("s_waitcnt vmcnt(" #n ")" ::: "memory")
; #define PG8_WAIT_L(n) asm volatile("s_waitcnt lgkmcnt(" #n ")" ::: "memory")
; #define PG8_BAR __builtin_amdgcn_s_barrier()
; #define PG8_SCHED __builtin_amdgcn_sched_barrier(0)
; template <class Epi, class Sched, bool ALIGN_EPI = false, bool SP2 = false>
; __device__ __forceinline__ void gemm_phase(PG8_LAS unsigned char* lds, const Gemm g, const Sched& S, const Epi& E) {
;     ...
;             PG8_WAIT_V(8); PG8_WAIT_L(0); PG8_BAR; PG8_MMA(1, 0, At, B0); PG8_MMA(1, 1, At, B1); PG8_BAR; PG8_SCHED;
;             PG8_LDB(B0, 1, 0); PG8_LDB(B1, 1, 1); PG8_SCHED; PG8_LDA(At, 1, 0); PG8_STAGE(PG8_SA(0, 1), a2 + hstep, voffA);
;             PG8_WAIT_V(8); PG8_WAIT_L(0); PG8_BAR; PG8_MMA(0, 0, At, B0); PG8_MMA(0, 1, At, B1); PG8_BAR; PG8_SCHED;
	v_mfma_f32_16x16x32_bf16 v[62:65], v[138:141], v[178:181], v[62:65]
	v_mfma_f32_16x16x32_bf16 v[58:61], v[154:157], v[178:181], v[58:61]
	v_mfma_f32_16x16x32_bf16 v[42:45], v[154:157], v[186:189], v[42:45]
	v_mfma_f32_16x16x32_bf16 v[46:49], v[138:141], v[186:189], v[46:49]
	v_mfma_f32_16x16x32_bf16 v[30:33], v[138:141], v[194:197], v[30:33]
	v_mfma_f32_16x16x32_bf16 v[26:29], v[154:157], v[194:197], v[26:29]
	v_mfma_f32_16x16x32_bf16 v[10:13], v[154:157], v[202:205], v[10:13]
	v_mfma_f32_16x16x32_bf16 v[14:17], v[138:141], v[202:205], v[14:17]
	v_mfma_f32_16x16x32_bf16 v[62:65], v[144:147], v[182:185], v[62:65]
	v_mfma_f32_16x16x32_bf16 v[58:61], v[158:161], v[182:185], v[58:61]
	v_mfma_f32_16x16x32_bf16 v[42:45], v[158:161], v[190:193], v[42:45]
	v_mfma_f32_16x16x32_bf16 v[46:49], v[144:147], v[190:193], v[46:49]
	v_mfma_f32_16x16x32_bf16 v[30:33], v[144:147], v[198:201], v[30:33]
	v_mfma_f32_16x16x32_bf16 v[26:29], v[158:161], v[198:201], v[26:29]
	v_mfma_f32_16x16x32_bf16 v[10:13], v[158:161], v[224:227], v[10:13]
	v_mfma_f32_16x16x32_bf16 v[14:17], v[144:147], v[224:227], v[14:17]
	v_mfma_f32_16x16x32_bf16 v[54:57], v[162:165], v[178:181], v[54:57]
	v_mfma_f32_16x16x32_bf16 v[50:53], v[170:173], v[178:181], v[50:53]
	v_mfma_f32_16x16x32_bf16 v[34:37], v[170:173], v[186:189], v[34:37]
	v_mfma_f32_16x16x32_bf16 v[38:41], v[162:165], v[186:189], v[38:41]
	v_mfma_f32_16x16x32_bf16 v[22:25], v[162:165], v[194:197], v[22:25]
	v_mfma_f32_16x16x32_bf16 v[18:21], v[170:173], v[194:197], v[18:21]
	v_mfma_f32_16x16x32_bf16 v[2:5], v[170:173], v[202:205], v[2:5]
	v_mfma_f32_16x16x32_bf16 v[6:9], v[162:165], v[202:205], v[6:9]
	v_mfma_f32_16x16x32_bf16 v[54:57], v[166:169], v[182:185], v[54:57]
	v_mfma_f32_16x16x32_bf16 v[50:53], v[174:177], v[182:185], v[50:53]
	v_mfma_f32_16x16x32_bf16 v[34:37], v[174:177], v[190:193], v[34:37]
	v_mfma_f32_16x16x32_bf16 v[38:41], v[166:169], v[190:193], v[38:41]
	v_mfma_f32_16x16x32_bf16 v[22:25], v[166:169], v[198:201], v[22:25]
	v_mfma_f32_16x16x32_bf16 v[18:21], v[174:177], v[198:201], v[18:21]
	v_mfma_f32_16x16x32_bf16 v[2:5], v[174:177], v[224:227], v[2:5]
	v_mfma_f32_16x16x32_bf16 v[6:9], v[166:169], v[224:227], v[6:9]
	s_barrier
	s_setprio 0
	s_add_i32 s44, 0, 0x18000
	s_add_i32 s45, 0, 0x1c000
	v_add_u32_e32 v158, s44, v151
	v_add_u32_e32 v174, s45, v151
	ds_read_b128 v[138:141], v158
	ds_read_b128 v[144:147], v158 offset:1024
	ds_read_b128 v[154:157], v158 offset:2048
	ds_read_b128 v[158:161], v158 offset:3072
	ds_read_b128 v[162:165], v174
	ds_read_b128 v[166:169], v174 offset:1024
	ds_read_b128 v[170:173], v174 offset:2048
	ds_read_b128 v[174:177], v174 offset:3072
	s_add_u32 s10, s16, 0x50000
	s_addc_u32 s11, s17, 0
	s_mov_b32 m0, s25
	v_lshl_add_u64 v[234:235], s[10:11], 0, v[130:131]
	ds_read_b128 v[178:181], v153 offset:32768
	ds_read_b128 v[182:185], v153 offset:33792
	ds_read_b128 v[186:189], v153 offset:34816
	ds_read_b128 v[190:193], v153 offset:35840
	ds_read_b128 v[194:197], v153 offset:36864
	ds_read_b128 v[198:201], v153 offset:37888
	ds_read_b128 v[202:205], v153 offset:38912
	ds_read_b128 v[224:227], v153 offset:39936
	global_load_lds_dwordx4 v[234:235], off
	v_lshl_add_u64 v[234:235], s[10:11], 0, v[132:133]
	s_mov_b32 m0, s26
	s_nop 0
	global_load_lds_dwordx4 v[234:235], off
	s_waitcnt vmcnt(8)
	s_waitcnt lgkmcnt(0)
	s_setprio 1
	s_barrier
	v_mfma_f32_16x16x32_bf16 v[126:129], v[138:141], v[178:181], v[126:129]
	v_mfma_f32_16x16x32_bf16 v[122:125], v[154:157], v[178:181], v[122:125]
	v_mfma_f32_16x16x32_bf16 v[106:109], v[154:157], v[186:189], v[106:109]
	v_mfma_f32_16x16x32_bf16 v[110:113], v[138:141], v[186:189], v[110:113]
	v_mfma_f32_16x16x32_bf16 v[94:97], v[138:141], v[194:197], v[94:97]
	v_mfma_f32_16x16x32_bf16 v[90:93], v[154:157], v[194:197], v[90:93]
	v_mfma_f32_16x16x32_bf16 v[74:77], v[154:157], v[202:205], v[74:77]
	v_mfma_f32_16x16x32_bf16 v[78:81], v[138:141], v[202:205], v[78:81]
	v_mfma_f32_16x16x32_bf16 v[126:129], v[144:147], v[182:185], v[126:129]
	v_mfma_f32_16x16x32_bf16 v[122:125], v[158:161], v[182:185], v[122:125]
	v_mfma_f32_16x16x32_bf16 v[106:109], v[158:161], v[190:193], v[106:109]
	v_mfma_f32_16x16x32_bf16 v[110:113], v[144:147], v[190:193], v[110:113]
	v_mfma_f32_16x16x32_bf16 v[94:97], v[144:147], v[198:201], v[94:97]
	v_mfma_f32_16x16x32_bf16 v[90:93], v[158:161], v[198:201], v[90:93]
	v_mfma_f32_16x16x32_bf16 v[74:77], v[158:161], v[224:227], v[74:77]
	v_mfma_f32_16x16x32_bf16 v[78:81], v[144:147], v[224:227], v[78:81]
	v_mfma_f32_16x16x32_bf16 v[118:121], v[162:165], v[178:181], v[118:121]
	v_mfma_f32_16x16x32_bf16 v[114:117], v[170:173], v[178:181], v[114:117]
	v_mfma_f32_16x16x32_bf16 v[98:101], v[170:173], v[186:189], v[98:101]
	v_mfma_f32_16x16x32_bf16 v[102:105], v[162:165], v[186:189], v[102:105]
	v_mfma_f32_16x16x32_bf16 v[86:89], v[162:165], v[194:197], v[86:89]
	v_mfma_f32_16x16x32_bf16 v[82:85], v[170:173], v[194:197], v[82:85]
	v_mfma_f32_16x16x32_bf16 v[66:69], v[170:173], v[202:205], v[66:69]
	v_mfma_f32_16x16x32_bf16 v[70:73], v[162:165], v[202:205], v[70:73]
	v_mfma_f32_16x16x32_bf16 v[118:121], v[166:169], v[182:185], v[118:121]
	v_mfma_f32_16x16x32_bf16 v[114:117], v[174:177], v[182:185], v[114:117]
	v_mfma_f32_16x16x32_bf16 v[98:101], v[174:177], v[190:193], v[98:101]
	v_mfma_f32_16x16x32_bf16 v[102:105], v[166:169], v[190:193], v[102:105]
	v_mfma_f32_16x16x32_bf16 v[86:89], v[166:169], v[198:201], v[86:89]
	v_mfma_f32_16x16x32_bf16 v[82:85], v[174:177], v[198:201], v[82:85]
	v_mfma_f32_16x16x32_bf16 v[66:69], v[174:177], v[224:227], v[66:69]
	v_mfma_f32_16x16x32_bf16 v[70:73], v[166:169], v[224:227], v[70:73]
	s_barrier
; #define PG8_STAGE(bufoff, gbase, voff) do { _Pragma("unroll") for (int _i = 0; _i < 2; ++_i) \
;         __builtin_amdgcn_global_load_lds((const unsigned*)((const char*)(gbase) + (voff)[_i]), (PG8_LAS unsigned*)(lds + (bufoff) + ldsw + _i * 8192), 16, 0, 0); } while (0)
; #define PG8_LDA(dst, b, h) do { _Pragma("unroll") for (int m = 0; m < 4; ++m) _Pragma("unroll") for (int k = 0; k < 2; ++k) dst[m][k] = *(const PG8_LAS bf16x8*)(lds + PG8_SA(b, h) + aoff + m * 2048 + k * 1024); } while (0)
; #define PG8_MMA(ai, bj, At, Bt) do { __builtin_amdgcn_s_setprio(1); _Pragma("unroll") for (int m = 0; m < 4; ++m) _Pragma("unroll") for (int n = 0; n < 2; ++n) _Pragma("unroll") for (int k = 0; k < 2; ++k) \
;         acc[ai][bj][m][n] = __builtin_amdgcn_mfma_f32_16x16x32_bf16(Bt[n][k], At[m][k], acc[ai][bj][m][n], 0, 0, 0); __builtin_amdgcn_s_setprio(0); } while (0)
; #define PG8_WAIT_V(n) asm volatile("s_waitcnt vmcnt(" #n ")" ::: "memory")
; #define PG8_WAIT_L(n) asm volatile("s_waitcnt lgkmcnt(" #n ")" ::: "memory")
; #define PG8_BAR __builtin_amdgcn_s_barrier()
; #define PG8_SCHED __builtin_amdgcn_sched_barrier(0)
; template <class Epi, class Sched, bool ALIGN_EPI = false, bool SP2 = false>
; __device__ __forceinline__ void gemm_phase(PG8_LAS unsigned char* lds, const Gemm g, const Sched& S, const Epi& E) {
;     ...
;             PG8_LDA(At, 1, 1); PG8_STAGE(PG8_SB(1, 0), b3, voffB); PG8_STAGE(PG8_SB(1, 1), b3 + hstep, voffB); PG8_STAGE(PG8_SA(1, 0), a3, voffA);
;             PG8_WAIT_V(8); PG8_WAIT_L(0); PG8_BAR; PG8_MMA(1, 0, At, B0); PG8_MMA(1, 1, At, B1); PG8_BAR; PG8_SCHED;
;     __device__ __forceinline__ void operator()(const f32x4 (&acc)[2][2][4][2], const Unit& u, int wr, int wc, int fr, int fq) const {
;     ...
;                 const int row = row0 + ai * 128 + m * 16;
; #pragma unroll
;                 for (int bj = 0; bj < 2; ++bj) {
;                     const int c = col0 + bj * 128;
;                     const u32x4 g = *(const u32x4*)(G + (size_t)row * P2W + c);
;                     const u32x4 t = *(const u32x4*)(T + (size_t)row * D + c);
	s_setprio 0
	s_add_i32 s10, s44, s20
	v_lshl_add_u64 v[148:149], v[148:149], 0, s[86:87]
	s_mov_b32 m0, s10
	ds_read_b128 v[178:181], v153 offset:49152
	ds_read_b128 v[182:185], v153 offset:50176
	ds_read_b128 v[186:189], v153 offset:51200
	ds_read_b128 v[190:193], v153 offset:52224
	ds_read_b128 v[194:197], v153 offset:53248
	ds_read_b128 v[198:201], v153 offset:54272
	ds_read_b128 v[202:205], v153 offset:55296
	ds_read_b128 v[224:227], v153 offset:56320
	global_load_lds_dwordx4 v[148:149], off
	s_add_i32 m0, s10, 0x2000
	s_add_u32 s10, s14, 0x50080
	v_lshl_add_u64 v[148:149], v[228:229], 0, s[86:87]
	s_addc_u32 s11, s15, 0
	s_add_i32 s14, s45, s20
	global_load_lds_dwordx4 v[148:149], off
	v_lshl_add_u64 v[148:149], s[10:11], 0, v[0:1]
	s_mov_b32 m0, s14
	s_nop 0
	global_load_lds_dwordx4 v[148:149], off
	v_lshl_add_u64 v[148:149], s[10:11], 0, v[134:135]
	s_add_i32 m0, s14, 0x2000
	s_nop 0
	global_load_lds_dwordx4 v[148:149], off
	v_lshl_add_u64 v[148:149], v[230:231], 0, s[86:87]
	s_mov_b32 m0, s27
	s_nop 0
	global_load_lds_dwordx4 v[148:149], off
	v_lshl_add_u64 v[148:149], v[232:233], 0, s[86:87]
	s_mov_b32 m0, s28
	s_nop 0
	global_load_lds_dwordx4 v[148:149], off
	s_waitcnt vmcnt(8)
	s_waitcnt lgkmcnt(0)
	s_setprio 1
	s_barrier
	v_mfma_f32_16x16x32_bf16 v[62:65], v[138:141], v[178:181], v[62:65]
	v_mfma_f32_16x16x32_bf16 v[58:61], v[154:157], v[178:181], v[58:61]
	v_mfma_f32_16x16x32_bf16 v[42:45], v[154:157], v[186:189], v[42:45]
	v_mfma_f32_16x16x32_bf16 v[46:49], v[138:141], v[186:189], v[46:49]
	v_mfma_f32_16x16x32_bf16 v[30:33], v[138:141], v[194:197], v[30:33]
	v_mfma_f32_16x16x32_bf16 v[26:29], v[154:157], v[194:197], v[26:29]
	v_mfma_f32_16x16x32_bf16 v[10:13], v[154:157], v[202:205], v[10:13]
	v_mfma_f32_16x16x32_bf16 v[14:17], v[138:141], v[202:205], v[14:17]
	v_mfma_f32_16x16x32_bf16 v[62:65], v[144:147], v[182:185], v[62:65]
	v_mfma_f32_16x16x32_bf16 v[58:61], v[158:161], v[182:185], v[58:61]
	v_mfma_f32_16x16x32_bf16 v[42:45], v[158:161], v[190:193], v[42:45]
	v_mfma_f32_16x16x32_bf16 v[46:49], v[144:147], v[190:193], v[46:49]
	v_mfma_f32_16x16x32_bf16 v[30:33], v[144:147], v[198:201], v[30:33]
	v_mfma_f32_16x16x32_bf16 v[26:29], v[158:161], v[198:201], v[26:29]
	v_mfma_f32_16x16x32_bf16 v[10:13], v[158:161], v[224:227], v[10:13]
	v_mfma_f32_16x16x32_bf16 v[14:17], v[144:147], v[224:227], v[14:17]
	v_mfma_f32_16x16x32_bf16 v[54:57], v[162:165], v[178:181], v[54:57]
	v_mfma_f32_16x16x32_bf16 v[50:53], v[170:173], v[178:181], v[50:53]
	v_mfma_f32_16x16x32_bf16 v[34:37], v[170:173], v[186:189], v[34:37]
	v_mfma_f32_16x16x32_bf16 v[38:41], v[162:165], v[186:189], v[38:41]
	v_mfma_f32_16x16x32_bf16 v[22:25], v[162:165], v[194:197], v[22:25]
	v_mfma_f32_16x16x32_bf16 v[18:21], v[170:173], v[194:197], v[18:21]
	v_mfma_f32_16x16x32_bf16 v[2:5], v[170:173], v[202:205], v[2:5]
	v_mfma_f32_16x16x32_bf16 v[6:9], v[162:165], v[202:205], v[6:9]
	v_mfma_f32_16x16x32_bf16 v[54:57], v[166:169], v[182:185], v[54:57]
	v_mfma_f32_16x16x32_bf16 v[50:53], v[174:177], v[182:185], v[50:53]
	v_mfma_f32_16x16x32_bf16 v[34:37], v[174:177], v[190:193], v[34:37]
	v_mfma_f32_16x16x32_bf16 v[38:41], v[166:169], v[190:193], v[38:41]
	v_mfma_f32_16x16x32_bf16 v[22:25], v[166:169], v[198:201], v[22:25]
	v_mfma_f32_16x16x32_bf16 v[18:21], v[174:177], v[198:201], v[18:21]
	v_mfma_f32_16x16x32_bf16 v[2:5], v[174:177], v[224:227], v[2:5]
	v_mfma_f32_16x16x32_bf16 v[6:9], v[166:169], v[224:227], v[6:9]
	s_barrier
	s_setprio 0
	s_add_i32 s43, s43, 2
	s_add_u32 s41, s41, 0x100
	s_addc_u32 s42, s42, 0
	s_cmp_gt_u32 s43, 17
	s_mov_b64 s[10:11], s[12:13]
	s_cbranch_scc0 .LBB0_919
	v_lshl_add_u32 v140, s38, 8, v150
	v_lshl_or_b32 v141, s39, 8, v152
	v_mul_lo_u32 v138, v140, s83
	v_lshlrev_b32_e32 v139, 11, v140
	v_lshl_add_u32 v138, v141, 1, v138
	v_lshl_add_u32 v139, v141, 1, v139
	global_load_dwordx4 v[144:147], v138, s[72:73]
	global_load_dwordx4 v[156:159], v139, s[36:37]
	global_load_dwordx4 v[160:163], v138, s[72:73] offset:256
	global_load_dwordx4 v[164:167], v139, s[36:37] offset:256
	v_add_u32_e32 v140, 0x1a000, v138
	v_add_u32_e32 v141, 0x8000, v139
	global_load_dwordx4 v[168:171], v140, s[72:73]
	global_load_dwordx4 v[172:175], v141, s[36:37]
	global_load_dwordx4 v[176:179], v140, s[72:73] offset:256
	global_load_dwordx4 v[180:183], v141, s[36:37] offset:256
	v_add_u32_e32 v140, 0x34000, v138
	v_add_u32_e32 v141, 0x10000, v139
	global_load_dwordx4 v[184:187], v140, s[72:73]
	global_load_dwordx4 v[188:191], v141, s[36:37]
	global_load_dwordx4 v[192:195], v140, s[72:73] offset:256
	global_load_dwordx4 v[196:199], v141, s[36:37] offset:256
	v_add_u32_e32 v140, 0x4e000, v138
	v_add_u32_e32 v141, 0x18000, v139
	global_load_dwordx4 v[200:203], v140, s[72:73]
	global_load_dwordx4 v[224:227], v141, s[36:37]
	global_load_dwordx4 v[228:231], v140, s[72:73] offset:256
	global_load_dwordx4 v[232:235], v141, s[36:37] offset:256
	s_and_b64 vcc, exec, s[6:7]
	s_cbranch_vccz .LBB0_922
	s_barrier

; #define PG8_STAGE(bufoff, gbase, voff) do { _Pragma("unroll") for (int _i = 0; _i < 2; ++_i) \
;         __builtin_amdgcn_global_load_lds((const unsigned*)((const char*)(gbase) + (voff)[_i]), (PG8_LAS unsigned*)(lds + (bufoff) + ldsw + _i * 8192), 16, 0, 0); } while (0)
; #define PG8_LDA(dst, b, h) do { _Pragma("unroll") for (int m = 0; m < 4; ++m) _Pragma("unroll") for (int k = 0; k < 2; ++k) dst[m][k] = *(const PG8_LAS bf16x8*)(lds + PG8_SA(b, h) + aoff + m * 2048 + k * 1024); } while (0)
; #define PG8_LDB(dst, b, h) do { _Pragma("unroll") for (int n = 0; n < 2; ++n) _Pragma("unroll") for (int k = 0; k < 2; ++k) dst[n][k] = *(const PG8_LAS bf16x8*)(lds + PG8_SB(b, h) + boff + n * 2048 + k * 1024); } while (0)
; template <class Epi, class Sched, bool ALIGN_EPI = false, bool SP2 = false>
; __device__ __forceinline__ void gemm_phase(PG8_LAS unsigned char* lds, const Gemm g, const Sched& S, const Epi& E) {
;     ...
;         for (int t = 0; t < nt; t += 2) {
;             const bool last = (t == nt - 2);
;             const char* a1 = cA + (size_t)(t + 1) * kstep;
;             const char* a2 = last ? nA : cA + (size_t)(t + 2) * kstep; const char* b2 = last ? nB : cB + (size_t)(t + 2) * kstep;
;             const char* a3 = a2 + kstep; const char* b3 = b2 + kstep;
;             if (last && has_next) S.a_ready(nxt);
;             if constexpr (SP2) {
;             PG8_LDB(B0, 0, 0); PG8_LDB(B1, 0, 1); PG8_SCHED; PG8_LDA(At, 0, 0); PG8_STAGE(PG8_SA(1, 1), a1 + hstep, voffA);
;             PG8_WAIT_V(8); PG8_WAIT_L(0); PG8_BAR; PG8_MMA(0, 0, At, B0); PG8_MMA(0, 1, At, B1); PG8_BAR; PG8_SCHED;
;             PG8_LDA(At, 0, 1); PG8_STAGE(PG8_SB(0, 0), b2, voffB); PG8_STAGE(PG8_SB(0, 1), b2 + hstep, voffB); PG8_STAGE(PG8_SA(0, 0), a2, voffA);
;             PG8_WAIT_V(8); PG8_WAIT_L(0); PG8_BAR; PG8_MMA(1, 0, At, B0); PG8_MMA(1, 1, At, B1); PG8_BAR; PG8_SCHED;
;             PG8_LDB(B0, 1, 0); PG8_LDB(B1, 1, 1); PG8_SCHED; PG8_LDA(At, 1, 0); PG8_STAGE(PG8_SA(0, 1), a2 + hstep, voffA);
;             PG8_WAIT_V(8); PG8_WAIT_L(0); PG8_BAR; PG8_MMA(0, 0, At, B0); PG8_MMA(0, 1, At, B1); PG8_BAR; PG8_SCHED;
;             PG8_LDA(At, 1, 1); PG8_STAGE(PG8_SB(1, 0), b3, voffB); PG8_STAGE(PG8_SB(1, 1), b3 + hstep, voffB); PG8_STAGE(PG8_SA(1, 0), a3, voffA);
;             PG8_WAIT_V(8); PG8_WAIT_L(0); PG8_BAR; PG8_MMA(1, 0, At, B0); PG8_MMA(1, 1, At, B1); PG8_BAR; PG8_SCHED;
.LBB0_1050:
	s_add_u32 s24, s22, 0xfffc0080
	s_addc_u32 s25, s23, -1
	s_add_i32 s51, 0, 0x10000
	s_cmp_eq_u32 s50, 12
	s_cselect_b32 s27, s13, s25
	s_cselect_b32 s26, s19, s24
	s_cselect_b32 s25, s11, s49
	s_cselect_b32 s24, s21, s48
	s_add_i32 s55, 0, 0x14000
	v_add_u32_e32 v156, s51, v149
	v_add_u32_e32 v172, s55, v149
	ds_read_b128 v[138:141], v156
	ds_read_b128 v[144:147], v156 offset:1024
	ds_read_b128 v[152:155], v156 offset:2048
	ds_read_b128 v[156:159], v156 offset:3072
	ds_read_b128 v[160:163], v172
	ds_read_b128 v[164:167], v172 offset:1024
	ds_read_b128 v[168:171], v172 offset:2048
	ds_read_b128 v[172:175], v172 offset:3072
	v_lshl_add_u64 v[204:205], s[22:23], 0, v[136:137]
	s_add_i32 m0, s38, 0xc000
	ds_read_b128 v[176:179], v151
	ds_read_b128 v[180:183], v151 offset:1024
	ds_read_b128 v[184:187], v151 offset:2048
	ds_read_b128 v[188:191], v151 offset:3072
	ds_read_b128 v[192:195], v151 offset:4096
	ds_read_b128 v[196:199], v151 offset:5120
	ds_read_b128 v[200:203], v151 offset:6144
	ds_read_b128 v[224:227], v151 offset:7168
	global_load_lds_dwordx4 v[204:205], off
	v_lshl_add_u64 v[204:205], s[22:23], 0, v[142:143]
	s_add_i32 m0, s38, 0xe000
	s_nop 0
	global_load_lds_dwordx4 v[204:205], off
	s_waitcnt vmcnt(8)
	s_waitcnt lgkmcnt(0)
	s_setprio 1
	s_barrier
	v_mfma_f32_16x16x32_bf16 v[126:129], v[138:141], v[176:179], v[126:129]
	v_mfma_f32_16x16x32_bf16 v[122:125], v[152:155], v[176:179], v[122:125]
	v_mfma_f32_16x16x32_bf16 v[106:109], v[152:155], v[184:187], v[106:109]
	v_mfma_f32_16x16x32_bf16 v[110:113], v[138:141], v[184:187], v[110:113]
	v_mfma_f32_16x16x32_bf16 v[94:97], v[138:141], v[192:195], v[94:97]
	v_mfma_f32_16x16x32_bf16 v[90:93], v[152:155], v[192:195], v[90:93]
	v_mfma_f32_16x16x32_bf16 v[74:77], v[152:155], v[200:203], v[74:77]
	v_mfma_f32_16x16x32_bf16 v[78:81], v[138:141], v[200:203], v[78:81]
	v_mfma_f32_16x16x32_bf16 v[126:129], v[144:147], v[180:183], v[126:129]
	v_mfma_f32_16x16x32_bf16 v[122:125], v[156:159], v[180:183], v[122:125]
	v_mfma_f32_16x16x32_bf16 v[106:109], v[156:159], v[188:191], v[106:109]
	v_mfma_f32_16x16x32_bf16 v[110:113], v[144:147], v[188:191], v[110:113]
	v_mfma_f32_16x16x32_bf16 v[94:97], v[144:147], v[196:199], v[94:97]
	v_mfma_f32_16x16x32_bf16 v[90:93], v[156:159], v[196:199], v[90:93]
	v_mfma_f32_16x16x32_bf16 v[74:77], v[156:159], v[224:227], v[74:77]
	v_mfma_f32_16x16x32_bf16 v[78:81], v[144:147], v[224:227], v[78:81]
	v_mfma_f32_16x16x32_bf16 v[118:121], v[160:163], v[176:179], v[118:121]
	v_mfma_f32_16x16x32_bf16 v[114:117], v[168:171], v[176:179], v[114:117]
	v_mfma_f32_16x16x32_bf16 v[98:101], v[168:171], v[184:187], v[98:101]
	v_mfma_f32_16x16x32_bf16 v[102:105], v[160:163], v[184:187], v[102:105]
	v_mfma_f32_16x16x32_bf16 v[86:89], v[160:163], v[192:195], v[86:89]
	v_mfma_f32_16x16x32_bf16 v[82:85], v[168:171], v[192:195], v[82:85]
	v_mfma_f32_16x16x32_bf16 v[66:69], v[168:171], v[200:203], v[66:69]
	v_mfma_f32_16x16x32_bf16 v[70:73], v[160:163], v[200:203], v[70:73]
	v_mfma_f32_16x16x32_bf16 v[118:121], v[164:167], v[180:183], v[118:121]
	v_mfma_f32_16x16x32_bf16 v[114:117], v[172:175], v[180:183], v[114:117]
	v_mfma_f32_16x16x32_bf16 v[98:101], v[172:175], v[188:191], v[98:101]
	v_mfma_f32_16x16x32_bf16 v[102:105], v[164:167], v[188:191], v[102:105]
	v_mfma_f32_16x16x32_bf16 v[86:89], v[164:167], v[196:199], v[86:89]
	v_mfma_f32_16x16x32_bf16 v[82:85], v[172:175], v[196:199], v[82:85]
	v_mfma_f32_16x16x32_bf16 v[66:69], v[172:175], v[224:227], v[66:69]
	v_mfma_f32_16x16x32_bf16 v[70:73], v[164:167], v[224:227], v[70:73]
	s_barrier
	s_setprio 0
	s_add_i32 s51, s51, s31
	v_lshl_add_u64 v[204:205], s[24:25], 0, v[0:1]
	s_mov_b32 m0, s51
	ds_read_b128 v[176:179], v151 offset:16384
	ds_read_b128 v[180:183], v151 offset:17408
	ds_read_b128 v[184:187], v151 offset:18432
	ds_read_b128 v[188:191], v151 offset:19456
	ds_read_b128 v[192:195], v151 offset:20480
	ds_read_b128 v[196:199], v151 offset:21504
	ds_read_b128 v[200:203], v151 offset:22528
	ds_read_b128 v[224:227], v151 offset:23552
	global_load_lds_dwordx4 v[204:205], off
	s_add_i32 m0, s51, 0x2000
	s_add_u32 s52, s24, 0x40000
	v_lshl_add_u64 v[228:229], s[24:25], 0, v[134:135]
	s_addc_u32 s53, s25, 0
	s_add_i32 s51, s55, s31
	global_load_lds_dwordx4 v[228:229], off
	v_lshl_add_u64 v[230:231], s[52:53], 0, v[0:1]
	s_mov_b32 m0, s51
	v_lshl_add_u64 v[232:233], s[26:27], 0, v[132:133]
	global_load_lds_dwordx4 v[230:231], off
	v_lshl_add_u64 v[230:231], s[52:53], 0, v[134:135]
	s_add_i32 m0, s51, 0x2000
	s_nop 0
	global_load_lds_dwordx4 v[230:231], off
	v_lshl_add_u64 v[230:231], s[26:27], 0, v[130:131]
	s_mov_b32 m0, s38
	s_nop 0
	global_load_lds_dwordx4 v[230:231], off
	s_mov_b32 m0, s39
	s_nop 0
	global_load_lds_dwordx4 v[232:233], off
	s_waitcnt vmcnt(8)
	s_waitcnt lgkmcnt(0)
	s_setprio 1
	s_barrier
; #define PG8_STAGE(bufoff, gbase, voff) do { _Pragma("unroll") for (int _i = 0; _i < 2; ++_i) \
;         __builtin_amdgcn_global_load_lds((const unsigned*)((const char*)(gbase) + (voff)[_i]), (PG8_LAS unsigned*)(lds + (bufoff) + ldsw + _i * 8192), 16, 0, 0); } while (0)
; #define PG8_LDA(dst, b, h) do { _Pragma("unroll") for (int m = 0; m < 4; ++m) _Pragma("unroll") for (int k = 0; k < 2; ++k) dst[m][k] = *(const PG8_LAS bf16x8*)(lds + PG8_SA(b, h) + aoff + m * 2048 + k * 1024); } while (0)
; #define PG8_LDB(dst, b, h) do { _Pragma("unroll") for (int n = 0; n < 2; ++n) _Pragma("unroll") for (int k = 0; k < 2; ++k) dst[n][k] = *(const PG8_LAS bf16x8*)(lds + PG8_SB(b, h) + boff + n * 2048 + k * 1024); } while (0)
; #define PG8_MMA(ai, bj, At, Bt) do { __builtin_amdgcn_s_setprio(1); _Pragma("unroll") for (int m = 0; m < 4; ++m) _Pragma("unroll") for (int n = 0; n < 2; ++n) _Pragma("unroll") for (int k = 0; k < 2; ++k) \
;         acc[ai][bj][m][n] = __builtin_amdgcn_mfma_f32_16x16x32_bf16(Bt[n][k], At[m][k], acc[ai][bj][m][n], 0, 0, 0); __builtin_amdgcn_s_setprio(0); } while (0)
; #define PG8_WAIT_V(n) asm volatile("s_waitcnt vmcnt(" #n ")" ::: "memory")
; #define PG8_WAIT_L(n) asm volatile("s_waitcnt lgkmcnt(" #n ")" ::: "memory")
; #define PG8_BAR __builtin_amdgcn_s_barrier()
; #define PG8_SCHED __builtin_amdgcn_sched_barrier(0)
; template <class Epi, class Sched, bool ALIGN_EPI = false, bool SP2 = false>
; __device__ __forceinline__ void gemm_phase(PG8_LAS unsigned char* lds, const Gemm g, const Sched& S, const Epi& E) {
;     ...
;             PG8_WAIT_V(8); PG8_WAIT_L(0); PG8_BAR; PG8_MMA(1, 0, At, B0); PG8_MMA(1, 1, At, B1); PG8_BAR; PG8_SCHED;
;             PG8_LDB(B0, 1, 0); PG8_LDB(B1, 1, 1); PG8_SCHED; PG8_LDA(At, 1, 0); PG8_STAGE(PG8_SA(0, 1), a2 + hstep, voffA);
;             PG8_WAIT_V(8); PG8_WAIT_L(0); PG8_BAR; PG8_MMA(0, 0, At, B0); PG8_MMA(0, 1, At, B1); PG8_BAR; PG8_SCHED;
	v_mfma_f32_16x16x32_bf16 v[62:65], v[138:141], v[176:179], v[62:65]
	v_mfma_f32_16x16x32_bf16 v[58:61], v[152:155], v[176:179], v[58:61]
	v_mfma_f32_16x16x32_bf16 v[42:45], v[152:155], v[184:187], v[42:45]
	v_mfma_f32_16x16x32_bf16 v[46:49], v[138:141], v[184:187], v[46:49]
	v_mfma_f32_16x16x32_bf16 v[30:33], v[138:141], v[192:195], v[30:33]
	v_mfma_f32_16x16x32_bf16 v[26:29], v[152:155], v[192:195], v[26:29]
	v_mfma_f32_16x16x32_bf16 v[10:13], v[152:155], v[200:203], v[10:13]
	v_mfma_f32_16x16x32_bf16 v[14:17], v[138:141], v[200:203], v[14:17]
	v_mfma_f32_16x16x32_bf16 v[62:65], v[144:147], v[180:183], v[62:65]
	v_mfma_f32_16x16x32_bf16 v[58:61], v[156:159], v[180:183], v[58:61]
	v_mfma_f32_16x16x32_bf16 v[42:45], v[156:159], v[188:191], v[42:45]
	v_mfma_f32_16x16x32_bf16 v[46:49], v[144:147], v[188:191], v[46:49]
	v_mfma_f32_16x16x32_bf16 v[30:33], v[144:147], v[196:199], v[30:33]
	v_mfma_f32_16x16x32_bf16 v[26:29], v[156:159], v[196:199], v[26:29]
	v_mfma_f32_16x16x32_bf16 v[10:13], v[156:159], v[224:227], v[10:13]
	v_mfma_f32_16x16x32_bf16 v[14:17], v[144:147], v[224:227], v[14:17]
	v_mfma_f32_16x16x32_bf16 v[54:57], v[160:163], v[176:179], v[54:57]
	v_mfma_f32_16x16x32_bf16 v[50:53], v[168:171], v[176:179], v[50:53]
	v_mfma_f32_16x16x32_bf16 v[34:37], v[168:171], v[184:187], v[34:37]
	v_mfma_f32_16x16x32_bf16 v[38:41], v[160:163], v[184:187], v[38:41]
	v_mfma_f32_16x16x32_bf16 v[22:25], v[160:163], v[192:195], v[22:25]
	v_mfma_f32_16x16x32_bf16 v[18:21], v[168:171], v[192:195], v[18:21]
	v_mfma_f32_16x16x32_bf16 v[2:5], v[168:171], v[200:203], v[2:5]
	v_mfma_f32_16x16x32_bf16 v[6:9], v[160:163], v[200:203], v[6:9]
	v_mfma_f32_16x16x32_bf16 v[54:57], v[164:167], v[180:183], v[54:57]
	v_mfma_f32_16x16x32_bf16 v[50:53], v[172:175], v[180:183], v[50:53]
	v_mfma_f32_16x16x32_bf16 v[34:37], v[172:175], v[188:191], v[34:37]
	v_mfma_f32_16x16x32_bf16 v[38:41], v[164:167], v[188:191], v[38:41]
	v_mfma_f32_16x16x32_bf16 v[22:25], v[164:167], v[196:199], v[22:25]
	v_mfma_f32_16x16x32_bf16 v[18:21], v[172:175], v[196:199], v[18:21]
	v_mfma_f32_16x16x32_bf16 v[2:5], v[172:175], v[224:227], v[2:5]
	v_mfma_f32_16x16x32_bf16 v[6:9], v[164:167], v[224:227], v[6:9]
	s_barrier
	s_setprio 0
	s_add_i32 s51, 0, 0x18000
	s_add_i32 s52, 0, 0x1c000
	v_add_u32_e32 v156, s51, v149
	v_add_u32_e32 v172, s52, v149
	ds_read_b128 v[138:141], v156
	ds_read_b128 v[144:147], v156 offset:1024
	ds_read_b128 v[152:155], v156 offset:2048
	ds_read_b128 v[156:159], v156 offset:3072
	ds_read_b128 v[160:163], v172
	ds_read_b128 v[164:167], v172 offset:1024
	ds_read_b128 v[168:171], v172 offset:2048
	ds_read_b128 v[172:175], v172 offset:3072
	s_add_u32 s26, s26, 0x40000
	s_addc_u32 s27, s27, 0
	s_mov_b32 m0, s41
	v_lshl_add_u64 v[234:235], s[26:27], 0, v[130:131]
	ds_read_b128 v[176:179], v151 offset:32768
	ds_read_b128 v[180:183], v151 offset:33792
	ds_read_b128 v[184:187], v151 offset:34816
	ds_read_b128 v[188:191], v151 offset:35840
	ds_read_b128 v[192:195], v151 offset:36864
	ds_read_b128 v[196:199], v151 offset:37888
	ds_read_b128 v[200:203], v151 offset:38912
	ds_read_b128 v[224:227], v151 offset:39936
	global_load_lds_dwordx4 v[234:235], off
	v_lshl_add_u64 v[234:235], s[26:27], 0, v[132:133]
	s_mov_b32 m0, s42
	s_nop 0
	global_load_lds_dwordx4 v[234:235], off
	s_waitcnt vmcnt(8)
	s_waitcnt lgkmcnt(0)
	s_setprio 1
	s_barrier
	v_mfma_f32_16x16x32_bf16 v[126:129], v[138:141], v[176:179], v[126:129]
	v_mfma_f32_16x16x32_bf16 v[122:125], v[152:155], v[176:179], v[122:125]
	v_mfma_f32_16x16x32_bf16 v[106:109], v[152:155], v[184:187], v[106:109]
	v_mfma_f32_16x16x32_bf16 v[110:113], v[138:141], v[184:187], v[110:113]
	v_mfma_f32_16x16x32_bf16 v[94:97], v[138:141], v[192:195], v[94:97]
	v_mfma_f32_16x16x32_bf16 v[90:93], v[152:155], v[192:195], v[90:93]
	v_mfma_f32_16x16x32_bf16 v[74:77], v[152:155], v[200:203], v[74:77]
	v_mfma_f32_16x16x32_bf16 v[78:81], v[138:141], v[200:203], v[78:81]
	v_mfma_f32_16x16x32_bf16 v[126:129], v[144:147], v[180:183], v[126:129]
	v_mfma_f32_16x16x32_bf16 v[122:125], v[156:159], v[180:183], v[122:125]
	v_mfma_f32_16x16x32_bf16 v[106:109], v[156:159], v[188:191], v[106:109]
	v_mfma_f32_16x16x32_bf16 v[110:113], v[144:147], v[188:191], v[110:113]
	v_mfma_f32_16x16x32_bf16 v[94:97], v[144:147], v[196:199], v[94:97]
	v_mfma_f32_16x16x32_bf16 v[90:93], v[156:159], v[196:199], v[90:93]
	v_mfma_f32_16x16x32_bf16 v[74:77], v[156:159], v[224:227], v[74:77]
	v_mfma_f32_16x16x32_bf16 v[78:81], v[144:147], v[224:227], v[78:81]
	v_mfma_f32_16x16x32_bf16 v[118:121], v[160:163], v[176:179], v[118:121]
	v_mfma_f32_16x16x32_bf16 v[114:117], v[168:171], v[176:179], v[114:117]
	v_mfma_f32_16x16x32_bf16 v[98:101], v[168:171], v[184:187], v[98:101]
	v_mfma_f32_16x16x32_bf16 v[102:105], v[160:163], v[184:187], v[102:105]
	v_mfma_f32_16x16x32_bf16 v[86:89], v[160:163], v[192:195], v[86:89]
	v_mfma_f32_16x16x32_bf16 v[82:85], v[168:171], v[192:195], v[82:85]
	v_mfma_f32_16x16x32_bf16 v[66:69], v[168:171], v[200:203], v[66:69]
	v_mfma_f32_16x16x32_bf16 v[70:73], v[160:163], v[200:203], v[70:73]
	v_mfma_f32_16x16x32_bf16 v[118:121], v[164:167], v[180:183], v[118:121]
	v_mfma_f32_16x16x32_bf16 v[114:117], v[172:175], v[180:183], v[114:117]
	v_mfma_f32_16x16x32_bf16 v[98:101], v[172:175], v[188:191], v[98:101]
	v_mfma_f32_16x16x32_bf16 v[102:105], v[164:167], v[188:191], v[102:105]
	v_mfma_f32_16x16x32_bf16 v[86:89], v[164:167], v[196:199], v[86:89]
	v_mfma_f32_16x16x32_bf16 v[82:85], v[172:175], v[196:199], v[82:85]
	v_mfma_f32_16x16x32_bf16 v[66:69], v[172:175], v[224:227], v[66:69]
	v_mfma_f32_16x16x32_bf16 v[70:73], v[164:167], v[224:227], v[70:73]
	s_barrier
; #define PG8_STAGE(bufoff, gbase, voff) do { _Pragma("unroll") for (int _i = 0; _i < 2; ++_i) \
;         __builtin_amdgcn_global_load_lds((const unsigned*)((const char*)(gbase) + (voff)[_i]), (PG8_LAS unsigned*)(lds + (bufoff) + ldsw + _i * 8192), 16, 0, 0); } while (0)
; #define PG8_LDA(dst, b, h) do { _Pragma("unroll") for (int m = 0; m < 4; ++m) _Pragma("unroll") for (int k = 0; k < 2; ++k) dst[m][k] = *(const PG8_LAS bf16x8*)(lds + PG8_SA(b, h) + aoff + m * 2048 + k * 1024); } while (0)
; #define PG8_MMA(ai, bj, At, Bt) do { __builtin_amdgcn_s_setprio(1); _Pragma("unroll") for (int m = 0; m < 4; ++m) _Pragma("unroll") for (int n = 0; n < 2; ++n) _Pragma("unroll") for (int k = 0; k < 2; ++k) \
;         acc[ai][bj][m][n] = __builtin_amdgcn_mfma_f32_16x16x32_bf16(Bt[n][k], At[m][k], acc[ai][bj][m][n], 0, 0, 0); __builtin_amdgcn_s_setprio(0); } while (0)
; #define PG8_WAIT_V(n) asm volatile("s_waitcnt vmcnt(" #n ")" ::: "memory")
; #define PG8_WAIT_L(n) asm volatile("s_waitcnt lgkmcnt(" #n ")" ::: "memory")
; #define PG8_BAR __builtin_amdgcn_s_barrier()
; #define PG8_SCHED __builtin_amdgcn_sched_barrier(0)
; template <class Epi, class Sched, bool ALIGN_EPI = false, bool SP2 = false>
; __device__ __forceinline__ void gemm_phase(PG8_LAS unsigned char* lds, const Gemm g, const Sched& S, const Epi& E) {
;     ...
;             PG8_LDA(At, 1, 1); PG8_STAGE(PG8_SB(1, 0), b3, voffB); PG8_STAGE(PG8_SB(1, 1), b3 + hstep, voffB); PG8_STAGE(PG8_SA(1, 0), a3, voffA);
;             PG8_WAIT_V(8); PG8_WAIT_L(0); PG8_BAR; PG8_MMA(1, 0, At, B0); PG8_MMA(1, 1, At, B1); PG8_BAR; PG8_SCHED;
;     __device__ __forceinline__ void operator()(const f32x4 (&acc)[2][2][4][2], const Unit& u, int wr, int wc, int fr, int fq) const {
;     ...
;                 const int row = row0 + ai * 128 + m * 16; float p = 0.f;
; #pragma unroll
;                 for (int bj = 0; bj < 2; ++bj) {
;                     const size_t off = (size_t)row * D + col0 + bj * 128;
;                     const u32x4 xx = *(const u32x4*)(xb + off);
	s_setprio 0
	s_add_i32 s26, s51, s31
	v_lshl_add_u64 v[204:205], v[204:205], 0, s[86:87]
	s_mov_b32 m0, s26
	ds_read_b128 v[176:179], v151 offset:49152
	ds_read_b128 v[180:183], v151 offset:50176
	ds_read_b128 v[184:187], v151 offset:51200
	ds_read_b128 v[188:191], v151 offset:52224
	ds_read_b128 v[192:195], v151 offset:53248
	ds_read_b128 v[196:199], v151 offset:54272
	ds_read_b128 v[200:203], v151 offset:55296
	ds_read_b128 v[224:227], v151 offset:56320
	global_load_lds_dwordx4 v[204:205], off
	s_add_i32 m0, s26, 0x2000
	s_add_u32 s24, s24, 0x40080
	v_lshl_add_u64 v[204:205], v[228:229], 0, s[86:87]
	s_addc_u32 s25, s25, 0
	s_add_i32 s26, s52, s31
	global_load_lds_dwordx4 v[204:205], off
	v_lshl_add_u64 v[204:205], s[24:25], 0, v[0:1]
	s_mov_b32 m0, s26
	s_nop 0
	global_load_lds_dwordx4 v[204:205], off
	v_lshl_add_u64 v[204:205], s[24:25], 0, v[134:135]
	s_add_i32 m0, s26, 0x2000
	s_nop 0
	global_load_lds_dwordx4 v[204:205], off
	v_lshl_add_u64 v[204:205], v[230:231], 0, s[86:87]
	s_mov_b32 m0, s44
	s_nop 0
	global_load_lds_dwordx4 v[204:205], off
	v_lshl_add_u64 v[204:205], v[232:233], 0, s[86:87]
	s_mov_b32 m0, s45
	s_nop 0
	global_load_lds_dwordx4 v[204:205], off
	s_waitcnt vmcnt(8)
	s_waitcnt lgkmcnt(0)
	s_setprio 1
	s_barrier
	v_mfma_f32_16x16x32_bf16 v[62:65], v[138:141], v[176:179], v[62:65]
	v_mfma_f32_16x16x32_bf16 v[58:61], v[152:155], v[176:179], v[58:61]
	v_mfma_f32_16x16x32_bf16 v[42:45], v[152:155], v[184:187], v[42:45]
	v_mfma_f32_16x16x32_bf16 v[46:49], v[138:141], v[184:187], v[46:49]
	v_mfma_f32_16x16x32_bf16 v[30:33], v[138:141], v[192:195], v[30:33]
	v_mfma_f32_16x16x32_bf16 v[26:29], v[152:155], v[192:195], v[26:29]
	v_mfma_f32_16x16x32_bf16 v[10:13], v[152:155], v[200:203], v[10:13]
	v_mfma_f32_16x16x32_bf16 v[14:17], v[138:141], v[200:203], v[14:17]
	v_mfma_f32_16x16x32_bf16 v[62:65], v[144:147], v[180:183], v[62:65]
	v_mfma_f32_16x16x32_bf16 v[58:61], v[156:159], v[180:183], v[58:61]
	v_mfma_f32_16x16x32_bf16 v[42:45], v[156:159], v[188:191], v[42:45]
	v_mfma_f32_16x16x32_bf16 v[46:49], v[144:147], v[188:191], v[46:49]
	v_mfma_f32_16x16x32_bf16 v[30:33], v[144:147], v[196:199], v[30:33]
	v_mfma_f32_16x16x32_bf16 v[26:29], v[156:159], v[196:199], v[26:29]
	v_mfma_f32_16x16x32_bf16 v[10:13], v[156:159], v[224:227], v[10:13]
	v_mfma_f32_16x16x32_bf16 v[14:17], v[144:147], v[224:227], v[14:17]
	v_mfma_f32_16x16x32_bf16 v[54:57], v[160:163], v[176:179], v[54:57]
	v_mfma_f32_16x16x32_bf16 v[50:53], v[168:171], v[176:179], v[50:53]
	v_mfma_f32_16x16x32_bf16 v[34:37], v[168:171], v[184:187], v[34:37]
	v_mfma_f32_16x16x32_bf16 v[38:41], v[160:163], v[184:187], v[38:41]
	v_mfma_f32_16x16x32_bf16 v[22:25], v[160:163], v[192:195], v[22:25]
	v_mfma_f32_16x16x32_bf16 v[18:21], v[168:171], v[192:195], v[18:21]
	v_mfma_f32_16x16x32_bf16 v[2:5], v[168:171], v[200:203], v[2:5]
	v_mfma_f32_16x16x32_bf16 v[6:9], v[160:163], v[200:203], v[6:9]
	v_mfma_f32_16x16x32_bf16 v[54:57], v[164:167], v[180:183], v[54:57]
	v_mfma_f32_16x16x32_bf16 v[50:53], v[172:175], v[180:183], v[50:53]
	v_mfma_f32_16x16x32_bf16 v[34:37], v[172:175], v[188:191], v[34:37]
	v_mfma_f32_16x16x32_bf16 v[38:41], v[164:167], v[188:191], v[38:41]
	v_mfma_f32_16x16x32_bf16 v[22:25], v[164:167], v[196:199], v[22:25]
	v_mfma_f32_16x16x32_bf16 v[18:21], v[172:175], v[196:199], v[18:21]
	v_mfma_f32_16x16x32_bf16 v[2:5], v[172:175], v[224:227], v[2:5]
	v_mfma_f32_16x16x32_bf16 v[6:9], v[164:167], v[224:227], v[6:9]
	s_barrier
	s_setprio 0
	s_add_i32 s50, s50, 2
	s_add_u32 s22, s22, 0x100
	s_addc_u32 s23, s23, 0
	s_add_u32 s48, s48, 0x100
	s_addc_u32 s49, s49, 0
	s_cmp_gt_u32 s50, 13
	s_cbranch_scc0 .LBB0_1050
	v_lshl_add_u32 v138, s20, 8, v148
	v_lshl_or_b32 v139, s18, 8, v150
	v_lshlrev_b32_e32 v138, 11, v138
	v_lshl_add_u32 v138, v139, 1, v138
	global_load_dwordx4 v[152:155], v138, s[34:35]
	global_load_dwordx4 v[156:159], v138, s[34:35] offset:256
	v_add_u32_e32 v139, 0x8000, v138
	global_load_dwordx4 v[160:163], v139, s[34:35]
	global_load_dwordx4 v[164:167], v139, s[34:35] offset:256
	v_add_u32_e32 v139, 0x10000, v138
	global_load_dwordx4 v[168:171], v139, s[34:35]
	global_load_dwordx4 v[172:175], v139, s[34:35] offset:256
	v_add_u32_e32 v139, 0x18000, v138
	global_load_dwordx4 v[176:179], v139, s[34:35]
	global_load_dwordx4 v[180:183], v139, s[34:35] offset:256
	v_add_u32_e32 v139, 0x40000, v138
	global_load_dwordx4 v[184:187], v139, s[34:35]
	global_load_dwordx4 v[188:191], v139, s[34:35] offset:256
	v_add_u32_e32 v139, 0x48000, v138
	global_load_dwordx4 v[192:195], v139, s[34:35]
	global_load_dwordx4 v[196:199], v139, s[34:35] offset:256
	v_add_u32_e32 v139, 0x50000, v138
	global_load_dwordx4 v[200:203], v139, s[34:35]
	global_load_dwordx4 v[224:227], v139, s[34:35] offset:256
	v_add_u32_e32 v139, 0x58000, v138
	global_load_dwordx4 v[228:231], v139, s[34:35]
	global_load_dwordx4 v[232:235], v139, s[34:35] offset:256
	s_and_b64 vcc, exec, s[8:9]
	s_cbranch_vccz .LBB0_1053
	s_barrier
